# v42: v37 with every packed f32 VALU op (v_pk_mul/add/fma_f32) replaced by its two scalar f32 ops (same IEEE op per element)
# speedup vs baseline: 1.0140x; 1.0140x over previous
; DI unsigned pack2(float a, float b) { f2_t v = {a, b}; bf2_t r = __builtin_convertvector(v, bf2_t); return __builtin_bit_cast(unsigned, r); }
; DI void rowpass(const Params& p, int l, bool first, int wv, char* smem) {
;     ...
;     const int b = R / TPB, j = R - b * TPB;
;     const bool isctx = j < 256;
;     const int mr = isctx ? 4 : b;
;     if (!first && l == 3 && isctx) continue;
;     const float* hin; float* hout;
;     if (isctx) {
;       hout = p.hc + (size_t)(b * 256 + j) * DM;
;       hin = (first || l == 0) ? p.ctx + (size_t)(b * 256 + j) * DM : hout;
;     } else {
;       hout = p.out + (size_t)(b * 2048 + (j - 256)) * DM;
;       hin = (first || l == 0) ? p.x + (size_t)(b * 2048 + (j - 256)) * DM : hout;
;     }
;     f32x4 hv[8];
; #pragma unroll
;     for (int i = 0; i < 8; ++i) hv[i] = *(const f32x4*)(hin + i * 256 + lane * 4);
;     ...
;       float ss = 0.f;
; #pragma unroll
;       for (int i = 0; i < 8; ++i) ss += hv[i][0] * hv[i][0] + hv[i][1] * hv[i][1] + hv[i][2] * hv[i][2] + hv[i][3] * hv[i][3];
;       ss = wave_sum(ss);
;       const float r2 = rsqrtf(ss * (1.f / DM) + EPSV);
;       const float* shift = p.mod + (size_t)(lnext * 5 + mr) * 6144;
;       const float* scale = shift + 2048;
;       const float* gpre = p.pre_g + lnext * DM;
;       u16* np = p.nbuf + (size_t)R * DM;
; #pragma unroll
;       for (int i = 0; i < 8; ++i) {
;         const f32x4 sh = *(const f32x4*)(shift + i * 256 + lane * 4);
;         const f32x4 sc = *(const f32x4*)(scale + i * 256 + lane * 4);
;         const f32x4 gp = *(const f32x4*)(gpre + i * 256 + lane * 4);
;         float o[4];
; #pragma unroll
;         for (int e = 0; e < 4; ++e) o[e] = ((hv[i][e] * r2) * gp[e]) * (1.f + sc[e]) + sh[e];
;         u32x2 pk; pk[0] = pack2(o[0], o[1]); pk[1] = pack2(o[2], o[3]);
;         *(u32x2*)(np + i * 256 + lane * 4) = pk;
;       }
.LBB0_84:
	s_and_b64 s[4:5], s[4:5], exec
	s_cselect_b32 s3, 4, s3
	s_ashr_i32 s9, s8, 31
	s_lshl_b64 s[4:5], s[8:9], 13
	s_add_u32 s4, s6, s4
	s_addc_u32 s5, s7, s5
	v_lshl_add_u64 v[2:3], s[4:5], 0, v[38:39]
	global_load_dwordx4 v[44:47], v[2:3], off
	global_load_dwordx4 v[48:51], v[2:3], off offset:1024
	global_load_dwordx4 v[22:25], v[2:3], off offset:2048
	global_load_dwordx4 v[18:21], v[2:3], off offset:3072
	s_movk_i32 s6, 0x1000
	v_add_co_u32_e32 v2, vcc, s6, v2
	s_mul_hi_i32 s5, s3, 0x6000
	s_nop 0
	v_addc_co_u32_e32 v3, vcc, 0, v3, vcc
	global_load_dwordx4 v[14:17], v[2:3], off
	global_load_dwordx4 v[10:13], v[2:3], off offset:1024
	global_load_dwordx4 v[6:9], v[2:3], off offset:2048
	s_nop 0
	global_load_dwordx4 v[2:5], v[2:3], off offset:3072
	s_nop 0
	global_load_dwordx4 v[52:55], v[26:27], off
	s_mulk_i32 s3, 0x6000
	s_add_u32 s4, s62, s3
	s_addc_u32 s5, s63, s5
	v_lshl_add_u64 v[64:65], s[4:5], 0, v[38:39]
	s_movk_i32 s3, 0x3000
	v_add_co_u32_e32 v40, vcc, s3, v64
	s_ashr_i32 s3, s2, 31
	s_nop 0
	v_addc_co_u32_e32 v41, vcc, 0, v65, vcc
	global_load_dwordx4 v[56:59], v[64:65], off
	global_load_dwordx4 v[60:63], v[40:41], off offset:-4096
	s_lshl_b64 s[4:5], s[2:3], 12
	s_mov_b32 s3, 0x800000
	s_mov_b64 s[8:9], 0x2000
	s_waitcnt vmcnt(10)
	v_mul_f32_e32 v0, v45, v45
	s_waitcnt vmcnt(9)
	v_mul_f32_e32 v42, v49, v49
	s_waitcnt vmcnt(8)
	v_mul_f32_e32 v43, v23, v23
	v_fmac_f32_e32 v0, v44, v44
	v_fmac_f32_e32 v42, v48, v48
	s_waitcnt vmcnt(7)
	v_mul_f32_e32 v66, v19, v19
	v_fmac_f32_e32 v43, v22, v22
	v_fmac_f32_e32 v0, v46, v46
	v_fmac_f32_e32 v42, v50, v50
	v_fmac_f32_e32 v66, v18, v18
	v_fmac_f32_e32 v43, v24, v24
	s_waitcnt vmcnt(6)
	v_mul_f32_e32 v67, v15, v15
	v_fmac_f32_e32 v0, v47, v47
	v_fmac_f32_e32 v42, v51, v51
	v_fmac_f32_e32 v66, v20, v20
	s_waitcnt vmcnt(5)
	v_mul_f32_e32 v68, v11, v11
	v_fmac_f32_e32 v43, v25, v25
	v_fmac_f32_e32 v67, v14, v14
	v_add_f32_e32 v0, v0, v42
	s_waitcnt vmcnt(4)
	v_mul_f32_e32 v69, v7, v7
	v_fmac_f32_e32 v66, v21, v21
	v_fmac_f32_e32 v68, v10, v10
	v_fmac_f32_e32 v67, v16, v16
	v_add_f32_e32 v0, v0, v43
	s_waitcnt vmcnt(3)
	v_mul_f32_e32 v70, v3, v3
	v_fmac_f32_e32 v69, v6, v6
	v_fmac_f32_e32 v68, v12, v12
	v_fmac_f32_e32 v67, v17, v17
	v_add_f32_e32 v0, v0, v66
	v_fmac_f32_e32 v70, v2, v2
	v_fmac_f32_e32 v69, v8, v8
	v_fmac_f32_e32 v68, v13, v13
	v_add_f32_e32 v0, v0, v67
	v_fmac_f32_e32 v70, v4, v4
	v_fmac_f32_e32 v69, v9, v9
	v_add_f32_e32 v0, v0, v68
	v_fmac_f32_e32 v70, v5, v5
	v_add_f32_e32 v0, v0, v69
	v_add_f32_e32 v0, v0, v70
	v_mov_b32_e32 v42, v0
	s_nop 1
	v_permlane32_swap_b32_e32 v0, v42
	v_add_f32_e32 v0, v0, v42
	ds_swizzle_b32 v42, v0 offset:swizzle(SWAP,16)
	s_waitcnt vmcnt(0)
	v_add_f32_e32 v60, 1.0, v60
	v_add_f32_e32 v61, 1.0, v61
	v_add_f32_e32 v62, 1.0, v62
	v_add_f32_e32 v63, 1.0, v63
	v_lshl_add_u64 v[66:67], v[64:65], 0, s[8:9]
	s_waitcnt lgkmcnt(0)
	v_add_f32_e32 v0, v0, v42
	ds_swizzle_b32 v42, v0 offset:swizzle(SWAP,8)
	s_waitcnt lgkmcnt(0)
	v_add_f32_e32 v0, v0, v42
	ds_swizzle_b32 v42, v0 offset:swizzle(SWAP,4)
	s_waitcnt lgkmcnt(0)
	v_add_f32_e32 v0, v0, v42
	ds_swizzle_b32 v42, v0 offset:swizzle(SWAP,2)
	s_waitcnt lgkmcnt(0)
	v_add_f32_e32 v0, v0, v42
	ds_swizzle_b32 v42, v0 offset:swizzle(SWAP,1)
	s_waitcnt lgkmcnt(0)
	v_add_f32_e32 v0, v0, v42
	v_fmamk_f32 v0, v0, 0x3a000000, v232
	v_mul_f32_e32 v42, 0x4b800000, v0
	v_cmp_gt_f32_e32 vcc, s3, v0
	v_readlane_b32 s3, v253, 56
	s_add_i32 s2, s2, s3
	v_cndmask_b32_e32 v0, v0, v42, vcc
	v_rsq_f32_e32 v0, v0
	v_lshl_add_u64 v[42:43], v[28:29], 0, s[4:5]
	s_cmpk_gt_i32 s2, 0x23ff
	v_mul_f32_e32 v68, 0x45800000, v0
	v_cndmask_b32_e32 v0, v0, v68, vcc
	v_mul_f32_e32 v44, v44, v0
	v_mul_f32_e32 v45, v45, v0
	v_mul_f32_e32 v46, v46, v0
	v_mul_f32_e32 v47, v47, v0
	v_mul_f32_e32 v44, v52, v44
	v_mul_f32_e32 v45, v53, v45
	v_mul_f32_e32 v46, v54, v46
	v_mul_f32_e32 v47, v55, v47
	v_fma_f32 v44, v60, v44, v56
	v_fma_f32 v45, v61, v45, v57
	v_fma_f32 v46, v62, v46, v58
	v_fma_f32 v47, v63, v47, v59
	v_cvt_pk_bf16_f32 v44, v44, v45
	v_cvt_pk_bf16_f32 v45, v46, v47
	global_store_dwordx2 v[42:43], v[44:45], off
	global_load_dwordx4 v[44:47], v[26:27], off offset:1024
	s_nop 0
	global_load_dwordx4 v[52:55], v[66:67], off offset:1024
	global_load_dwordx4 v[56:59], v[64:65], off offset:1024
	v_mul_f32_e32 v48, v48, v0
	v_mul_f32_e32 v49, v49, v0
	v_mul_f32_e32 v50, v50, v0
	v_mul_f32_e32 v51, v51, v0
	v_mul_f32_e32 v22, v22, v0
	v_mul_f32_e32 v23, v23, v0
	v_mul_f32_e32 v24, v24, v0
	v_mul_f32_e32 v25, v25, v0
	v_mul_f32_e32 v18, v18, v0
	v_mul_f32_e32 v19, v19, v0
	v_mul_f32_e32 v20, v20, v0
	v_mul_f32_e32 v21, v21, v0
	v_mul_f32_e32 v14, v14, v0
	v_mul_f32_e32 v15, v15, v0
	v_mul_f32_e32 v16, v16, v0
	v_mul_f32_e32 v17, v17, v0
	v_mul_f32_e32 v10, v10, v0
	v_mul_f32_e32 v11, v11, v0
	v_mul_f32_e32 v12, v12, v0
	v_mul_f32_e32 v13, v13, v0
	v_mul_f32_e32 v6, v6, v0
	v_mul_f32_e32 v7, v7, v0
	v_mul_f32_e32 v8, v8, v0
	v_mul_f32_e32 v9, v9, v0
	v_mul_f32_e32 v2, v2, v0
	v_mul_f32_e32 v3, v3, v0
	v_mul_f32_e32 v4, v4, v0
	v_mul_f32_e32 v5, v5, v0
	s_waitcnt vmcnt(2)
; DI unsigned pack2(float a, float b) { f2_t v = {a, b}; bf2_t r = __builtin_convertvector(v, bf2_t); return __builtin_bit_cast(unsigned, r); }
; DI void rowpass(const Params& p, int l, bool first, int wv, char* smem) {
;     ...
; #pragma unroll
;       for (int i = 0; i < 8; ++i) {
;         const f32x4 sh = *(const f32x4*)(shift + i * 256 + lane * 4);
;         const f32x4 sc = *(const f32x4*)(scale + i * 256 + lane * 4);
;         const f32x4 gp = *(const f32x4*)(gpre + i * 256 + lane * 4);
;         float o[4];
; #pragma unroll
;         for (int e = 0; e < 4; ++e) o[e] = ((hv[i][e] * r2) * gp[e]) * (1.f + sc[e]) + sh[e];
;         u32x2 pk; pk[0] = pack2(o[0], o[1]); pk[1] = pack2(o[2], o[3]);
;         *(u32x2*)(np + i * 256 + lane * 4) = pk;
;       }
	v_mul_f32_e32 v44, v44, v48
	v_mul_f32_e32 v45, v45, v49
	s_waitcnt vmcnt(1)
	v_add_f32_e32 v48, 1.0, v52
	v_add_f32_e32 v49, 1.0, v53
	v_mul_f32_e32 v46, v46, v50
	v_mul_f32_e32 v47, v47, v51
	v_add_f32_e32 v50, 1.0, v54
	v_add_f32_e32 v51, 1.0, v55
	s_waitcnt vmcnt(0)
	v_fma_f32 v44, v48, v44, v56
	v_fma_f32 v45, v49, v45, v57
	v_fma_f32 v46, v50, v46, v58
	v_fma_f32 v47, v51, v47, v59
	v_cvt_pk_bf16_f32 v44, v44, v45
	v_cvt_pk_bf16_f32 v45, v46, v47
	global_store_dwordx2 v[42:43], v[44:45], off offset:512
	global_load_dwordx4 v[44:47], v[26:27], off offset:2048
	s_nop 0
	global_load_dwordx4 v[48:51], v[66:67], off offset:2048
	global_load_dwordx4 v[52:55], v[64:65], off offset:2048
	s_waitcnt vmcnt(2)
	v_mul_f32_e32 v22, v22, v44
	v_mul_f32_e32 v23, v23, v45
	s_waitcnt vmcnt(1)
	v_add_f32_e32 v44, 1.0, v48
	v_add_f32_e32 v45, 1.0, v49
	v_mul_f32_e32 v24, v24, v46
	v_mul_f32_e32 v25, v25, v47
	v_add_f32_e32 v46, 1.0, v50
	v_add_f32_e32 v47, 1.0, v51
	s_waitcnt vmcnt(0)
	v_fma_f32 v22, v44, v22, v52
	v_fma_f32 v23, v45, v23, v53
	v_fma_f32 v24, v46, v24, v54
	v_fma_f32 v25, v47, v25, v55
	v_cvt_pk_bf16_f32 v22, v22, v23
	v_cvt_pk_bf16_f32 v23, v24, v25
	global_store_dwordx2 v[42:43], v[22:23], off offset:1024
	global_load_dwordx4 v[22:25], v[26:27], off offset:3072
	s_nop 0
	global_load_dwordx4 v[44:47], v[66:67], off offset:3072
	global_load_dwordx4 v[48:51], v[64:65], off offset:3072
	s_waitcnt vmcnt(2)
	v_mul_f32_e32 v18, v18, v22
	v_mul_f32_e32 v19, v19, v23
	s_waitcnt vmcnt(1)
	v_add_f32_e32 v22, 1.0, v44
	v_add_f32_e32 v23, 1.0, v45
	v_mul_f32_e32 v20, v20, v24
	v_mul_f32_e32 v21, v21, v25
	v_add_f32_e32 v24, 1.0, v46
	v_add_f32_e32 v25, 1.0, v47
	s_waitcnt vmcnt(0)
	v_fma_f32 v18, v22, v18, v48
	v_fma_f32 v19, v23, v19, v49
	v_fma_f32 v20, v24, v20, v50
	v_fma_f32 v21, v25, v21, v51
	v_cvt_pk_bf16_f32 v18, v18, v19
	v_cvt_pk_bf16_f32 v19, v20, v21
	global_store_dwordx2 v[42:43], v[18:19], off offset:1536
	v_add_co_u32_e32 v48, vcc, s6, v64
	global_load_dwordx4 v[18:21], v[40:41], off
	global_load_dwordx4 v[22:25], v[30:31], off
	v_addc_co_u32_e32 v49, vcc, 0, v65, vcc
	global_load_dwordx4 v[44:47], v[48:49], off
	s_waitcnt vmcnt(2)
	v_add_f32_e32 v18, 1.0, v18
	v_add_f32_e32 v19, 1.0, v19
	s_waitcnt vmcnt(1)
	v_mul_f32_e32 v14, v14, v22
	v_mul_f32_e32 v15, v15, v23
	v_mul_f32_e32 v16, v16, v24
	v_mul_f32_e32 v17, v17, v25
	v_add_f32_e32 v20, 1.0, v20
	v_add_f32_e32 v21, 1.0, v21
	s_waitcnt vmcnt(0)
	v_fma_f32 v14, v18, v14, v44
	v_fma_f32 v15, v19, v15, v45
	v_fma_f32 v16, v20, v16, v46
	v_fma_f32 v17, v21, v17, v47
	v_cvt_pk_bf16_f32 v14, v14, v15
	v_cvt_pk_bf16_f32 v15, v16, v17
	global_store_dwordx2 v[42:43], v[14:15], off offset:2048
	global_load_dwordx4 v[14:17], v[32:33], off
	s_nop 0
	global_load_dwordx4 v[18:21], v[40:41], off offset:1024
	global_load_dwordx4 v[22:25], v[48:49], off offset:1024
	s_waitcnt vmcnt(2)
	v_mul_f32_e32 v10, v10, v14
	v_mul_f32_e32 v11, v11, v15
	s_waitcnt vmcnt(1)
	v_add_f32_e32 v14, 1.0, v18
	v_add_f32_e32 v15, 1.0, v19
	v_mul_f32_e32 v12, v12, v16
	v_mul_f32_e32 v13, v13, v17
	v_add_f32_e32 v16, 1.0, v20
	v_add_f32_e32 v17, 1.0, v21
	s_waitcnt vmcnt(0)
	v_fma_f32 v10, v14, v10, v22
	v_fma_f32 v11, v15, v11, v23
	v_fma_f32 v12, v16, v12, v24
	v_fma_f32 v13, v17, v13, v25
	v_cvt_pk_bf16_f32 v10, v10, v11
	v_cvt_pk_bf16_f32 v11, v12, v13
	global_store_dwordx2 v[42:43], v[10:11], off offset:2560
	global_load_dwordx4 v[10:13], v[34:35], off
	s_nop 0
	global_load_dwordx4 v[14:17], v[40:41], off offset:2048
	global_load_dwordx4 v[18:21], v[48:49], off offset:2048
	s_waitcnt vmcnt(2)
	v_mul_f32_e32 v6, v6, v10
	v_mul_f32_e32 v7, v7, v11
	s_waitcnt vmcnt(1)
	v_add_f32_e32 v10, 1.0, v14
	v_add_f32_e32 v11, 1.0, v15
	v_mul_f32_e32 v8, v8, v12
	v_mul_f32_e32 v9, v9, v13
	v_add_f32_e32 v12, 1.0, v16
	v_add_f32_e32 v13, 1.0, v17
	s_waitcnt vmcnt(0)
	v_fma_f32 v6, v10, v6, v18
	v_fma_f32 v7, v11, v7, v19
	v_fma_f32 v8, v12, v8, v20
	v_fma_f32 v9, v13, v9, v21
	v_cvt_pk_bf16_f32 v6, v6, v7
	v_cvt_pk_bf16_f32 v7, v8, v9
	global_store_dwordx2 v[42:43], v[6:7], off offset:3072
	global_load_dwordx4 v[6:9], v[36:37], off
	s_nop 0
	global_load_dwordx4 v[10:13], v[40:41], off offset:3072
	global_load_dwordx4 v[14:17], v[48:49], off offset:3072
	s_waitcnt vmcnt(2)
	v_mul_f32_e32 v2, v2, v6
	v_mul_f32_e32 v3, v3, v7
	s_waitcnt vmcnt(1)
	v_add_f32_e32 v6, 1.0, v10
	v_add_f32_e32 v7, 1.0, v11
	v_mul_f32_e32 v4, v4, v8
	v_mul_f32_e32 v5, v5, v9
	v_add_f32_e32 v8, 1.0, v12
	v_add_f32_e32 v9, 1.0, v13
	s_waitcnt vmcnt(0)
	v_fma_f32 v2, v6, v2, v14
	v_fma_f32 v3, v7, v3, v15
	v_fma_f32 v4, v8, v4, v16
	v_fma_f32 v5, v9, v5, v17
	v_cvt_pk_bf16_f32 v2, v2, v3
	v_cvt_pk_bf16_f32 v3, v4, v5
	global_store_dwordx2 v[42:43], v[2:3], off offset:3584
	s_cbranch_scc1 .LBB0_88

; DI float bf_lo(unsigned u) { return __uint_as_float(u << 16); }
; DI float bf_hi(unsigned u) { return __uint_as_float(u & 0xffff0000u); }
; DI void rowpass(const Params& p, int l, bool first, int wv, char* smem) {
;     ...
;       } else {
; #pragma unroll
;         for (int i = 0; i < 8; ++i) yv[i] = (f32x4){0.f, 0.f, 0.f, 0.f};
; #pragma unroll
;         for (int kc = 0; kc < 8; ++kc) {
;           const u16* yp = p.ypart + ((size_t)kc * 1024 + (size_t)(b * 256 + j)) * DM;
; #pragma unroll
;           for (int i = 0; i < 8; ++i) {
;             const u32x2 u = *(const u32x2*)(yp + i * 256 + lane * 4);
;             yv[i][0] += bf_lo(u[0]); yv[i][1] += bf_hi(u[0]); yv[i][2] += bf_lo(u[1]); yv[i][3] += bf_hi(u[1]);
;           }
;         }
.LBB0_111:
	s_andn2_b64 vcc, exec, s[10:11]
	s_movk_i32 s20, 0x6000
	s_cbranch_vccnz .LBB0_113
	s_lshl_b32 s7, s24, 11
	s_sub_i32 s10, s6, s7
	s_ashr_i32 s11, s10, 31
	s_lshl_b64 s[10:11], s[10:11], 12
	v_lshl_add_u64 v[112:113], v[136:137], 0, s[10:11]
	v_add_co_u32_e32 v100, vcc, 0x400000, v112
	s_mov_b32 s7, 0x800000
	s_nop 0
	v_addc_co_u32_e32 v101, vcc, 0, v113, vcc
	global_load_dwordx2 v[140:141], v[112:113], off
	global_load_dwordx2 v[144:145], v[112:113], off offset:512
	global_load_dwordx2 v[148:149], v[112:113], off offset:1024
	global_load_dwordx2 v[152:153], v[112:113], off offset:1536
	global_load_dwordx2 v[168:169], v[112:113], off offset:2048
	global_load_dwordx2 v[128:129], v[112:113], off offset:2560
	global_load_dwordx2 v[114:115], v[112:113], off offset:3072
	global_load_dwordx2 v[98:99], v[112:113], off offset:3584
	v_add_co_u32_e32 v102, vcc, s7, v112
	global_load_dwordx2 v[142:143], v[100:101], off
	global_load_dwordx2 v[146:147], v[100:101], off offset:512
	global_load_dwordx2 v[150:151], v[100:101], off offset:1024
	global_load_dwordx2 v[166:167], v[100:101], off offset:1536
	global_load_dwordx2 v[170:171], v[100:101], off offset:2048
	global_load_dwordx2 v[154:155], v[100:101], off offset:2560
	global_load_dwordx2 v[116:117], v[100:101], off offset:3072
	s_nop 0
	global_load_dwordx2 v[100:101], v[100:101], off offset:3584
	v_addc_co_u32_e32 v103, vcc, 0, v113, vcc
	global_load_dwordx2 v[214:215], v[102:103], off
	global_load_dwordx2 v[202:203], v[102:103], off offset:512
	global_load_dwordx2 v[192:193], v[102:103], off offset:1024
	global_load_dwordx2 v[182:183], v[102:103], off offset:1536
	global_load_dwordx2 v[172:173], v[102:103], off offset:2048
	global_load_dwordx2 v[156:157], v[102:103], off offset:2560
	global_load_dwordx2 v[118:119], v[102:103], off offset:3072
	s_nop 0
	global_load_dwordx2 v[102:103], v[102:103], off offset:3584
	s_mov_b32 s7, 0xc00000
	v_add_co_u32_e32 v104, vcc, s7, v112
	s_mov_b32 s7, 0x1000000
	s_nop 0
	v_addc_co_u32_e32 v105, vcc, 0, v113, vcc
	v_add_co_u32_e32 v106, vcc, s7, v112
	s_mov_b32 s7, 0x1400000
	s_nop 0
	v_addc_co_u32_e32 v107, vcc, 0, v113, vcc
	v_add_co_u32_e32 v108, vcc, s7, v112
	s_mov_b32 s7, 0x1800000
	s_nop 0
	v_addc_co_u32_e32 v109, vcc, 0, v113, vcc
	v_add_co_u32_e32 v110, vcc, s7, v112
	s_mov_b32 s7, 0x1c00000
	s_nop 0
	v_addc_co_u32_e32 v111, vcc, 0, v113, vcc
	v_add_co_u32_e32 v112, vcc, s7, v112
	global_load_dwordx2 v[216:217], v[104:105], off
	global_load_dwordx2 v[204:205], v[104:105], off offset:512
	global_load_dwordx2 v[194:195], v[104:105], off offset:1024
	global_load_dwordx2 v[184:185], v[104:105], off offset:1536
	global_load_dwordx2 v[174:175], v[104:105], off offset:2048
	global_load_dwordx2 v[158:159], v[104:105], off offset:2560
	global_load_dwordx2 v[120:121], v[104:105], off offset:3072
	s_nop 0
	global_load_dwordx2 v[104:105], v[104:105], off offset:3584
	v_addc_co_u32_e32 v113, vcc, 0, v113, vcc
	global_load_dwordx2 v[218:219], v[106:107], off
	global_load_dwordx2 v[206:207], v[106:107], off offset:512
	global_load_dwordx2 v[196:197], v[106:107], off offset:1024
	global_load_dwordx2 v[186:187], v[106:107], off offset:1536
	global_load_dwordx2 v[176:177], v[106:107], off offset:2048
	global_load_dwordx2 v[160:161], v[106:107], off offset:2560
	global_load_dwordx2 v[122:123], v[106:107], off offset:3072
	s_nop 0
	global_load_dwordx2 v[106:107], v[106:107], off offset:3584
	s_nop 0
	global_load_dwordx2 v[220:221], v[108:109], off
	global_load_dwordx2 v[208:209], v[108:109], off offset:512
	global_load_dwordx2 v[198:199], v[108:109], off offset:1024
	global_load_dwordx2 v[188:189], v[108:109], off offset:1536
	global_load_dwordx2 v[178:179], v[108:109], off offset:2048
	global_load_dwordx2 v[162:163], v[108:109], off offset:2560
	global_load_dwordx2 v[124:125], v[108:109], off offset:3072
	s_nop 0
	global_load_dwordx2 v[108:109], v[108:109], off offset:3584
	s_nop 0
	global_load_dwordx2 v[222:223], v[110:111], off
	global_load_dwordx2 v[210:211], v[110:111], off offset:512
	global_load_dwordx2 v[200:201], v[110:111], off offset:1024
	global_load_dwordx2 v[190:191], v[110:111], off offset:1536
	global_load_dwordx2 v[180:181], v[110:111], off offset:2048
	global_load_dwordx2 v[164:165], v[110:111], off offset:2560
	global_load_dwordx2 v[126:127], v[110:111], off offset:3072
	s_nop 0
	global_load_dwordx2 v[110:111], v[110:111], off offset:3584
	s_waitcnt vmcnt(55)
	v_lshlrev_b32_e32 v138, 16, v140
	global_load_dwordx2 v[224:225], v[112:113], off
	v_and_b32_e32 v139, 0xffff0000, v140
	v_lshlrev_b32_e32 v140, 16, v141
	v_and_b32_e32 v141, 0xffff0000, v141
	v_add_f32_e32 v138, 0, v138
	v_add_f32_e32 v139, 0, v139
	s_waitcnt vmcnt(48)
	v_lshlrev_b32_e32 v226, 16, v142
	v_and_b32_e32 v227, 0xffff0000, v142
	v_add_f32_e32 v140, 0, v140
	v_add_f32_e32 v141, 0, v141
	v_lshlrev_b32_e32 v142, 16, v143
	v_and_b32_e32 v143, 0xffff0000, v143
	v_add_f32_e32 v138, v138, v226
	v_add_f32_e32 v139, v139, v227
	s_waitcnt vmcnt(40)
	v_lshlrev_b32_e32 v226, 16, v214
	v_and_b32_e32 v227, 0xffff0000, v214
	v_add_f32_e32 v140, v140, v142
	v_add_f32_e32 v141, v141, v143
	v_lshlrev_b32_e32 v142, 16, v215
	v_and_b32_e32 v143, 0xffff0000, v215
	global_load_dwordx2 v[214:215], v[112:113], off offset:512
	v_add_f32_e32 v140, v140, v142
	v_add_f32_e32 v141, v141, v143
	v_add_f32_e32 v138, v138, v226
	v_add_f32_e32 v139, v139, v227
	s_waitcnt vmcnt(33)
	v_lshlrev_b32_e32 v142, 16, v217
	v_and_b32_e32 v143, 0xffff0000, v217
	v_add_f32_e32 v140, v140, v142
	v_add_f32_e32 v141, v141, v143
	s_waitcnt vmcnt(25)
; DI float bf_lo(unsigned u) { return __uint_as_float(u << 16); }
; DI float bf_hi(unsigned u) { return __uint_as_float(u & 0xffff0000u); }
; DI void rowpass(const Params& p, int l, bool first, int wv, char* smem) {
;     ...
; #pragma unroll
;         for (int kc = 0; kc < 8; ++kc) {
;           const u16* yp = p.ypart + ((size_t)kc * 1024 + (size_t)(b * 256 + j)) * DM;
; #pragma unroll
;           for (int i = 0; i < 8; ++i) {
;             const u32x2 u = *(const u32x2*)(yp + i * 256 + lane * 4);
;             yv[i][0] += bf_lo(u[0]); yv[i][1] += bf_hi(u[0]); yv[i][2] += bf_lo(u[1]); yv[i][3] += bf_hi(u[1]);
;           }
;         }
	v_lshlrev_b32_e32 v142, 16, v219
	v_and_b32_e32 v143, 0xffff0000, v219
	v_add_f32_e32 v140, v140, v142
	v_add_f32_e32 v141, v141, v143
	s_waitcnt vmcnt(17)
	v_lshlrev_b32_e32 v142, 16, v221
	v_and_b32_e32 v143, 0xffff0000, v221
	v_add_f32_e32 v140, v140, v142
	v_add_f32_e32 v141, v141, v143
	s_waitcnt vmcnt(9)
	v_lshlrev_b32_e32 v142, 16, v223
	v_and_b32_e32 v143, 0xffff0000, v223
	v_add_f32_e32 v140, v140, v142
	v_add_f32_e32 v141, v141, v143
	v_lshlrev_b32_e32 v226, 16, v216
	v_and_b32_e32 v227, 0xffff0000, v216
	v_lshlrev_b32_e32 v216, 16, v146
	v_and_b32_e32 v217, 0xffff0000, v146
	v_lshlrev_b32_e32 v146, 16, v147
	v_and_b32_e32 v147, 0xffff0000, v147
	v_add_f32_e32 v138, v138, v226
	v_add_f32_e32 v139, v139, v227
	v_lshlrev_b32_e32 v226, 16, v218
	v_and_b32_e32 v227, 0xffff0000, v218
	v_add_f32_e32 v138, v138, v226
	v_add_f32_e32 v139, v139, v227
	v_lshlrev_b32_e32 v226, 16, v220
	v_and_b32_e32 v227, 0xffff0000, v220
	v_add_f32_e32 v138, v138, v226
	v_add_f32_e32 v139, v139, v227
	v_lshlrev_b32_e32 v226, 16, v222
	v_and_b32_e32 v227, 0xffff0000, v222
	v_add_f32_e32 v138, v138, v226
	v_add_f32_e32 v139, v139, v227
	s_waitcnt vmcnt(1)
	v_lshlrev_b32_e32 v142, 16, v225
	v_and_b32_e32 v143, 0xffff0000, v225
	v_add_f32_e32 v140, v140, v142
	v_add_f32_e32 v141, v141, v143
	v_lshlrev_b32_e32 v142, 16, v144
	v_and_b32_e32 v143, 0xffff0000, v144
	v_lshlrev_b32_e32 v144, 16, v145
	v_and_b32_e32 v145, 0xffff0000, v145
	v_add_f32_e32 v142, 0, v142
	v_add_f32_e32 v143, 0, v143
	v_add_f32_e32 v144, 0, v144
	v_add_f32_e32 v145, 0, v145
	v_add_f32_e32 v142, v142, v216
	v_add_f32_e32 v143, v143, v217
	v_lshlrev_b32_e32 v216, 16, v202
	v_and_b32_e32 v217, 0xffff0000, v202
	v_add_f32_e32 v144, v144, v146
	v_add_f32_e32 v145, v145, v147
	v_lshlrev_b32_e32 v146, 16, v203
	v_and_b32_e32 v147, 0xffff0000, v203
	global_load_dwordx2 v[202:203], v[112:113], off offset:1024
	v_add_f32_e32 v144, v144, v146
	v_add_f32_e32 v145, v145, v147
	v_lshlrev_b32_e32 v146, 16, v205
	v_and_b32_e32 v147, 0xffff0000, v205
	v_add_f32_e32 v144, v144, v146
	v_add_f32_e32 v145, v145, v147
	v_lshlrev_b32_e32 v146, 16, v207
	v_and_b32_e32 v147, 0xffff0000, v207
	v_add_f32_e32 v144, v144, v146
	v_add_f32_e32 v145, v145, v147
	v_lshlrev_b32_e32 v146, 16, v209
	v_and_b32_e32 v147, 0xffff0000, v209
	v_add_f32_e32 v144, v144, v146
	v_add_f32_e32 v145, v145, v147
	v_lshlrev_b32_e32 v146, 16, v211
	v_and_b32_e32 v147, 0xffff0000, v211
	v_add_f32_e32 v144, v144, v146
	v_add_f32_e32 v145, v145, v147
	s_waitcnt vmcnt(1)
	v_lshlrev_b32_e32 v146, 16, v215
	v_and_b32_e32 v147, 0xffff0000, v215
	v_add_f32_e32 v144, v144, v146
	v_add_f32_e32 v145, v145, v147
	v_lshlrev_b32_e32 v146, 16, v148
	v_and_b32_e32 v147, 0xffff0000, v148
	v_lshlrev_b32_e32 v148, 16, v149
	v_and_b32_e32 v149, 0xffff0000, v149
	v_add_f32_e32 v142, v142, v216
	v_add_f32_e32 v143, v143, v217
	v_lshlrev_b32_e32 v216, 16, v204
	v_and_b32_e32 v217, 0xffff0000, v204
	v_add_f32_e32 v146, 0, v146
	v_add_f32_e32 v147, 0, v147
	v_lshlrev_b32_e32 v204, 16, v150
	v_and_b32_e32 v205, 0xffff0000, v150
	v_add_f32_e32 v148, 0, v148
	v_add_f32_e32 v149, 0, v149
	v_lshlrev_b32_e32 v150, 16, v151
	v_and_b32_e32 v151, 0xffff0000, v151
	v_add_f32_e32 v146, v146, v204
	v_add_f32_e32 v147, v147, v205
	v_lshlrev_b32_e32 v204, 16, v192
	v_and_b32_e32 v205, 0xffff0000, v192
	v_add_f32_e32 v148, v148, v150
	v_add_f32_e32 v149, v149, v151
	v_lshlrev_b32_e32 v150, 16, v193
	v_and_b32_e32 v151, 0xffff0000, v193
	global_load_dwordx2 v[192:193], v[112:113], off offset:1536
	v_add_f32_e32 v148, v148, v150
	v_add_f32_e32 v149, v149, v151
	v_lshlrev_b32_e32 v150, 16, v195
	v_and_b32_e32 v151, 0xffff0000, v195
	v_add_f32_e32 v148, v148, v150
	v_add_f32_e32 v149, v149, v151
	v_lshlrev_b32_e32 v150, 16, v197
	v_and_b32_e32 v151, 0xffff0000, v197
	v_add_f32_e32 v148, v148, v150
	v_add_f32_e32 v149, v149, v151
	v_lshlrev_b32_e32 v150, 16, v199
	v_and_b32_e32 v151, 0xffff0000, v199
	v_add_f32_e32 v148, v148, v150
	v_add_f32_e32 v149, v149, v151
	v_lshlrev_b32_e32 v150, 16, v201
	v_and_b32_e32 v151, 0xffff0000, v201
	v_add_f32_e32 v148, v148, v150
	v_add_f32_e32 v149, v149, v151
	v_add_f32_e32 v146, v146, v204
	v_add_f32_e32 v147, v147, v205
	v_lshlrev_b32_e32 v204, 16, v194
	v_and_b32_e32 v205, 0xffff0000, v194
	v_lshlrev_b32_e32 v194, 16, v166
	v_and_b32_e32 v195, 0xffff0000, v166
	v_lshlrev_b32_e32 v166, 16, v167
	v_and_b32_e32 v167, 0xffff0000, v167
	v_add_f32_e32 v142, v142, v216
	v_add_f32_e32 v143, v143, v217
	v_lshlrev_b32_e32 v216, 16, v206
	v_and_b32_e32 v217, 0xffff0000, v206
	v_add_f32_e32 v146, v146, v204
	v_add_f32_e32 v147, v147, v205
	v_lshlrev_b32_e32 v204, 16, v196
	v_and_b32_e32 v205, 0xffff0000, v196
	v_add_f32_e32 v142, v142, v216
	v_add_f32_e32 v143, v143, v217
	v_lshlrev_b32_e32 v216, 16, v208
	v_and_b32_e32 v217, 0xffff0000, v208
	v_add_f32_e32 v146, v146, v204
	v_add_f32_e32 v147, v147, v205
	v_lshlrev_b32_e32 v204, 16, v198
	v_and_b32_e32 v205, 0xffff0000, v198
	v_add_f32_e32 v142, v142, v216
	v_add_f32_e32 v143, v143, v217
	v_lshlrev_b32_e32 v216, 16, v210
	v_and_b32_e32 v217, 0xffff0000, v210
	v_add_f32_e32 v146, v146, v204
	v_add_f32_e32 v147, v147, v205
	v_lshlrev_b32_e32 v204, 16, v200
	v_and_b32_e32 v205, 0xffff0000, v200
	v_lshlrev_b32_e32 v226, 16, v224
	v_and_b32_e32 v227, 0xffff0000, v224
	v_add_f32_e32 v142, v142, v216
	v_add_f32_e32 v143, v143, v217
	v_lshlrev_b32_e32 v216, 16, v214
	v_and_b32_e32 v217, 0xffff0000, v214
	s_waitcnt vmcnt(1)
; DI float bf_lo(unsigned u) { return __uint_as_float(u << 16); }
; DI float bf_hi(unsigned u) { return __uint_as_float(u & 0xffff0000u); }
; DI void rowpass(const Params& p, int l, bool first, int wv, char* smem) {
;     ...
; #pragma unroll
;         for (int kc = 0; kc < 8; ++kc) {
;           const u16* yp = p.ypart + ((size_t)kc * 1024 + (size_t)(b * 256 + j)) * DM;
; #pragma unroll
;           for (int i = 0; i < 8; ++i) {
;             const u32x2 u = *(const u32x2*)(yp + i * 256 + lane * 4);
;             yv[i][0] += bf_lo(u[0]); yv[i][1] += bf_hi(u[0]); yv[i][2] += bf_lo(u[1]); yv[i][3] += bf_hi(u[1]);
;           }
;         }
	v_lshlrev_b32_e32 v150, 16, v203
	v_and_b32_e32 v151, 0xffff0000, v203
	v_add_f32_e32 v148, v148, v150
	v_add_f32_e32 v149, v149, v151
	v_lshlrev_b32_e32 v150, 16, v152
	v_and_b32_e32 v151, 0xffff0000, v152
	v_lshlrev_b32_e32 v152, 16, v153
	v_and_b32_e32 v153, 0xffff0000, v153
	v_add_f32_e32 v150, 0, v150
	v_add_f32_e32 v151, 0, v151
	v_add_f32_e32 v152, 0, v152
	v_add_f32_e32 v153, 0, v153
	v_add_f32_e32 v150, v150, v194
	v_add_f32_e32 v151, v151, v195
	v_lshlrev_b32_e32 v194, 16, v182
	v_and_b32_e32 v195, 0xffff0000, v182
	v_add_f32_e32 v152, v152, v166
	v_add_f32_e32 v153, v153, v167
	v_lshlrev_b32_e32 v166, 16, v183
	v_and_b32_e32 v167, 0xffff0000, v183
	global_load_dwordx2 v[182:183], v[112:113], off offset:2048
	v_add_f32_e32 v152, v152, v166
	v_add_f32_e32 v153, v153, v167
	v_lshlrev_b32_e32 v166, 16, v185
	v_and_b32_e32 v167, 0xffff0000, v185
	v_add_f32_e32 v152, v152, v166
	v_add_f32_e32 v153, v153, v167
	v_lshlrev_b32_e32 v166, 16, v187
	v_and_b32_e32 v167, 0xffff0000, v187
	v_add_f32_e32 v152, v152, v166
	v_add_f32_e32 v153, v153, v167
	v_lshlrev_b32_e32 v166, 16, v189
	v_and_b32_e32 v167, 0xffff0000, v189
	v_add_f32_e32 v152, v152, v166
	v_add_f32_e32 v153, v153, v167
	v_lshlrev_b32_e32 v166, 16, v191
	v_and_b32_e32 v167, 0xffff0000, v191
	v_add_f32_e32 v152, v152, v166
	v_add_f32_e32 v153, v153, v167
	v_add_f32_e32 v150, v150, v194
	v_add_f32_e32 v151, v151, v195
	v_lshlrev_b32_e32 v194, 16, v184
	v_and_b32_e32 v195, 0xffff0000, v184
	v_lshlrev_b32_e32 v184, 16, v170
	v_and_b32_e32 v185, 0xffff0000, v170
	v_lshlrev_b32_e32 v170, 16, v171
	v_and_b32_e32 v171, 0xffff0000, v171
	s_waitcnt vmcnt(1)
	v_lshlrev_b32_e32 v166, 16, v193
	v_and_b32_e32 v167, 0xffff0000, v193
	v_add_f32_e32 v152, v152, v166
	v_add_f32_e32 v153, v153, v167
	v_lshlrev_b32_e32 v166, 16, v168
	v_and_b32_e32 v167, 0xffff0000, v168
	v_lshlrev_b32_e32 v168, 16, v169
	v_and_b32_e32 v169, 0xffff0000, v169
	v_add_f32_e32 v166, 0, v166
	v_add_f32_e32 v167, 0, v167
	v_add_f32_e32 v168, 0, v168
	v_add_f32_e32 v169, 0, v169
	v_add_f32_e32 v166, v166, v184
	v_add_f32_e32 v167, v167, v185
	v_lshlrev_b32_e32 v184, 16, v172
	v_and_b32_e32 v185, 0xffff0000, v172
	v_add_f32_e32 v168, v168, v170
	v_add_f32_e32 v169, v169, v171
	v_lshlrev_b32_e32 v170, 16, v173
	v_and_b32_e32 v171, 0xffff0000, v173
	global_load_dwordx2 v[172:173], v[112:113], off offset:2560
	v_add_f32_e32 v168, v168, v170
	v_add_f32_e32 v169, v169, v171
	v_lshlrev_b32_e32 v170, 16, v175
	v_and_b32_e32 v171, 0xffff0000, v175
	v_add_f32_e32 v168, v168, v170
	v_add_f32_e32 v169, v169, v171
	v_lshlrev_b32_e32 v170, 16, v177
	v_and_b32_e32 v171, 0xffff0000, v177
	v_add_f32_e32 v168, v168, v170
	v_add_f32_e32 v169, v169, v171
	v_lshlrev_b32_e32 v170, 16, v179
	v_and_b32_e32 v171, 0xffff0000, v179
	v_add_f32_e32 v168, v168, v170
	v_add_f32_e32 v169, v169, v171
	v_lshlrev_b32_e32 v170, 16, v181
	v_and_b32_e32 v171, 0xffff0000, v181
	v_add_f32_e32 v168, v168, v170
	v_add_f32_e32 v169, v169, v171
	v_add_f32_e32 v166, v166, v184
	v_add_f32_e32 v167, v167, v185
	v_lshlrev_b32_e32 v184, 16, v174
	v_and_b32_e32 v185, 0xffff0000, v174
	v_lshlrev_b32_e32 v174, 16, v154
	v_and_b32_e32 v175, 0xffff0000, v154
	v_lshlrev_b32_e32 v154, 16, v155
	v_and_b32_e32 v155, 0xffff0000, v155
	v_add_f32_e32 v150, v150, v194
	v_add_f32_e32 v151, v151, v195
	v_lshlrev_b32_e32 v194, 16, v186
	v_and_b32_e32 v195, 0xffff0000, v186
	v_add_f32_e32 v166, v166, v184
	v_add_f32_e32 v167, v167, v185
	v_lshlrev_b32_e32 v184, 16, v176
	v_and_b32_e32 v185, 0xffff0000, v176
	v_add_f32_e32 v150, v150, v194
	v_add_f32_e32 v151, v151, v195
	v_lshlrev_b32_e32 v194, 16, v188
	v_and_b32_e32 v195, 0xffff0000, v188
	v_add_f32_e32 v166, v166, v184
	v_add_f32_e32 v167, v167, v185
	v_lshlrev_b32_e32 v184, 16, v178
	v_and_b32_e32 v185, 0xffff0000, v178
	v_add_f32_e32 v150, v150, v194
	v_add_f32_e32 v151, v151, v195
	v_lshlrev_b32_e32 v194, 16, v190
	v_and_b32_e32 v195, 0xffff0000, v190
	v_add_f32_e32 v166, v166, v184
	v_add_f32_e32 v167, v167, v185
	v_lshlrev_b32_e32 v184, 16, v180
	v_and_b32_e32 v185, 0xffff0000, v180
	v_add_f32_e32 v146, v146, v204
	v_add_f32_e32 v147, v147, v205
	v_lshlrev_b32_e32 v204, 16, v202
	v_and_b32_e32 v205, 0xffff0000, v202
	v_add_f32_e32 v150, v150, v194
	v_add_f32_e32 v151, v151, v195
	v_lshlrev_b32_e32 v194, 16, v192
	s_waitcnt vmcnt(1)
	v_lshlrev_b32_e32 v170, 16, v183
	v_and_b32_e32 v171, 0xffff0000, v183
	v_add_f32_e32 v168, v168, v170
	v_add_f32_e32 v169, v169, v171
	v_lshlrev_b32_e32 v170, 16, v128
	v_and_b32_e32 v171, 0xffff0000, v128
	v_lshlrev_b32_e32 v128, 16, v129
	v_and_b32_e32 v129, 0xffff0000, v129
	v_add_f32_e32 v128, 0, v128
	v_add_f32_e32 v129, 0, v129
	v_add_f32_e32 v170, 0, v170
	v_add_f32_e32 v171, 0, v171
	v_add_f32_e32 v128, v128, v154
	v_add_f32_e32 v129, v129, v155
	v_lshlrev_b32_e32 v154, 16, v157
	v_and_b32_e32 v155, 0xffff0000, v157
	v_add_f32_e32 v128, v128, v154
	v_add_f32_e32 v129, v129, v155
	v_lshlrev_b32_e32 v154, 16, v159
	v_and_b32_e32 v155, 0xffff0000, v159
	v_add_f32_e32 v128, v128, v154
	v_add_f32_e32 v129, v129, v155
	v_lshlrev_b32_e32 v154, 16, v161
	v_and_b32_e32 v155, 0xffff0000, v161
	v_add_f32_e32 v128, v128, v154
	v_add_f32_e32 v129, v129, v155
	v_lshlrev_b32_e32 v154, 16, v163
	v_and_b32_e32 v155, 0xffff0000, v163
	v_add_f32_e32 v128, v128, v154
	v_add_f32_e32 v129, v129, v155
	v_lshlrev_b32_e32 v154, 16, v165
	v_and_b32_e32 v155, 0xffff0000, v165
	v_add_f32_e32 v128, v128, v154
	v_add_f32_e32 v129, v129, v155
	v_add_f32_e32 v170, v170, v174
	v_add_f32_e32 v171, v171, v175
	v_lshlrev_b32_e32 v174, 16, v156
	v_and_b32_e32 v175, 0xffff0000, v156
	v_lshlrev_b32_e32 v156, 16, v114
	v_and_b32_e32 v157, 0xffff0000, v114
	v_lshlrev_b32_e32 v114, 16, v115
	v_and_b32_e32 v115, 0xffff0000, v115
	v_add_f32_e32 v170, v170, v174
	v_add_f32_e32 v171, v171, v175
	v_lshlrev_b32_e32 v174, 16, v158
	v_and_b32_e32 v175, 0xffff0000, v158
	v_add_f32_e32 v156, 0, v156
	v_add_f32_e32 v157, 0, v157
	s_waitcnt vmcnt(0)
; DI float bf_lo(unsigned u) { return __uint_as_float(u << 16); }
; DI float bf_hi(unsigned u) { return __uint_as_float(u & 0xffff0000u); }
; DI void rowpass(const Params& p, int l, bool first, int wv, char* smem) {
;     ...
; #pragma unroll
;         for (int kc = 0; kc < 8; ++kc) {
;           const u16* yp = p.ypart + ((size_t)kc * 1024 + (size_t)(b * 256 + j)) * DM;
; #pragma unroll
;           for (int i = 0; i < 8; ++i) {
;             const u32x2 u = *(const u32x2*)(yp + i * 256 + lane * 4);
;             yv[i][0] += bf_lo(u[0]); yv[i][1] += bf_hi(u[0]); yv[i][2] += bf_lo(u[1]); yv[i][3] += bf_hi(u[1]);
;           }
;         }
	v_lshlrev_b32_e32 v154, 16, v173
	v_and_b32_e32 v155, 0xffff0000, v173
	v_add_f32_e32 v154, v128, v154
	v_add_f32_e32 v155, v129, v155
	global_load_dwordx2 v[128:129], v[112:113], off offset:3072
	v_lshlrev_b32_e32 v158, 16, v116
	global_load_dwordx2 v[112:113], v[112:113], off offset:3584
	v_and_b32_e32 v159, 0xffff0000, v116
	v_add_f32_e32 v114, 0, v114
	v_add_f32_e32 v115, 0, v115
	v_lshlrev_b32_e32 v116, 16, v117
	v_and_b32_e32 v117, 0xffff0000, v117
	v_add_f32_e32 v156, v156, v158
	v_add_f32_e32 v157, v157, v159
	v_lshlrev_b32_e32 v158, 16, v118
	v_and_b32_e32 v159, 0xffff0000, v118
	v_add_f32_e32 v114, v114, v116
	v_add_f32_e32 v115, v115, v117
	v_lshlrev_b32_e32 v116, 16, v119
	v_and_b32_e32 v117, 0xffff0000, v119
	v_add_f32_e32 v156, v156, v158
	v_add_f32_e32 v157, v157, v159
	v_lshlrev_b32_e32 v158, 16, v120
	v_and_b32_e32 v159, 0xffff0000, v120
	v_add_f32_e32 v114, v114, v116
	v_add_f32_e32 v115, v115, v117
	v_lshlrev_b32_e32 v116, 16, v121
	v_and_b32_e32 v117, 0xffff0000, v121
	v_add_f32_e32 v156, v156, v158
	v_add_f32_e32 v157, v157, v159
	v_lshlrev_b32_e32 v158, 16, v122
	v_and_b32_e32 v159, 0xffff0000, v122
	v_add_f32_e32 v114, v114, v116
	v_add_f32_e32 v115, v115, v117
	v_lshlrev_b32_e32 v116, 16, v123
	v_and_b32_e32 v117, 0xffff0000, v123
	v_add_f32_e32 v156, v156, v158
	v_add_f32_e32 v157, v157, v159
	v_lshlrev_b32_e32 v158, 16, v124
	v_and_b32_e32 v159, 0xffff0000, v124
	v_add_f32_e32 v114, v114, v116
	v_add_f32_e32 v115, v115, v117
	v_lshlrev_b32_e32 v116, 16, v125
	v_and_b32_e32 v117, 0xffff0000, v125
	v_add_f32_e32 v156, v156, v158
	v_add_f32_e32 v157, v157, v159
	v_lshlrev_b32_e32 v158, 16, v126
	v_and_b32_e32 v159, 0xffff0000, v126
	v_add_f32_e32 v114, v114, v116
	v_add_f32_e32 v115, v115, v117
	v_lshlrev_b32_e32 v116, 16, v127
	v_and_b32_e32 v117, 0xffff0000, v127
	v_add_f32_e32 v156, v156, v158
	v_add_f32_e32 v157, v157, v159
	v_add_f32_e32 v114, v114, v116
	v_add_f32_e32 v115, v115, v117
	v_add_f32_e32 v170, v170, v174
	v_add_f32_e32 v171, v171, v175
	v_lshlrev_b32_e32 v174, 16, v160
	v_and_b32_e32 v175, 0xffff0000, v160
	v_add_f32_e32 v170, v170, v174
	v_add_f32_e32 v171, v171, v175
	v_lshlrev_b32_e32 v174, 16, v162
	v_and_b32_e32 v175, 0xffff0000, v162
	v_add_f32_e32 v170, v170, v174
	v_add_f32_e32 v171, v171, v175
	v_lshlrev_b32_e32 v174, 16, v164
	v_and_b32_e32 v175, 0xffff0000, v164
	v_and_b32_e32 v195, 0xffff0000, v192
	v_add_f32_e32 v166, v166, v184
	v_add_f32_e32 v167, v167, v185
	v_lshlrev_b32_e32 v184, 16, v182
	v_and_b32_e32 v185, 0xffff0000, v182
	v_add_f32_e32 v170, v170, v174
	v_add_f32_e32 v171, v171, v175
	v_lshlrev_b32_e32 v174, 16, v172
	v_and_b32_e32 v175, 0xffff0000, v172
	v_add_f32_e32 v138, v138, v226
	v_add_f32_e32 v139, v139, v227
	v_add_f32_e32 v142, v142, v216
	v_add_f32_e32 v143, v143, v217
	v_add_f32_e32 v146, v146, v204
	v_add_f32_e32 v147, v147, v205
	v_add_f32_e32 v150, v150, v194
	v_add_f32_e32 v151, v151, v195
	v_add_f32_e32 v166, v166, v184
	v_add_f32_e32 v167, v167, v185
	v_add_f32_e32 v170, v170, v174
	v_add_f32_e32 v171, v171, v175
	s_waitcnt vmcnt(1)
	v_lshlrev_b32_e32 v158, 16, v128
	v_and_b32_e32 v159, 0xffff0000, v128
	v_lshlrev_b32_e32 v116, 16, v129
	v_and_b32_e32 v117, 0xffff0000, v129
	v_add_f32_e32 v156, v156, v158
	v_add_f32_e32 v157, v157, v159
	v_add_f32_e32 v158, v114, v116
	v_add_f32_e32 v159, v115, v117
	v_lshlrev_b32_e32 v114, 16, v98
	v_and_b32_e32 v115, 0xffff0000, v98
	v_lshlrev_b32_e32 v98, 16, v99
	v_and_b32_e32 v99, 0xffff0000, v99
	v_add_f32_e32 v114, 0, v114
	v_add_f32_e32 v115, 0, v115
	v_lshlrev_b32_e32 v116, 16, v100
	v_and_b32_e32 v117, 0xffff0000, v100
	v_add_f32_e32 v98, 0, v98
	v_add_f32_e32 v99, 0, v99
	v_lshlrev_b32_e32 v100, 16, v101
	v_and_b32_e32 v101, 0xffff0000, v101
	v_add_f32_e32 v114, v114, v116
	v_add_f32_e32 v115, v115, v117
	v_lshlrev_b32_e32 v116, 16, v102
	v_and_b32_e32 v117, 0xffff0000, v102
	v_add_f32_e32 v98, v98, v100
	v_add_f32_e32 v99, v99, v101
	v_lshlrev_b32_e32 v100, 16, v103
	v_and_b32_e32 v101, 0xffff0000, v103
	v_add_f32_e32 v114, v114, v116
	v_add_f32_e32 v115, v115, v117
	v_lshlrev_b32_e32 v116, 16, v104
	v_and_b32_e32 v117, 0xffff0000, v104
	v_add_f32_e32 v98, v98, v100
	v_add_f32_e32 v99, v99, v101
	v_lshlrev_b32_e32 v100, 16, v105
	v_and_b32_e32 v101, 0xffff0000, v105
	v_add_f32_e32 v114, v114, v116
	v_add_f32_e32 v115, v115, v117
	v_lshlrev_b32_e32 v116, 16, v106
	v_and_b32_e32 v117, 0xffff0000, v106
	v_add_f32_e32 v98, v98, v100
	v_add_f32_e32 v99, v99, v101
	v_lshlrev_b32_e32 v100, 16, v107
	v_and_b32_e32 v101, 0xffff0000, v107
	v_add_f32_e32 v114, v114, v116
	v_add_f32_e32 v115, v115, v117
	v_lshlrev_b32_e32 v116, 16, v108
	v_and_b32_e32 v117, 0xffff0000, v108
	v_add_f32_e32 v98, v98, v100
	v_add_f32_e32 v99, v99, v101
	v_lshlrev_b32_e32 v100, 16, v109
	v_and_b32_e32 v101, 0xffff0000, v109
	v_add_f32_e32 v114, v114, v116
	v_add_f32_e32 v115, v115, v117
	v_lshlrev_b32_e32 v116, 16, v110
	v_and_b32_e32 v117, 0xffff0000, v110
	v_add_f32_e32 v98, v98, v100
	v_add_f32_e32 v99, v99, v101
	v_lshlrev_b32_e32 v100, 16, v111
	v_and_b32_e32 v101, 0xffff0000, v111
	v_add_f32_e32 v114, v114, v116
	v_add_f32_e32 v115, v115, v117
	s_waitcnt vmcnt(0)
	v_lshlrev_b32_e32 v116, 16, v112
	v_and_b32_e32 v117, 0xffff0000, v112
	v_add_f32_e32 v98, v98, v100
	v_add_f32_e32 v99, v99, v101
	v_lshlrev_b32_e32 v100, 16, v113
	v_and_b32_e32 v101, 0xffff0000, v113
	v_add_f32_e32 v160, v114, v116
	v_add_f32_e32 v161, v115, v117
	v_add_f32_e32 v162, v98, v100
	v_add_f32_e32 v163, v99, v101

; DI void rowpass(const Params& p, int l, bool first, int wv, char* smem) {
;     ...
;       for (int i = 0; i < 8; ++i) ss += yv[i][0] * yv[i][0] + yv[i][1] * yv[i][1] + yv[i][2] * yv[i][2] + yv[i][3] * yv[i][3];
;       const float* gate = p.mod + (size_t)(l * 5 + mr) * 6144 + 4096;
;       f32x4 gtv[8];
; #pragma unroll
;       for (int i = 0; i < 8; ++i) gtv[i] = *(const f32x4*)(gate + i * 256 + lane * 4);
;       f32x4 shv[8], scv[8];
;       if (l < 3) {
;         const float* shift = p.mod + (size_t)(lnext * 5 + mr) * 6144;
; #pragma unroll
;         for (int i = 0; i < 8; ++i) { shv[i] = *(const f32x4*)(shift + i * 256 + lane * 4); scv[i] = *(const f32x4*)(shift + 2048 + i * 256 + lane * 4); }
;       }
;       ss = wave_sum(ss);
;       const float r1 = rsqrtf(ss * (1.f / DM) + EPSV);
; #pragma unroll
;       for (int i = 0; i < 8; ++i) {
;         const f32x4 gpv = *(const f32x4*)(lg_post + i * 256 + lane * 4);
; #pragma unroll
;         for (int e = 0; e < 4; ++e) hv[i][e] += gtv[i][e] * ((yv[i][e] * r1) * gpv[e]);
;         *(f32x4*)(hout + i * 256 + lane * 4) = hv[i];
;       }
.Lrp_pfset:
	v_writelane_b32 v255, s2, 62
	v_mul_f32_e32 v0, v139, v139
	v_mul_f32_e32 v164, v143, v143
	v_fmac_f32_e32 v164, v142, v142
	v_mul_f32_e32 v165, v147, v147
	v_fmac_f32_e32 v0, v138, v138
	v_fmac_f32_e32 v164, v144, v144
	v_fmac_f32_e32 v165, v146, v146
	v_mul_f32_e32 v172, v151, v151
	v_fmac_f32_e32 v0, v140, v140
	v_fmac_f32_e32 v164, v145, v145
	v_fmac_f32_e32 v165, v148, v148
	v_fmac_f32_e32 v172, v150, v150
	v_mul_f32_e32 v173, v167, v167
	v_fmac_f32_e32 v0, v141, v141
	v_fmac_f32_e32 v165, v149, v149
	v_fmac_f32_e32 v172, v152, v152
	v_fmac_f32_e32 v173, v166, v166
	v_mul_f32_e32 v174, v171, v171
	v_add_f32_e32 v0, v0, v164
	v_fmac_f32_e32 v172, v153, v153
	v_fmac_f32_e32 v173, v168, v168
	v_fmac_f32_e32 v174, v170, v170
	v_mul_f32_e32 v175, v157, v157
	v_add_f32_e32 v0, v165, v0
	v_fmac_f32_e32 v173, v169, v169
	v_fmac_f32_e32 v174, v154, v154
	v_fmac_f32_e32 v175, v156, v156
	v_mul_f32_e32 v176, v161, v161
	v_add_f32_e32 v0, v172, v0
	v_fmac_f32_e32 v174, v155, v155
	v_fmac_f32_e32 v175, v158, v158
	v_fmac_f32_e32 v176, v160, v160
	v_add_f32_e32 v0, v173, v0
	v_fmac_f32_e32 v175, v159, v159
	v_fmac_f32_e32 v176, v162, v162
	v_add_f32_e32 v0, v174, v0
	v_fmac_f32_e32 v176, v163, v163
	v_add_f32_e32 v0, v175, v0
	v_add_f32_e32 v0, v176, v0
	v_mov_b32_e32 v164, v0
	s_nop 1
	v_permlane32_swap_b32_e32 v0, v164
	v_add_f32_e32 v0, v0, v164
	ds_swizzle_b32 v164, v0 offset:swizzle(SWAP,16)
	s_mov_b32 s2, 0x800000
	ds_read_b128 v[172:175], v212
	s_waitcnt lgkmcnt(1)
	v_add_f32_e32 v0, v0, v164
	ds_swizzle_b32 v164, v0 offset:swizzle(SWAP,8)
	s_waitcnt lgkmcnt(0)
	v_add_f32_e32 v0, v0, v164
	ds_swizzle_b32 v164, v0 offset:swizzle(SWAP,4)
	s_waitcnt lgkmcnt(0)
	v_add_f32_e32 v0, v0, v164
	ds_swizzle_b32 v164, v0 offset:swizzle(SWAP,2)
	s_waitcnt lgkmcnt(0)
	v_add_f32_e32 v0, v0, v164
	ds_swizzle_b32 v164, v0 offset:swizzle(SWAP,1)
	s_waitcnt lgkmcnt(0)
	v_add_f32_e32 v0, v0, v164
	v_fmamk_f32 v0, v0, 0x3a000000, v232
	v_cmp_gt_f32_e32 vcc, s2, v0
	v_mul_f32_e32 v164, 0x4b800000, v0
	s_nop 0
	v_cndmask_b32_e32 v0, v0, v164, vcc
	v_rsq_f32_e32 v0, v0
	s_nop 0
	v_mul_f32_e32 v164, 0x45800000, v0
	v_cndmask_b32_e32 v0, v0, v164, vcc
	v_mul_f32_e32 v138, v138, v0
	v_mul_f32_e32 v139, v139, v0
	v_lshl_add_u64 v[164:165], v[130:131], 2, s[0:1]
	v_mul_f32_e32 v138, v172, v138
	v_mul_f32_e32 v139, v173, v139
	s_movk_i32 s0, 0x1000
	v_fma_f32 v94, v126, v138, v94
	v_fma_f32 v95, v127, v139, v95
	v_mul_f32_e32 v126, v140, v0
	v_mul_f32_e32 v127, v141, v0
	v_mul_f32_e32 v138, v142, v0
	v_mul_f32_e32 v139, v143, v0
	v_mul_f32_e32 v126, v174, v126
	v_mul_f32_e32 v127, v175, v127
	s_nop 0
	v_fma_f32 v96, v128, v126, v96
	v_fma_f32 v97, v129, v127, v97
	ds_read_b128 v[126:129], v212 offset:1024
	global_store_dwordx4 v[164:165], v[94:97], off
	s_waitcnt lgkmcnt(0)
	v_mul_f32_e32 v126, v126, v138
	v_mul_f32_e32 v127, v127, v139
	s_nop 0
	v_fma_f32 v90, v122, v126, v90
	v_fma_f32 v91, v123, v127, v91
	v_mul_f32_e32 v122, v144, v0
	v_mul_f32_e32 v123, v145, v0
	v_mul_f32_e32 v126, v146, v0
	v_mul_f32_e32 v127, v147, v0
	v_mul_f32_e32 v122, v128, v122
	v_mul_f32_e32 v123, v129, v123
	s_nop 0
	v_fma_f32 v92, v124, v122, v92
	v_fma_f32 v93, v125, v123, v93
	ds_read_b128 v[122:125], v212 offset:2048
	global_store_dwordx4 v[164:165], v[90:93], off offset:1024
	s_waitcnt lgkmcnt(0)
	v_mul_f32_e32 v122, v122, v126
	v_mul_f32_e32 v123, v123, v127
	s_nop 0
	v_fma_f32 v86, v118, v122, v86
	v_fma_f32 v87, v119, v123, v87
	v_mul_f32_e32 v118, v148, v0
	v_mul_f32_e32 v119, v149, v0
	v_mul_f32_e32 v122, v150, v0
	v_mul_f32_e32 v123, v151, v0
	v_mul_f32_e32 v118, v124, v118
	v_mul_f32_e32 v119, v125, v119
	s_nop 0
	v_fma_f32 v88, v120, v118, v88
	v_fma_f32 v89, v121, v119, v89
	ds_read_b128 v[118:121], v212 offset:3072
	global_store_dwordx4 v[164:165], v[86:89], off offset:2048
	s_waitcnt lgkmcnt(0)
	v_mul_f32_e32 v118, v118, v122
	v_mul_f32_e32 v119, v119, v123
	v_fma_f32 v82, v114, v118, v82
	v_fma_f32 v83, v115, v119, v83
	v_mul_f32_e32 v114, v152, v0
	v_mul_f32_e32 v115, v153, v0
	v_mul_f32_e32 v118, v166, v0
	v_mul_f32_e32 v119, v167, v0
	v_mul_f32_e32 v114, v120, v114
	v_mul_f32_e32 v115, v121, v115
	s_nop 0
	v_fma_f32 v84, v116, v114, v84
	v_fma_f32 v85, v117, v115, v85
	ds_read_b128 v[114:117], v212 offset:4096
	global_store_dwordx4 v[164:165], v[82:85], off offset:3072
	s_waitcnt lgkmcnt(0)
	v_mul_f32_e32 v114, v114, v118
	v_mul_f32_e32 v115, v115, v119
	v_fma_f32 v78, v110, v114, v78
	v_fma_f32 v79, v111, v115, v79
	v_mul_f32_e32 v110, v168, v0
	v_mul_f32_e32 v111, v169, v0
	v_add_co_u32_e32 v114, vcc, s0, v164
	v_mul_f32_e32 v110, v116, v110
	v_mul_f32_e32 v111, v117, v111
	v_mul_f32_e32 v116, v170, v0
	v_mul_f32_e32 v117, v171, v0
	v_fma_f32 v80, v112, v110, v80
	v_fma_f32 v81, v113, v111, v81
	ds_read_b128 v[110:113], v212 offset:5120
	v_addc_co_u32_e32 v115, vcc, 0, v165, vcc
	s_and_b64 vcc, exec, s[4:5]
	global_store_dwordx4 v[114:115], v[78:81], off
	s_waitcnt lgkmcnt(0)
	v_mul_f32_e32 v110, v116, v110
	v_mul_f32_e32 v111, v117, v111
	v_fma_f32 v74, v106, v110, v74
	v_fma_f32 v75, v107, v111, v75
	v_mul_f32_e32 v106, v154, v0
	v_mul_f32_e32 v107, v155, v0
	v_mul_f32_e32 v110, v156, v0
	v_mul_f32_e32 v111, v157, v0
	v_mul_f32_e32 v106, v106, v112
	v_mul_f32_e32 v107, v107, v113
	s_nop 0
	v_fma_f32 v76, v108, v106, v76
	v_fma_f32 v77, v109, v107, v77
	ds_read_b128 v[106:109], v212 offset:6144
	global_store_dwordx4 v[114:115], v[74:77], off offset:1024
	s_waitcnt lgkmcnt(0)
	v_mul_f32_e32 v106, v110, v106
	v_mul_f32_e32 v107, v111, v107
	v_fma_f32 v70, v102, v106, v70
	v_fma_f32 v71, v103, v107, v71
	v_mul_f32_e32 v102, v158, v0
	v_mul_f32_e32 v103, v159, v0
	v_mul_f32_e32 v106, v160, v0
	v_mul_f32_e32 v107, v161, v0
	v_mul_f32_e32 v102, v102, v108
	v_mul_f32_e32 v103, v103, v109
	s_nop 0
	v_fma_f32 v72, v104, v102, v72
	v_fma_f32 v73, v105, v103, v73
	ds_read_b128 v[102:105], v212 offset:7168
	global_store_dwordx4 v[114:115], v[70:73], off offset:2048
	s_waitcnt lgkmcnt(0)
	v_mul_f32_e32 v102, v106, v102
	v_mul_f32_e32 v103, v107, v103
	v_fma_f32 v66, v98, v102, v66
	v_fma_f32 v67, v99, v103, v67
	v_mul_f32_e32 v98, v162, v0
	v_mul_f32_e32 v99, v163, v0
	s_nop 0
	v_mul_f32_e32 v98, v98, v104
	v_mul_f32_e32 v99, v99, v105
	s_nop 0
	v_fma_f32 v68, v100, v98, v68
	v_fma_f32 v69, v101, v99, v69
	global_store_dwordx4 v[114:115], v[66:69], off offset:3072
	s_cbranch_vccnz .LBB0_103
; DI unsigned pack2(float a, float b) { f2_t v = {a, b}; bf2_t r = __builtin_convertvector(v, bf2_t); return __builtin_bit_cast(unsigned, r); }
; DI void rowpass(const Params& p, int l, bool first, int wv, char* smem) {
;     ...
;       if (l < 3) {
;         float s2 = 0.f;
; #pragma unroll
;         for (int i = 0; i < 8; ++i) s2 += hv[i][0] * hv[i][0] + hv[i][1] * hv[i][1] + hv[i][2] * hv[i][2] + hv[i][3] * hv[i][3];
;         s2 = wave_sum(s2);
;         const float r2 = rsqrtf(s2 * (1.f / DM) + EPSV);
;         u16* np = p.nbuf + (size_t)R * DM;
; #pragma unroll
;         for (int i = 0; i < 8; ++i) {
;           const f32x4 grv = *(const f32x4*)(lg_pre + i * 256 + lane * 4);
;           float o[4];
; #pragma unroll
;           for (int e = 0; e < 4; ++e) o[e] = ((hv[i][e] * r2) * grv[e]) * (1.f + scv[i][e]) + shv[i][e];
;           u32x2 pk; pk[0] = pack2(o[0], o[1]); pk[1] = pack2(o[2], o[3]);
;           *(u32x2*)(np + i * 256 + lane * 4) = pk;
;         }
	v_mul_f32_e32 v0, v95, v95
	v_fma_f32 v98, v94, v94, v0
	v_fma_f32 v99, v95, v95, v0
	v_mul_f32_e32 v0, v97, v97
	v_fma_f32 v98, v96, v96, v98
	v_fma_f32 v99, v97, v97, v99
	s_ashr_i32 s7, s6, 31
	v_add_f32_e32 v98, v0, v98
	v_add_f32_e32 v99, v0, v99
	v_mul_f32_e32 v0, v91, v91
	v_fma_f32 v100, v90, v90, v0
	v_fma_f32 v101, v91, v91, v0
	v_mul_f32_e32 v0, v93, v93
	v_fma_f32 v100, v92, v92, v100
	v_fma_f32 v101, v93, v93, v101
	s_lshl_b64 s[0:1], s[6:7], 12
	v_add_f32_e32 v100, v0, v100
	v_add_f32_e32 v101, v0, v101
	v_mul_f32_e32 v0, v87, v87
	v_add_f32_e32 v98, v98, v100
	v_add_f32_e32 v99, v99, v101
	v_fma_f32 v100, v86, v86, v0
	v_fma_f32 v101, v87, v87, v0
	v_mul_f32_e32 v0, v89, v89
	v_fma_f32 v100, v88, v88, v100
	v_fma_f32 v101, v89, v89, v101
	s_nop 0
	v_add_f32_e32 v100, v0, v100
	v_add_f32_e32 v101, v0, v101
	v_mul_f32_e32 v0, v83, v83
	v_add_f32_e32 v98, v100, v98
	v_add_f32_e32 v99, v101, v99
	v_fma_f32 v100, v82, v82, v0
	v_fma_f32 v101, v83, v83, v0
	v_mul_f32_e32 v0, v85, v85
	v_fma_f32 v100, v84, v84, v100
	v_fma_f32 v101, v85, v85, v101
	s_nop 0
	v_add_f32_e32 v100, v0, v100
	v_add_f32_e32 v101, v0, v101
	v_mul_f32_e32 v0, v79, v79
	v_add_f32_e32 v98, v100, v98
	v_add_f32_e32 v99, v101, v99
	v_fma_f32 v100, v78, v78, v0
	v_fma_f32 v101, v79, v79, v0
	v_mul_f32_e32 v0, v81, v81
	v_fma_f32 v100, v80, v80, v100
	v_fma_f32 v101, v81, v81, v101
	s_nop 0
	v_add_f32_e32 v100, v0, v100
	v_add_f32_e32 v101, v0, v101
	v_mul_f32_e32 v0, v75, v75
	v_add_f32_e32 v98, v100, v98
	v_add_f32_e32 v99, v101, v99
	v_fma_f32 v100, v74, v74, v0
	v_fma_f32 v101, v75, v75, v0
	v_mul_f32_e32 v0, v77, v77
	v_fma_f32 v100, v76, v76, v100
	v_fma_f32 v101, v77, v77, v101
	s_nop 0
	v_add_f32_e32 v100, v0, v100
	v_add_f32_e32 v101, v0, v101
	v_mul_f32_e32 v0, v71, v71
	v_add_f32_e32 v98, v100, v98
	v_add_f32_e32 v99, v101, v99
	v_fma_f32 v100, v70, v70, v0
	v_fma_f32 v101, v71, v71, v0
	v_mul_f32_e32 v0, v73, v73
	v_fma_f32 v100, v72, v72, v100
	v_fma_f32 v101, v73, v73, v101
	s_nop 0
	v_add_f32_e32 v100, v0, v100
	v_add_f32_e32 v101, v0, v101
	v_mul_f32_e32 v0, v67, v67
	v_add_f32_e32 v98, v100, v98
	v_add_f32_e32 v99, v101, v99
	v_fma_f32 v100, v66, v66, v0
	v_fma_f32 v101, v67, v67, v0
	v_mul_f32_e32 v0, v69, v69
	v_fma_f32 v100, v68, v68, v100
	v_fma_f32 v101, v69, v69, v101
	s_nop 0
	v_add_f32_e32 v100, v0, v100
	v_add_f32_e32 v101, v0, v101
	v_add_f32_e32 v98, v100, v98
	v_add_f32_e32 v99, v101, v99
	ds_read_b128 v[100:103], v212 offset:8192
	v_mov_b32_e32 v0, v98
	s_nop 1
	v_permlane32_swap_b32_e32 v98, v0
	v_add_f32_e32 v0, v98, v0
	ds_swizzle_b32 v98, v0 offset:swizzle(SWAP,16)
	s_waitcnt lgkmcnt(0)
	v_add_f32_e32 v0, v0, v98
	ds_swizzle_b32 v98, v0 offset:swizzle(SWAP,8)
	s_waitcnt lgkmcnt(0)
	v_add_f32_e32 v0, v0, v98
	ds_swizzle_b32 v98, v0 offset:swizzle(SWAP,4)
	s_waitcnt lgkmcnt(0)
	v_add_f32_e32 v0, v0, v98
	ds_swizzle_b32 v98, v0 offset:swizzle(SWAP,2)
	s_waitcnt lgkmcnt(0)
	v_add_f32_e32 v0, v0, v98
	ds_swizzle_b32 v98, v0 offset:swizzle(SWAP,1)
	s_waitcnt lgkmcnt(0)
	v_add_f32_e32 v0, v0, v98
	v_fmamk_f32 v0, v0, 0x3a000000, v232
	v_cmp_gt_f32_e32 vcc, s2, v0
	v_mul_f32_e32 v98, 0x4b800000, v0
	s_nop 0
	v_cndmask_b32_e32 v0, v0, v98, vcc
	v_rsq_f32_e32 v0, v0
	s_nop 0
	v_mul_f32_e32 v98, 0x45800000, v0
	v_cndmask_b32_e32 v0, v0, v98, vcc
	v_mul_f32_e32 v94, v94, v0
	v_mul_f32_e32 v95, v95, v0
	v_mul_f32_e32 v96, v96, v0
	v_mul_f32_e32 v97, v97, v0
	v_mul_f32_e32 v94, v100, v94
	v_mul_f32_e32 v95, v101, v95
	v_add_f32_e32 v100, 1.0, v30
	v_add_f32_e32 v101, 1.0, v31
	v_mul_f32_e32 v96, v102, v96
	v_mul_f32_e32 v97, v103, v97
	v_fma_f32 v94, v100, v94, v2
	v_fma_f32 v95, v101, v95, v3
	v_add_f32_e32 v100, 1.0, v32
	v_add_f32_e32 v101, 1.0, v33
	v_lshl_add_u64 v[98:99], v[134:135], 0, s[0:1]
	v_fma_f32 v96, v100, v96, v4
	v_fma_f32 v97, v101, v97, v5
	v_cvt_pk_bf16_f32 v94, v94, v95
	v_cvt_pk_bf16_f32 v95, v96, v97
	global_store_dwordx2 v[98:99], v[94:95], off
	ds_read_b128 v[94:97], v212 offset:9216
	v_mul_f32_e32 v90, v90, v0
	v_mul_f32_e32 v91, v91, v0
	v_mul_f32_e32 v92, v92, v0
	v_mul_f32_e32 v93, v93, v0
	v_mul_f32_e32 v86, v86, v0
	v_mul_f32_e32 v87, v87, v0
	v_mul_f32_e32 v88, v88, v0
	v_mul_f32_e32 v89, v89, v0
	s_waitcnt lgkmcnt(0)
; DI unsigned pack2(float a, float b) { f2_t v = {a, b}; bf2_t r = __builtin_convertvector(v, bf2_t); return __builtin_bit_cast(unsigned, r); }
; DI void rowpass(const Params& p, int l, bool first, int wv, char* smem) {
;     ...
; #pragma unroll
;         for (int i = 0; i < 8; ++i) {
;           const f32x4 grv = *(const f32x4*)(lg_pre + i * 256 + lane * 4);
;           float o[4];
; #pragma unroll
;           for (int e = 0; e < 4; ++e) o[e] = ((hv[i][e] * r2) * grv[e]) * (1.f + scv[i][e]) + shv[i][e];
;           u32x2 pk; pk[0] = pack2(o[0], o[1]); pk[1] = pack2(o[2], o[3]);
;           *(u32x2*)(np + i * 256 + lane * 4) = pk;
;         }
	v_mul_f32_e32 v90, v94, v90
	v_mul_f32_e32 v91, v95, v91
	v_add_f32_e32 v94, 1.0, v18
	v_add_f32_e32 v95, 1.0, v19
	v_mul_f32_e32 v92, v96, v92
	v_mul_f32_e32 v93, v97, v93
	v_fma_f32 v90, v94, v90, v6
	v_fma_f32 v91, v95, v91, v7
	v_add_f32_e32 v94, 1.0, v20
	v_add_f32_e32 v95, 1.0, v21
	v_cvt_pk_bf16_f32 v90, v90, v91
	v_fma_f32 v92, v94, v92, v8
	v_fma_f32 v93, v95, v93, v9
	v_mul_f32_e32 v82, v82, v0
	v_mul_f32_e32 v83, v83, v0
	v_cvt_pk_bf16_f32 v91, v92, v93
	global_store_dwordx2 v[98:99], v[90:91], off offset:512
	ds_read_b128 v[90:93], v212 offset:10240
	v_mul_f32_e32 v84, v84, v0
	v_mul_f32_e32 v85, v85, v0
	v_mul_f32_e32 v78, v78, v0
	v_mul_f32_e32 v79, v79, v0
	v_mul_f32_e32 v80, v80, v0
	v_mul_f32_e32 v81, v81, v0
	v_mul_f32_e32 v74, v74, v0
	v_mul_f32_e32 v75, v75, v0
	s_waitcnt lgkmcnt(0)
	v_mul_f32_e32 v86, v90, v86
	v_mul_f32_e32 v87, v91, v87
	v_add_f32_e32 v90, 1.0, v22
	v_add_f32_e32 v91, 1.0, v23
	v_mul_f32_e32 v88, v92, v88
	v_mul_f32_e32 v89, v93, v89
	v_fma_f32 v86, v90, v86, v14
	v_fma_f32 v87, v91, v87, v15
	v_add_f32_e32 v90, 1.0, v24
	v_add_f32_e32 v91, 1.0, v25
	v_cvt_pk_bf16_f32 v86, v86, v87
	v_fma_f32 v88, v90, v88, v16
	v_fma_f32 v89, v91, v89, v17
	v_mul_f32_e32 v76, v76, v0
	v_mul_f32_e32 v77, v77, v0
	v_cvt_pk_bf16_f32 v87, v88, v89
	global_store_dwordx2 v[98:99], v[86:87], off offset:1024
	ds_read_b128 v[86:89], v212 offset:11264
	v_mul_f32_e32 v70, v70, v0
	v_mul_f32_e32 v71, v71, v0
	v_mul_f32_e32 v72, v72, v0
	v_mul_f32_e32 v73, v73, v0
	v_mul_f32_e32 v66, v66, v0
	v_mul_f32_e32 v67, v67, v0
	v_mul_f32_e32 v68, v68, v0
	v_mul_f32_e32 v69, v69, v0
	s_waitcnt lgkmcnt(0)
	v_mul_f32_e32 v82, v86, v82
	v_mul_f32_e32 v83, v87, v83
	v_add_f32_e32 v86, 1.0, v26
	v_add_f32_e32 v87, 1.0, v27
	v_mul_f32_e32 v84, v88, v84
	v_mul_f32_e32 v85, v89, v85
	v_fma_f32 v82, v86, v82, v10
	v_fma_f32 v83, v87, v83, v11
	v_add_f32_e32 v86, 1.0, v28
	v_add_f32_e32 v87, 1.0, v29
	v_cvt_pk_bf16_f32 v82, v82, v83
	v_fma_f32 v84, v86, v84, v12
	v_fma_f32 v85, v87, v85, v13
	s_nop 0
	v_cvt_pk_bf16_f32 v83, v84, v85
	global_store_dwordx2 v[98:99], v[82:83], off offset:1536
	ds_read_b128 v[82:85], v212 offset:12288
	s_waitcnt lgkmcnt(0)
	v_mul_f32_e32 v78, v82, v78
	v_mul_f32_e32 v79, v83, v79
	v_add_f32_e32 v82, 1.0, v54
	v_add_f32_e32 v83, 1.0, v55
	v_mul_f32_e32 v80, v84, v80
	v_mul_f32_e32 v81, v85, v81
	v_fma_f32 v78, v82, v78, v34
	v_fma_f32 v79, v83, v79, v35
	v_add_f32_e32 v82, 1.0, v56
	v_add_f32_e32 v83, 1.0, v57
	v_cvt_pk_bf16_f32 v78, v78, v79
	v_fma_f32 v80, v82, v80, v36
	v_fma_f32 v81, v83, v81, v37
	s_nop 0
	v_cvt_pk_bf16_f32 v79, v80, v81
	global_store_dwordx2 v[98:99], v[78:79], off offset:2048
	ds_read_b128 v[78:81], v212 offset:13312
	s_waitcnt lgkmcnt(0)
	v_mul_f32_e32 v74, v74, v78
	v_mul_f32_e32 v75, v75, v79
	v_add_f32_e32 v78, 1.0, v50
	v_add_f32_e32 v79, 1.0, v51
	v_mul_f32_e32 v76, v76, v80
	v_mul_f32_e32 v77, v77, v81
	v_fma_f32 v74, v78, v74, v38
	v_fma_f32 v75, v79, v75, v39
	v_add_f32_e32 v78, 1.0, v52
	v_add_f32_e32 v79, 1.0, v53
	v_cvt_pk_bf16_f32 v74, v74, v75
	v_fma_f32 v76, v78, v76, v40
	v_fma_f32 v77, v79, v77, v41
	s_nop 0
	v_cvt_pk_bf16_f32 v75, v76, v77
	global_store_dwordx2 v[98:99], v[74:75], off offset:2560
	ds_read_b128 v[74:77], v212 offset:14336
	s_waitcnt lgkmcnt(0)
	v_mul_f32_e32 v70, v70, v74
	v_mul_f32_e32 v71, v71, v75
	v_add_f32_e32 v74, 1.0, v62
	v_add_f32_e32 v75, 1.0, v63
	v_mul_f32_e32 v72, v72, v76
	v_mul_f32_e32 v73, v73, v77
	v_fma_f32 v70, v74, v70, v42
	v_fma_f32 v71, v75, v71, v43
	v_add_f32_e32 v74, 1.0, v64
	v_add_f32_e32 v75, 1.0, v65
	v_cvt_pk_bf16_f32 v70, v70, v71
	v_fma_f32 v72, v74, v72, v44
	v_fma_f32 v73, v75, v73, v45
	s_nop 0
	v_cvt_pk_bf16_f32 v71, v72, v73
	global_store_dwordx2 v[98:99], v[70:71], off offset:3072
	ds_read_b128 v[70:73], v212 offset:15360
	s_waitcnt lgkmcnt(0)
	v_mul_f32_e32 v66, v66, v70
	v_mul_f32_e32 v67, v67, v71
	v_add_f32_e32 v70, 1.0, v58
	v_add_f32_e32 v71, 1.0, v59
	v_mul_f32_e32 v68, v68, v72
	v_mul_f32_e32 v69, v69, v73
	v_fma_f32 v66, v70, v66, v46
	v_fma_f32 v67, v71, v67, v47
	v_add_f32_e32 v70, 1.0, v60
	v_add_f32_e32 v71, 1.0, v61
	v_cvt_pk_bf16_f32 v66, v66, v67
	v_fma_f32 v68, v70, v68, v48
	v_fma_f32 v69, v71, v69, v49
	s_nop 0
	v_cvt_pk_bf16_f32 v67, v68, v69
	global_store_dwordx2 v[98:99], v[66:67], off offset:3584
	s_branch .LBB0_103

; template <int GP> DI void gemm_phase(const Params& p, int l, int which, char* smem, int wv) {
;     ...
;             if (ng) {
;               const float rinv = rinv8[ai * 4 + m];
; #pragma unroll
;               for (int e = 0; e < 8; ++e) { x1[e] = (x1[e] * rinv) * g1[e]; x2[e] = (x2[e] * rinv) * g2[e]; }
;             }
.LBB0_281:
	s_and_b64 vcc, exec, s[96:97]
	s_waitcnt vmcnt(0)
	s_cbranch_vccnz .LBB0_289
	v_mul_f32_e32 v178, v62, v176
	v_mul_f32_e32 v179, v63, v176
	v_mul_f32_e32 v180, v30, v176
	v_mul_f32_e32 v181, v31, v176
	v_mul_f32_e32 v194, v178, v146
	v_mul_f32_e32 v195, v179, v147
	v_mul_f32_e32 v178, v64, v176
	v_mul_f32_e32 v179, v65, v176
	v_mul_f32_e32 v186, v180, v148
	v_mul_f32_e32 v187, v181, v149
	v_mul_f32_e32 v180, v32, v176
	v_mul_f32_e32 v181, v33, v176
	v_mul_f32_e32 v188, v178, v150
	v_mul_f32_e32 v189, v179, v151
	v_mul_f32_e32 v178, v58, v176
	v_mul_f32_e32 v179, v59, v176
	v_mul_f32_e32 v182, v180, v152
	v_mul_f32_e32 v183, v181, v153
	v_mul_f32_e32 v180, v26, v176
	v_mul_f32_e32 v181, v27, v176
	v_mul_f32_e32 v184, v178, v154
	v_mul_f32_e32 v185, v179, v155
	v_mul_f32_e32 v178, v60, v176
	v_mul_f32_e32 v179, v61, v176
	v_mul_f32_e32 v177, v29, v176
	v_mul_f32_e32 v176, v28, v176
	v_mul_f32_e32 v180, v180, v156
	v_mul_f32_e32 v181, v181, v157
	v_mul_f32_e32 v178, v178, v158
	v_mul_f32_e32 v179, v179, v159
	v_mul_f32_e32 v176, v176, v160
	v_mul_f32_e32 v177, v177, v161
	s_branch .LBB0_290

; DI float fexp2(float x) { return __builtin_amdgcn_exp2f(x); }
; template <int GP> DI void gemm_phase(const Params& p, int l, int which, char* smem, int wv) {
;     ...
;         const int c1 = (hh == 64) ? ((wc & 1) * 32 + fq * 8) : ((wc & 1) * 64 + fq * 8);
;         const int c2 = c1 + hh;
;         const int nfq = (hh == 64) ? 32 : 16;
;         const int j0 = c1 & 63;
;         const bool use_col = (j0 >= nfq);
;         float frev[8];
; #pragma unroll
;         for (int e = 0; e < 8; ++e) frev[e] = rope ? fexp2(-(float)((j0 + e) & (nfq - 1)) * (13.287712379549449f / (float)nfq)) * 0.15915494309189535f : 0.f;
;     ...
;             if (rope && !isctx) {
;               const int tt = (R % TPB) - 256;
;               const float pos = (float)(use_col ? (tt & 63) : (tt >> 6));
; #pragma unroll
;               for (int e = 0; e < 8; ++e) {
;                 float rev = pos * frev[e];
;                 rev = rev - floorf(rev);
;                 const float cs = __builtin_amdgcn_cosf(rev), sn = __builtin_amdgcn_sinf(rev);
;                 const float a = x1[e], bq = x2[e];
;                 x1[e] = a * cs - bq * sn; x2[e] = bq * cs + a * sn;
;               }
.LBB0_290:
	s_mul_hi_i32 s6, s22, 0x38e38e39
	s_lshr_b32 s7, s6, 31
	s_ashr_i32 s6, s6, 1
	s_add_i32 s6, s6, s7
	s_mul_i32 s6, s6, 9
	s_sub_i32 s6, s22, s6
	s_cmp_lg_u32 s6, 0
	s_cselect_b64 s[6:7], -1, 0
	s_and_b64 s[10:11], s[0:1], s[6:7]
	s_and_b64 s[2:3], s[2:3], exec
	s_cselect_b32 s6, 32, 16
	v_cvt_f32_ubyte0_e32 v131, s6
	s_mov_b32 s4, 0x41549a78
	v_div_scale_f32 v137, s[2:3], v131, v131, s4
	v_rcp_f32_e32 v143, v137
	s_add_i32 s2, s6, -1
	v_and_b32_e32 v163, 56, v144
	v_cmp_gt_u32_e64 s[16:17], s6, v163
	v_fma_f32 v165, -v137, v143, 1.0
	v_fmac_f32_e32 v143, v165, v143
	v_div_scale_f32 v165, vcc, s4, v131, s4
	v_mul_f32_e32 v167, v165, v143
	v_fma_f32 v169, -v137, v167, v165
	v_fmac_f32_e32 v167, v169, v143
	v_fma_f32 v137, -v137, v167, v165
	v_div_fmas_f32 v137, v137, v143, v167
	v_div_fixup_f32 v131, v137, v131, s4
	v_bitop3_b32 v137, v144, s2, 56 bitop3:0x80
	v_cvt_f32_ubyte0_e32 v137, v137
	v_bitop3_b32 v143, v163, s2, 1 bitop3:0xc8
	v_mul_f32_e64 v137, v131, -v137
	v_cvt_f32_ubyte0_e32 v143, v143
	v_exp_f32_e32 v137, v137
	v_mul_f32_e64 v143, v131, -v143
	v_exp_f32_e32 v143, v143
	v_bitop3_b32 v165, v163, s2, 3 bitop3:0xc8
	v_mul_f32_e32 v137, 0.15915494, v137
	v_cndmask_b32_e64 v240, 0, v137, s[0:1]
	v_mul_f32_e32 v137, 0.15915494, v143
	v_bitop3_b32 v143, v163, s2, 2 bitop3:0xc8
	v_cvt_f32_ubyte0_e32 v143, v143
	v_mul_f32_e64 v143, v131, -v143
	v_cvt_f32_ubyte0_e32 v165, v165
	v_exp_f32_e32 v143, v143
	v_mul_f32_e64 v165, v131, -v165
	v_exp_f32_e32 v165, v165
	v_cndmask_b32_e64 v241, 0, v137, s[0:1]
	v_mul_f32_e32 v137, 0.15915494, v143
	v_bitop3_b32 v143, v163, s2, 4 bitop3:0xc8
	v_cndmask_b32_e64 v227, 0, v137, s[0:1]
	v_mul_f32_e32 v137, 0.15915494, v165
	v_cvt_f32_ubyte0_e32 v143, v143
	v_bitop3_b32 v165, v163, s2, 5 bitop3:0xc8
	v_mul_f32_e64 v143, v131, -v143
	v_cvt_f32_ubyte0_e32 v165, v165
	v_exp_f32_e32 v143, v143
	v_mul_f32_e64 v165, v131, -v165
	v_exp_f32_e32 v165, v165
	v_cndmask_b32_e64 v239, 0, v137, s[0:1]
	v_mul_f32_e32 v137, 0.15915494, v143
	v_cndmask_b32_e64 v143, 0, v137, s[0:1]
	v_mul_f32_e32 v137, 0.15915494, v165
	v_bitop3_b32 v165, v163, s2, 6 bitop3:0xc8
	v_bitop3_b32 v163, v163, s2, 7 bitop3:0xc8
	v_cvt_f32_ubyte0_e32 v165, v165
	v_cvt_f32_ubyte0_e32 v163, v163
	v_mul_f32_e64 v165, v131, -v165
	v_mul_f32_e64 v131, v131, -v163
	v_exp_f32_e32 v165, v165
	v_exp_f32_e32 v167, v131
	v_cndmask_b32_e64 v163, 0, v137, s[0:1]
	v_lshl_add_u32 v238, s22, 8, v209
	v_mul_f32_e32 v131, 0.15915494, v165
	v_mul_f32_e32 v137, 0.15915494, v167
	v_cndmask_b32_e64 v165, 0, 1, s[10:11]
	v_cndmask_b32_e64 v131, 0, v131, s[0:1]
	v_cmp_ne_u32_e64 s[30:31], 1, v165
	s_andn2_b64 vcc, exec, s[10:11]
	v_cndmask_b32_e64 v137, 0, v137, s[0:1]
	s_cbranch_vccnz .LBB0_292
	s_mov_b32 s0, 0x38e38e39
	v_mul_hi_i32 v165, v238, s0
	v_lshrrev_b32_e32 v167, 31, v165
	v_ashrrev_i32_e32 v165, 9, v165
	v_add_u32_e32 v165, v165, v167
	v_mul_i32_i24_e32 v165, 0x900, v165
	v_sub_u32_e32 v165, v238, v165
	v_add_u32_e32 v167, 0xffffff00, v165
	v_and_b32_e32 v165, 15, v165
	v_ashrrev_i32_e32 v167, 6, v167
	v_cndmask_b32_e64 v165, v165, v167, s[16:17]
	v_cvt_f32_i32_e32 v165, v165
	v_mul_f32_e32 v167, v240, v165
	v_floor_f32_e32 v167, v167
	v_fma_f32 v167, v240, v165, -v167
	v_cos_f32_e32 v190, v167
	v_sin_f32_e32 v192, v167
	v_mul_f32_e32 v167, v241, v165
	v_floor_f32_e32 v167, v167
	v_fma_f32 v167, v241, v165, -v167
	v_cos_f32_e32 v191, v167
	v_sin_f32_e32 v193, v167
	v_mul_f32_e32 v167, v227, v165
	v_floor_f32_e32 v167, v167
	v_fma_f32 v167, v227, v165, -v167
	v_mul_f32_e32 v196, v192, v186
	v_mul_f32_e32 v197, v193, v187
	v_mul_f32_e32 v186, v190, v186
	v_mul_f32_e32 v187, v191, v187
	v_fma_f32 v196, v190, v194, -v196
	v_fma_f32 v197, v191, v195, -v197
	v_fma_f32 v186, v192, v194, v186
	v_fma_f32 v187, v193, v195, v187
	v_cos_f32_e32 v190, v167
	v_sin_f32_e32 v192, v167
	v_mul_f32_e32 v167, v239, v165
	v_floor_f32_e32 v167, v167
	v_fma_f32 v167, v239, v165, -v167
	v_cos_f32_e32 v191, v167
	v_sin_f32_e32 v193, v167
	v_mul_f32_e32 v167, v143, v165
	v_floor_f32_e32 v167, v167
	v_fma_f32 v167, v143, v165, -v167
	v_mul_f32_e32 v194, v192, v182
	v_mul_f32_e32 v195, v193, v183
	v_mul_f32_e32 v182, v190, v182
	v_mul_f32_e32 v183, v191, v183
	v_fma_f32 v194, v190, v188, -v194
	v_fma_f32 v195, v191, v189, -v195
	v_fma_f32 v182, v192, v188, v182
	v_fma_f32 v183, v193, v189, v183
	v_cos_f32_e32 v188, v167
	v_sin_f32_e32 v190, v167
	v_mul_f32_e32 v167, v163, v165
	v_floor_f32_e32 v167, v167
	v_fma_f32 v167, v163, v165, -v167
	v_cos_f32_e32 v189, v167
	v_sin_f32_e32 v191, v167
	v_mul_f32_e32 v167, v131, v165
	v_floor_f32_e32 v167, v167
	v_fma_f32 v167, v131, v165, -v167
	v_mul_f32_e32 v192, v190, v180
	v_mul_f32_e32 v193, v191, v181
	v_mul_f32_e32 v180, v188, v180
	v_mul_f32_e32 v181, v189, v181
	v_fma_f32 v192, v188, v184, -v192
	v_fma_f32 v193, v189, v185, -v193
	v_fma_f32 v180, v190, v184, v180
	v_fma_f32 v181, v191, v185, v181
	v_cos_f32_e32 v184, v167
	v_sin_f32_e32 v188, v167
	v_mul_f32_e32 v167, v137, v165
	v_floor_f32_e32 v167, v167
	v_fma_f32 v165, v137, v165, -v167
	v_sin_f32_e32 v189, v165
	v_cos_f32_e32 v185, v165
	v_mul_f32_e32 v190, v188, v176
	v_mul_f32_e32 v191, v189, v177
	s_nop 0
	v_fma_f32 v190, v184, v178, -v190
	v_fma_f32 v191, v185, v179, -v191
	v_mul_f32_e32 v176, v184, v176
	v_mul_f32_e32 v177, v185, v177
	v_mov_b64_e32 v[184:185], v[192:193]
	v_fma_f32 v176, v188, v178, v176
	v_fma_f32 v177, v189, v179, v177
	v_mov_b64_e32 v[178:179], v[190:191]
	v_mov_b64_e32 v[188:189], v[194:195]
	v_mov_b64_e32 v[194:195], v[196:197]
; DI unsigned pack2(float a, float b) { f2_t v = {a, b}; bf2_t r = __builtin_convertvector(v, bf2_t); return __builtin_bit_cast(unsigned, r); }
; DI float fexp2(float x) { return __builtin_amdgcn_exp2f(x); }
; template <int GP> DI void gemm_phase(const Params& p, int l, int which, char* smem, int wv) {
;     ...
;             if (silu) {
; #pragma unroll
;               for (int e = 0; e < 8; ++e) { x1[e] = x1[e] * __builtin_amdgcn_rcpf(1.f + fexp2(-LOG2E * x1[e])); x2[e] = x2[e] * __builtin_amdgcn_rcpf(1.f + fexp2(-LOG2E * x2[e])); }
;             } else {
; #pragma unroll
;               for (int e = 0; e < 8; ++e) { x1[e] *= qmul; x2[e] *= qmul; }
;             }
;             u16* pp = p.P + (size_t)R * INW + n0 + head * 128;
;             u32x4 o;
;             o[0] = pack2(x1[0], x1[1]); o[1] = pack2(x1[2], x1[3]); o[2] = pack2(x1[4], x1[5]); o[3] = pack2(x1[6], x1[7]);
;             *(u32x4*)(pp + c1) = o;
;             o[0] = pack2(x2[0], x2[1]); o[1] = pack2(x2[2], x2[3]); o[2] = pack2(x2[4], x2[5]); o[3] = pack2(x2[6], x2[7]);
;             *(u32x4*)(pp + c2) = o;
.LBB0_292:
	v_cndmask_b32_e64 v165, 0, 1, s[52:53]
	v_cmp_ne_u32_e64 s[34:35], 1, v165
	s_andn2_b64 vcc, exec, s[52:53]
	s_mov_b64 s[0:1], -1
	s_cbranch_vccnz .LBB0_294
	v_mul_f32_e32 v190, s50, v194
	v_mul_f32_e32 v191, s50, v195
	v_mul_f32_e32 v192, s50, v186
	v_mul_f32_e32 v193, s50, v187
	v_mul_f32_e32 v196, s50, v188
	v_mul_f32_e32 v197, s50, v189
	v_mul_f32_e32 v198, s50, v182
	v_mul_f32_e32 v199, s50, v183
	v_mul_f32_e32 v200, s50, v184
	v_mul_f32_e32 v201, s50, v185
	v_mul_f32_e32 v202, s50, v180
	v_mul_f32_e32 v203, s50, v181
	v_mul_f32_e32 v204, s50, v178
	v_mul_f32_e32 v205, s50, v179
	v_mul_f32_e32 v206, s50, v176
	v_mul_f32_e32 v207, s50, v177
	s_mov_b64 s[0:1], 0
.LBB0_294:
	s_andn2_b64 vcc, exec, s[0:1]
	s_cbranch_vccnz .LBB0_296
	v_mul_f32_e32 v165, 0xbfb8aa3b, v194
	v_exp_f32_e32 v165, v165
	s_nop 0
	v_add_f32_e32 v165, 1.0, v165
	v_rcp_f32_e32 v190, v165
	v_mul_f32_e32 v165, 0xbfb8aa3b, v186
	v_exp_f32_e32 v165, v165
	s_nop 0
	v_add_f32_e32 v165, 1.0, v165
	v_rcp_f32_e32 v192, v165
	v_mul_f32_e32 v165, 0xbfb8aa3b, v195
	v_exp_f32_e32 v165, v165
	s_nop 0
	v_add_f32_e32 v165, 1.0, v165
	v_rcp_f32_e32 v191, v165
	v_mul_f32_e32 v165, 0xbfb8aa3b, v187
	v_exp_f32_e32 v165, v165
	v_mul_f32_e32 v190, v194, v190
	v_mul_f32_e32 v191, v195, v191
	v_add_f32_e32 v165, 1.0, v165
	v_rcp_f32_e32 v193, v165
	v_mul_f32_e32 v165, 0xbfb8aa3b, v188
	v_exp_f32_e32 v165, v165
	v_mul_f32_e32 v192, v186, v192
	v_mul_f32_e32 v193, v187, v193
	v_add_f32_e32 v165, 1.0, v165
	v_rcp_f32_e32 v186, v165
	v_mul_f32_e32 v165, 0xbfb8aa3b, v182
	v_exp_f32_e32 v165, v165
	s_nop 0
	v_add_f32_e32 v165, 1.0, v165
	v_rcp_f32_e32 v194, v165
	v_mul_f32_e32 v165, 0xbfb8aa3b, v189
	v_exp_f32_e32 v165, v165
	s_nop 0
	v_add_f32_e32 v165, 1.0, v165
	v_rcp_f32_e32 v187, v165
	v_mul_f32_e32 v165, 0xbfb8aa3b, v183
	v_exp_f32_e32 v165, v165
	v_mul_f32_e32 v196, v188, v186
	v_mul_f32_e32 v197, v189, v187
	v_add_f32_e32 v165, 1.0, v165
	v_rcp_f32_e32 v195, v165
	v_mul_f32_e32 v165, 0xbfb8aa3b, v184
	v_exp_f32_e32 v165, v165
	v_mul_f32_e32 v198, v182, v194
	v_mul_f32_e32 v199, v183, v195
	v_add_f32_e32 v165, 1.0, v165
	v_rcp_f32_e32 v182, v165
	v_mul_f32_e32 v165, 0xbfb8aa3b, v180
	v_exp_f32_e32 v165, v165
	s_nop 0
	v_add_f32_e32 v165, 1.0, v165
	v_rcp_f32_e32 v186, v165
	v_mul_f32_e32 v165, 0xbfb8aa3b, v185
	v_exp_f32_e32 v165, v165
	s_nop 0
	v_add_f32_e32 v165, 1.0, v165
	v_rcp_f32_e32 v183, v165
	v_mul_f32_e32 v165, 0xbfb8aa3b, v181
	v_exp_f32_e32 v165, v165
	v_mul_f32_e32 v200, v184, v182
	v_mul_f32_e32 v201, v185, v183
	v_add_f32_e32 v165, 1.0, v165
	v_rcp_f32_e32 v187, v165
	v_mul_f32_e32 v165, 0xbfb8aa3b, v178
	v_exp_f32_e32 v165, v165
	v_mul_f32_e32 v202, v180, v186
	v_mul_f32_e32 v203, v181, v187
	v_add_f32_e32 v165, 1.0, v165
	v_rcp_f32_e32 v180, v165
	v_mul_f32_e32 v165, 0xbfb8aa3b, v176
	v_exp_f32_e32 v165, v165
	s_nop 0
	v_add_f32_e32 v165, 1.0, v165
	v_rcp_f32_e32 v182, v165
	v_mul_f32_e32 v165, 0xbfb8aa3b, v179
	v_exp_f32_e32 v165, v165
	s_nop 0
	v_add_f32_e32 v165, 1.0, v165
	v_rcp_f32_e32 v181, v165
	v_mul_f32_e32 v165, 0xbfb8aa3b, v177
	v_exp_f32_e32 v165, v165
	v_mul_f32_e32 v204, v178, v180
	v_mul_f32_e32 v205, v179, v181
	v_add_f32_e32 v165, 1.0, v165
	v_rcp_f32_e32 v183, v165
	s_nop 0
	v_mul_f32_e32 v206, v176, v182
	v_mul_f32_e32 v207, v177, v183
.LBB0_296:
	v_readlane_b32 s0, v253, 21
	v_readlane_b32 s14, v253, 35
	v_readlane_b32 s15, v253, 36
	s_lshl_b32 s44, s24, 8
	v_readlane_b32 s1, v253, 22
	v_mov_b64_e32 v[176:177], s[14:15]
	s_ashr_i32 s45, s44, 31
	v_mad_i64_i32 v[176:177], s[0:1], v238, s85, v[176:177]
	v_lshl_add_u64 v[176:177], s[44:45], 1, v[176:177]
	s_lshl_b32 s18, s92, 1
	v_lshl_add_u64 v[180:181], v[176:177], 0, s[18:19]
	v_cvt_pk_bf16_f32 v176, v190, v191
	v_cvt_pk_bf16_f32 v177, v196, v197
	v_cvt_pk_bf16_f32 v178, v200, v201
	v_cvt_pk_bf16_f32 v179, v204, v205
	v_lshl_add_u64 v[180:181], v[144:145], 1, v[180:181]
	s_lshl_b32 s52, s37, 1
	s_mov_b32 s53, s19
	global_store_dwordx4 v[180:181], v[176:179], off
	v_lshl_add_u64 v[180:181], v[180:181], 0, s[52:53]
	s_and_b64 vcc, exec, s[96:97]
	v_cvt_pk_bf16_f32 v176, v192, v193
	v_cvt_pk_bf16_f32 v177, v198, v199
	v_cvt_pk_bf16_f32 v178, v202, v203
	v_cvt_pk_bf16_f32 v179, v206, v207
	v_readlane_b32 s2, v253, 23
	v_readlane_b32 s3, v253, 24
	v_readlane_b32 s4, v253, 25
	v_readlane_b32 s5, v253, 26
	v_readlane_b32 s6, v253, 27
	v_readlane_b32 s7, v253, 28
	v_readlane_b32 s8, v253, 29
	v_readlane_b32 s9, v253, 30
	v_readlane_b32 s10, v253, 31
	v_readlane_b32 s11, v253, 32
	v_readlane_b32 s12, v253, 33
	v_readlane_b32 s13, v253, 34
	global_store_dwordx4 v[180:181], v[176:179], off
	s_cbranch_vccnz .LBB0_345
	s_nop 0
	v_mul_f32_e32 v176, v54, v174
	v_mul_f32_e32 v177, v55, v174
	v_mul_f32_e32 v178, v22, v174
	v_mul_f32_e32 v179, v23, v174
	v_mul_f32_e32 v198, v176, v146
	v_mul_f32_e32 v199, v177, v147
	v_mul_f32_e32 v176, v56, v174
	v_mul_f32_e32 v177, v57, v174
	v_mul_f32_e32 v186, v178, v148
	v_mul_f32_e32 v187, v179, v149
	v_mul_f32_e32 v178, v24, v174
	v_mul_f32_e32 v179, v25, v174
	v_mul_f32_e32 v190, v176, v150
	v_mul_f32_e32 v191, v177, v151
	v_mul_f32_e32 v176, v50, v174
	v_mul_f32_e32 v177, v51, v174
	v_mul_f32_e32 v180, v178, v152
	v_mul_f32_e32 v181, v179, v153
	v_mul_f32_e32 v178, v18, v174
	v_mul_f32_e32 v179, v19, v174
	v_mul_f32_e32 v182, v176, v154
	v_mul_f32_e32 v183, v177, v155
	v_mul_f32_e32 v176, v52, v174
	v_mul_f32_e32 v177, v53, v174
	v_mul_f32_e32 v175, v21, v174
	v_mul_f32_e32 v174, v20, v174
	v_mul_f32_e32 v178, v178, v156
	v_mul_f32_e32 v179, v179, v157
	v_mul_f32_e32 v176, v176, v158
	v_mul_f32_e32 v177, v177, v159
	v_mul_f32_e32 v174, v174, v160
	v_mul_f32_e32 v175, v175, v161
	s_and_b64 vcc, exec, s[30:31]
	v_or_b32_e32 v165, 16, v238
	s_cbranch_vccnz .LBB0_299
; DI float fexp2(float x) { return __builtin_amdgcn_exp2f(x); }
; template <int GP> DI void gemm_phase(const Params& p, int l, int which, char* smem, int wv) {
;     ...
;             if (rope && !isctx) {
;               const int tt = (R % TPB) - 256;
;               const float pos = (float)(use_col ? (tt & 63) : (tt >> 6));
; #pragma unroll
;               for (int e = 0; e < 8; ++e) {
;                 float rev = pos * frev[e];
;                 rev = rev - floorf(rev);
;                 const float cs = __builtin_amdgcn_cosf(rev), sn = __builtin_amdgcn_sinf(rev);
;                 const float a = x1[e], bq = x2[e];
;                 x1[e] = a * cs - bq * sn; x2[e] = bq * cs + a * sn;
;               }
;             }
;             if (silu) {
; #pragma unroll
;               for (int e = 0; e < 8; ++e) { x1[e] = x1[e] * __builtin_amdgcn_rcpf(1.f + fexp2(-LOG2E * x1[e])); x2[e] = x2[e] * __builtin_amdgcn_rcpf(1.f + fexp2(-LOG2E * x2[e])); }
;             } else {
; #pragma unroll
;               for (int e = 0; e < 8; ++e) { x1[e] *= qmul; x2[e] *= qmul; }
;             }
.LBB0_298:
	s_mov_b32 s0, 0x38e38e39
	v_mul_hi_i32 v167, v165, s0
	v_lshrrev_b32_e32 v169, 31, v167
	v_ashrrev_i32_e32 v167, 9, v167
	v_add_u32_e32 v167, v167, v169
	v_mul_i32_i24_e32 v167, 0x900, v167
	v_sub_u32_e32 v167, v165, v167
	v_add_u32_e32 v169, 0xffffff00, v167
	v_and_b32_e32 v167, 31, v167
	v_ashrrev_i32_e32 v169, 6, v169
	v_cndmask_b32_e64 v167, v167, v169, s[16:17]
	v_cvt_f32_i32_e32 v167, v167
	v_mul_f32_e32 v169, v240, v167
	v_floor_f32_e32 v169, v169
	v_fma_f32 v169, v240, v167, -v169
	v_cos_f32_e32 v184, v169
	v_sin_f32_e32 v188, v169
	v_mul_f32_e32 v169, v241, v167
	v_floor_f32_e32 v169, v169
	v_fma_f32 v169, v241, v167, -v169
	v_sin_f32_e32 v189, v169
	v_cos_f32_e32 v185, v169
	v_mul_f32_e32 v169, v227, v167
	v_floor_f32_e32 v169, v169
	v_mul_f32_e32 v192, v188, v186
	v_mul_f32_e32 v193, v189, v187
	v_fma_f32 v169, v227, v167, -v169
	v_fma_f32 v192, v184, v198, -v192
	v_fma_f32 v193, v185, v199, -v193
	v_mul_f32_e32 v184, v184, v186
	v_mul_f32_e32 v185, v185, v187
	s_nop 0
	v_fma_f32 v186, v188, v198, v184
	v_fma_f32 v187, v189, v199, v185
	v_cos_f32_e32 v184, v169
	v_sin_f32_e32 v188, v169
	v_mul_f32_e32 v169, v239, v167
	v_floor_f32_e32 v169, v169
	v_fma_f32 v169, v239, v167, -v169
	v_cos_f32_e32 v185, v169
	v_sin_f32_e32 v189, v169
	v_mul_f32_e32 v169, v143, v167
	v_floor_f32_e32 v169, v169
	v_fma_f32 v169, v143, v167, -v169
	v_mul_f32_e32 v194, v188, v180
	v_mul_f32_e32 v195, v189, v181
	v_mul_f32_e32 v180, v184, v180
	v_mul_f32_e32 v181, v185, v181
	v_fma_f32 v194, v184, v190, -v194
	v_fma_f32 v195, v185, v191, -v195
	v_fma_f32 v180, v188, v190, v180
	v_fma_f32 v181, v189, v191, v181
	v_cos_f32_e32 v184, v169
	v_sin_f32_e32 v188, v169
	v_mul_f32_e32 v169, v163, v167
	v_floor_f32_e32 v169, v169
	v_fma_f32 v169, v163, v167, -v169
	v_cos_f32_e32 v185, v169
	v_sin_f32_e32 v189, v169
	v_mul_f32_e32 v169, v131, v167
	v_floor_f32_e32 v169, v169
	v_fma_f32 v169, v131, v167, -v169
	v_mul_f32_e32 v190, v188, v178
	v_mul_f32_e32 v191, v189, v179
	v_mul_f32_e32 v178, v184, v178
	v_mul_f32_e32 v179, v185, v179
	v_fma_f32 v190, v184, v182, -v190
	v_fma_f32 v191, v185, v183, -v191
	v_fma_f32 v178, v188, v182, v178
	v_fma_f32 v179, v189, v183, v179
	v_cos_f32_e32 v182, v169
	v_sin_f32_e32 v184, v169
	v_mul_f32_e32 v169, v137, v167
	v_floor_f32_e32 v169, v169
	v_fma_f32 v167, v137, v167, -v169
	v_sin_f32_e32 v185, v167
	v_cos_f32_e32 v183, v167
	v_mov_b64_e32 v[198:199], v[192:193]
	v_mul_f32_e32 v188, v184, v174
	v_mul_f32_e32 v189, v185, v175
	s_nop 0
	v_fma_f32 v188, v182, v176, -v188
	v_fma_f32 v189, v183, v177, -v189
	v_mul_f32_e32 v174, v182, v174
	v_mul_f32_e32 v175, v183, v175
	v_mov_b64_e32 v[182:183], v[190:191]
	v_fma_f32 v174, v184, v176, v174
	v_fma_f32 v175, v185, v177, v175
	v_mov_b64_e32 v[176:177], v[188:189]
	v_mov_b64_e32 v[190:191], v[194:195]
.LBB0_299:
	s_and_b64 vcc, exec, s[34:35]
	s_mov_b64 s[0:1], -1
	s_cbranch_vccnz .LBB0_301
	v_mul_f32_e32 v184, s50, v198
	v_mul_f32_e32 v185, s50, v199
	v_mul_f32_e32 v188, s50, v186
	v_mul_f32_e32 v189, s50, v187
	v_mul_f32_e32 v192, s50, v190
	v_mul_f32_e32 v193, s50, v191
	v_mul_f32_e32 v194, s50, v180
	v_mul_f32_e32 v195, s50, v181
	v_mul_f32_e32 v196, s50, v182
	v_mul_f32_e32 v197, s50, v183
	v_mul_f32_e32 v200, s50, v178
	v_mul_f32_e32 v201, s50, v179
	v_mul_f32_e32 v202, s50, v176
	v_mul_f32_e32 v203, s50, v177
	v_mul_f32_e32 v204, s50, v174
	v_mul_f32_e32 v205, s50, v175
	s_cbranch_execz .LBB0_302
	s_branch .LBB0_303

; DI unsigned pack2(float a, float b) { f2_t v = {a, b}; bf2_t r = __builtin_convertvector(v, bf2_t); return __builtin_bit_cast(unsigned, r); }
; DI float fexp2(float x) { return __builtin_amdgcn_exp2f(x); }
; template <int GP> DI void gemm_phase(const Params& p, int l, int which, char* smem, int wv) {
;     ...
;             if (ng) {
;               const float rinv = rinv8[ai * 4 + m];
; #pragma unroll
;               for (int e = 0; e < 8; ++e) { x1[e] = (x1[e] * rinv) * g1[e]; x2[e] = (x2[e] * rinv) * g2[e]; }
;             }
;     ...
;             if (silu) {
; #pragma unroll
;               for (int e = 0; e < 8; ++e) { x1[e] = x1[e] * __builtin_amdgcn_rcpf(1.f + fexp2(-LOG2E * x1[e])); x2[e] = x2[e] * __builtin_amdgcn_rcpf(1.f + fexp2(-LOG2E * x2[e])); }
;             } else {
; #pragma unroll
;               for (int e = 0; e < 8; ++e) { x1[e] *= qmul; x2[e] *= qmul; }
;             }
;             u16* pp = p.P + (size_t)R * INW + n0 + head * 128;
;             u32x4 o;
;             o[0] = pack2(x1[0], x1[1]); o[1] = pack2(x1[2], x1[3]); o[2] = pack2(x1[4], x1[5]); o[3] = pack2(x1[6], x1[7]);
;             *(u32x4*)(pp + c1) = o;
;             o[0] = pack2(x2[0], x2[1]); o[1] = pack2(x2[2], x2[3]); o[2] = pack2(x2[4], x2[5]); o[3] = pack2(x2[6], x2[7]);
;             *(u32x4*)(pp + c2) = o;
.LBB0_302:
	v_mul_f32_e32 v167, 0xbfb8aa3b, v198
	v_exp_f32_e32 v167, v167
	s_nop 0
	v_add_f32_e32 v167, 1.0, v167
	v_rcp_f32_e32 v184, v167
	v_mul_f32_e32 v167, 0xbfb8aa3b, v186
	v_exp_f32_e32 v167, v167
	s_nop 0
	v_add_f32_e32 v167, 1.0, v167
	v_rcp_f32_e32 v188, v167
	v_mul_f32_e32 v167, 0xbfb8aa3b, v199
	v_exp_f32_e32 v167, v167
	s_nop 0
	v_add_f32_e32 v167, 1.0, v167
	v_rcp_f32_e32 v185, v167
	v_mul_f32_e32 v167, 0xbfb8aa3b, v187
	v_exp_f32_e32 v167, v167
	v_mul_f32_e32 v184, v198, v184
	v_mul_f32_e32 v185, v199, v185
	v_add_f32_e32 v167, 1.0, v167
	v_rcp_f32_e32 v189, v167
	v_mul_f32_e32 v167, 0xbfb8aa3b, v190
	v_exp_f32_e32 v167, v167
	v_mul_f32_e32 v188, v186, v188
	v_mul_f32_e32 v189, v187, v189
	v_add_f32_e32 v167, 1.0, v167
	v_rcp_f32_e32 v186, v167
	v_mul_f32_e32 v167, 0xbfb8aa3b, v180
	v_exp_f32_e32 v167, v167
	s_nop 0
	v_add_f32_e32 v167, 1.0, v167
	v_rcp_f32_e32 v194, v167
	v_mul_f32_e32 v167, 0xbfb8aa3b, v191
	v_exp_f32_e32 v167, v167
	s_nop 0
	v_add_f32_e32 v167, 1.0, v167
	v_rcp_f32_e32 v187, v167
	v_mul_f32_e32 v167, 0xbfb8aa3b, v181
	v_exp_f32_e32 v167, v167
	v_mul_f32_e32 v192, v190, v186
	v_mul_f32_e32 v193, v191, v187
	v_add_f32_e32 v167, 1.0, v167
	v_rcp_f32_e32 v195, v167
	v_mul_f32_e32 v167, 0xbfb8aa3b, v182
	v_exp_f32_e32 v167, v167
	v_mul_f32_e32 v194, v180, v194
	v_mul_f32_e32 v195, v181, v195
	v_add_f32_e32 v167, 1.0, v167
	v_rcp_f32_e32 v180, v167
	v_mul_f32_e32 v167, 0xbfb8aa3b, v178
	v_exp_f32_e32 v167, v167
	s_nop 0
	v_add_f32_e32 v167, 1.0, v167
	v_rcp_f32_e32 v186, v167
	v_mul_f32_e32 v167, 0xbfb8aa3b, v183
	v_exp_f32_e32 v167, v167
	s_nop 0
	v_add_f32_e32 v167, 1.0, v167
	v_rcp_f32_e32 v181, v167
	v_mul_f32_e32 v167, 0xbfb8aa3b, v179
	v_exp_f32_e32 v167, v167
	v_mul_f32_e32 v196, v182, v180
	v_mul_f32_e32 v197, v183, v181
	v_add_f32_e32 v167, 1.0, v167
	v_rcp_f32_e32 v187, v167
	v_mul_f32_e32 v167, 0xbfb8aa3b, v176
	v_exp_f32_e32 v167, v167
	v_mul_f32_e32 v200, v178, v186
	v_mul_f32_e32 v201, v179, v187
	v_add_f32_e32 v167, 1.0, v167
	v_rcp_f32_e32 v178, v167
	v_mul_f32_e32 v167, 0xbfb8aa3b, v174
	v_exp_f32_e32 v167, v167
	s_nop 0
	v_add_f32_e32 v167, 1.0, v167
	v_rcp_f32_e32 v180, v167
	v_mul_f32_e32 v167, 0xbfb8aa3b, v177
	v_exp_f32_e32 v167, v167
	s_nop 0
	v_add_f32_e32 v167, 1.0, v167
	v_rcp_f32_e32 v179, v167
	v_mul_f32_e32 v167, 0xbfb8aa3b, v175
	v_exp_f32_e32 v167, v167
	v_mul_f32_e32 v202, v176, v178
	v_mul_f32_e32 v203, v177, v179
	v_add_f32_e32 v167, 1.0, v167
	v_rcp_f32_e32 v181, v167
	s_nop 0
	v_mul_f32_e32 v204, v174, v180
	v_mul_f32_e32 v205, v175, v181
.LBB0_303:
	v_readlane_b32 s0, v253, 21
	v_readlane_b32 s14, v253, 35
	v_readlane_b32 s15, v253, 36
	v_readlane_b32 s1, v253, 22
	v_cvt_pk_bf16_f32 v176, v196, v197
	v_mov_b64_e32 v[174:175], s[14:15]
	v_mad_i64_i32 v[174:175], s[0:1], v165, s85, v[174:175]
	v_lshl_add_u64 v[174:175], s[44:45], 1, v[174:175]
	v_lshl_add_u64 v[178:179], v[174:175], 0, s[18:19]
	v_cvt_pk_bf16_f32 v174, v184, v185
	v_cvt_pk_bf16_f32 v175, v192, v193
	v_cvt_pk_bf16_f32 v177, v202, v203
	v_lshl_add_u64 v[178:179], v[144:145], 1, v[178:179]
	s_mov_b32 s53, s19
	global_store_dwordx4 v[178:179], v[174:177], off
	v_lshl_add_u64 v[178:179], v[178:179], 0, s[52:53]
	s_and_b64 vcc, exec, s[96:97]
	v_cvt_pk_bf16_f32 v174, v188, v189
	v_cvt_pk_bf16_f32 v175, v194, v195
	v_cvt_pk_bf16_f32 v176, v200, v201
	v_cvt_pk_bf16_f32 v177, v204, v205
	v_readlane_b32 s2, v253, 23
	v_readlane_b32 s3, v253, 24
	v_readlane_b32 s4, v253, 25
	v_readlane_b32 s5, v253, 26
	v_readlane_b32 s6, v253, 27
	v_readlane_b32 s7, v253, 28
	v_readlane_b32 s8, v253, 29
	v_readlane_b32 s9, v253, 30
	v_readlane_b32 s10, v253, 31
	v_readlane_b32 s11, v253, 32
	v_readlane_b32 s12, v253, 33
	v_readlane_b32 s13, v253, 34
	global_store_dwordx4 v[178:179], v[174:177], off
	s_cbranch_vccnz .LBB0_346
	s_nop 0
	v_mul_f32_e32 v174, v46, v172
	v_mul_f32_e32 v175, v47, v172
	v_mul_f32_e32 v176, v14, v172
	v_mul_f32_e32 v177, v15, v172
	v_mul_f32_e32 v196, v174, v146
	v_mul_f32_e32 v197, v175, v147
	v_mul_f32_e32 v174, v48, v172
	v_mul_f32_e32 v175, v49, v172
	v_mul_f32_e32 v184, v176, v148
	v_mul_f32_e32 v185, v177, v149
	v_mul_f32_e32 v176, v16, v172
	v_mul_f32_e32 v177, v17, v172
	v_mul_f32_e32 v188, v174, v150
	v_mul_f32_e32 v189, v175, v151
	v_mul_f32_e32 v174, v42, v172
	v_mul_f32_e32 v175, v43, v172
	v_mul_f32_e32 v178, v176, v152
	v_mul_f32_e32 v179, v177, v153
	v_mul_f32_e32 v176, v10, v172
	v_mul_f32_e32 v177, v11, v172
	v_mul_f32_e32 v180, v174, v154
	v_mul_f32_e32 v181, v175, v155
	v_mul_f32_e32 v174, v44, v172
	v_mul_f32_e32 v175, v45, v172
	v_mul_f32_e32 v173, v13, v172
	v_mul_f32_e32 v172, v12, v172
	v_mul_f32_e32 v176, v176, v156
	v_mul_f32_e32 v177, v177, v157
	v_mul_f32_e32 v174, v174, v158
	v_mul_f32_e32 v175, v175, v159
	v_mul_f32_e32 v172, v172, v160
	v_mul_f32_e32 v173, v173, v161
	s_and_b64 vcc, exec, s[30:31]
	v_or_b32_e32 v165, 32, v238
	s_cbranch_vccnz .LBB0_306
; DI float fexp2(float x) { return __builtin_amdgcn_exp2f(x); }
; template <int GP> DI void gemm_phase(const Params& p, int l, int which, char* smem, int wv) {
;     ...
;             if (rope && !isctx) {
;               const int tt = (R % TPB) - 256;
;               const float pos = (float)(use_col ? (tt & 63) : (tt >> 6));
; #pragma unroll
;               for (int e = 0; e < 8; ++e) {
;                 float rev = pos * frev[e];
;                 rev = rev - floorf(rev);
;                 const float cs = __builtin_amdgcn_cosf(rev), sn = __builtin_amdgcn_sinf(rev);
;                 const float a = x1[e], bq = x2[e];
;                 x1[e] = a * cs - bq * sn; x2[e] = bq * cs + a * sn;
;               }
;             }
;             if (silu) {
; #pragma unroll
;               for (int e = 0; e < 8; ++e) { x1[e] = x1[e] * __builtin_amdgcn_rcpf(1.f + fexp2(-LOG2E * x1[e])); x2[e] = x2[e] * __builtin_amdgcn_rcpf(1.f + fexp2(-LOG2E * x2[e])); }
;             } else {
; #pragma unroll
;               for (int e = 0; e < 8; ++e) { x1[e] *= qmul; x2[e] *= qmul; }
;             }
.LBB0_305:
	s_mov_b32 s0, 0x38e38e39
	v_mul_hi_i32 v167, v165, s0
	v_lshrrev_b32_e32 v169, 31, v167
	v_ashrrev_i32_e32 v167, 9, v167
	v_add_u32_e32 v167, v167, v169
	v_mul_i32_i24_e32 v167, 0x900, v167
	v_sub_u32_e32 v167, v165, v167
	v_add_u32_e32 v169, 0xffffff00, v167
	v_and_b32_e32 v167, 47, v167
	v_ashrrev_i32_e32 v169, 6, v169
	v_cndmask_b32_e64 v167, v167, v169, s[16:17]
	v_cvt_f32_i32_e32 v167, v167
	v_mul_f32_e32 v169, v240, v167
	v_floor_f32_e32 v169, v169
	v_fma_f32 v169, v240, v167, -v169
	v_cos_f32_e32 v182, v169
	v_sin_f32_e32 v186, v169
	v_mul_f32_e32 v169, v241, v167
	v_floor_f32_e32 v169, v169
	v_fma_f32 v169, v241, v167, -v169
	v_sin_f32_e32 v187, v169
	v_cos_f32_e32 v183, v169
	v_mul_f32_e32 v169, v227, v167
	v_floor_f32_e32 v169, v169
	v_mul_f32_e32 v190, v186, v184
	v_mul_f32_e32 v191, v187, v185
	v_fma_f32 v169, v227, v167, -v169
	v_fma_f32 v190, v182, v196, -v190
	v_fma_f32 v191, v183, v197, -v191
	v_mul_f32_e32 v182, v182, v184
	v_mul_f32_e32 v183, v183, v185
	s_nop 0
	v_fma_f32 v184, v186, v196, v182
	v_fma_f32 v185, v187, v197, v183
	v_cos_f32_e32 v182, v169
	v_sin_f32_e32 v186, v169
	v_mul_f32_e32 v169, v239, v167
	v_floor_f32_e32 v169, v169
	v_fma_f32 v169, v239, v167, -v169
	v_cos_f32_e32 v183, v169
	v_sin_f32_e32 v187, v169
	v_mul_f32_e32 v169, v143, v167
	v_floor_f32_e32 v169, v169
	v_fma_f32 v169, v143, v167, -v169
	v_mul_f32_e32 v192, v186, v178
	v_mul_f32_e32 v193, v187, v179
	v_mul_f32_e32 v178, v182, v178
	v_mul_f32_e32 v179, v183, v179
	v_fma_f32 v192, v182, v188, -v192
	v_fma_f32 v193, v183, v189, -v193
	v_fma_f32 v178, v186, v188, v178
	v_fma_f32 v179, v187, v189, v179
	v_cos_f32_e32 v182, v169
	v_sin_f32_e32 v186, v169
	v_mul_f32_e32 v169, v163, v167
	v_floor_f32_e32 v169, v169
	v_fma_f32 v169, v163, v167, -v169
	v_cos_f32_e32 v183, v169
	v_sin_f32_e32 v187, v169
	v_mul_f32_e32 v169, v131, v167
	v_floor_f32_e32 v169, v169
	v_fma_f32 v169, v131, v167, -v169
	v_mul_f32_e32 v188, v186, v176
	v_mul_f32_e32 v189, v187, v177
	v_mul_f32_e32 v176, v182, v176
	v_mul_f32_e32 v177, v183, v177
	v_fma_f32 v188, v182, v180, -v188
	v_fma_f32 v189, v183, v181, -v189
	v_fma_f32 v176, v186, v180, v176
	v_fma_f32 v177, v187, v181, v177
	v_cos_f32_e32 v180, v169
	v_sin_f32_e32 v182, v169
	v_mul_f32_e32 v169, v137, v167
	v_floor_f32_e32 v169, v169
	v_fma_f32 v167, v137, v167, -v169
	v_sin_f32_e32 v183, v167
	v_cos_f32_e32 v181, v167
	v_mov_b64_e32 v[196:197], v[190:191]
	v_mul_f32_e32 v186, v182, v172
	v_mul_f32_e32 v187, v183, v173
	s_nop 0
	v_fma_f32 v186, v180, v174, -v186
	v_fma_f32 v187, v181, v175, -v187
	v_mul_f32_e32 v172, v180, v172
	v_mul_f32_e32 v173, v181, v173
	v_mov_b64_e32 v[180:181], v[188:189]
	v_fma_f32 v172, v182, v174, v172
	v_fma_f32 v173, v183, v175, v173
	v_mov_b64_e32 v[174:175], v[186:187]
	v_mov_b64_e32 v[188:189], v[192:193]
.LBB0_306:
	s_and_b64 vcc, exec, s[34:35]
	s_mov_b64 s[0:1], -1
	s_cbranch_vccnz .LBB0_308
	v_mul_f32_e32 v182, s50, v196
	v_mul_f32_e32 v183, s50, v197
	v_mul_f32_e32 v186, s50, v184
	v_mul_f32_e32 v187, s50, v185
	v_mul_f32_e32 v190, s50, v188
	v_mul_f32_e32 v191, s50, v189
	v_mul_f32_e32 v192, s50, v178
	v_mul_f32_e32 v193, s50, v179
	v_mul_f32_e32 v194, s50, v180
	v_mul_f32_e32 v195, s50, v181
	v_mul_f32_e32 v198, s50, v176
	v_mul_f32_e32 v199, s50, v177
	v_mul_f32_e32 v200, s50, v174
	v_mul_f32_e32 v201, s50, v175
	v_mul_f32_e32 v202, s50, v172
	v_mul_f32_e32 v203, s50, v173
	s_cbranch_execz .LBB0_309
	s_branch .LBB0_310

; DI unsigned pack2(float a, float b) { f2_t v = {a, b}; bf2_t r = __builtin_convertvector(v, bf2_t); return __builtin_bit_cast(unsigned, r); }
; DI float fexp2(float x) { return __builtin_amdgcn_exp2f(x); }
; template <int GP> DI void gemm_phase(const Params& p, int l, int which, char* smem, int wv) {
;     ...
;             if (ng) {
;               const float rinv = rinv8[ai * 4 + m];
; #pragma unroll
;               for (int e = 0; e < 8; ++e) { x1[e] = (x1[e] * rinv) * g1[e]; x2[e] = (x2[e] * rinv) * g2[e]; }
;             }
;     ...
;             if (silu) {
; #pragma unroll
;               for (int e = 0; e < 8; ++e) { x1[e] = x1[e] * __builtin_amdgcn_rcpf(1.f + fexp2(-LOG2E * x1[e])); x2[e] = x2[e] * __builtin_amdgcn_rcpf(1.f + fexp2(-LOG2E * x2[e])); }
;             } else {
; #pragma unroll
;               for (int e = 0; e < 8; ++e) { x1[e] *= qmul; x2[e] *= qmul; }
;             }
;             u16* pp = p.P + (size_t)R * INW + n0 + head * 128;
;             u32x4 o;
;             o[0] = pack2(x1[0], x1[1]); o[1] = pack2(x1[2], x1[3]); o[2] = pack2(x1[4], x1[5]); o[3] = pack2(x1[6], x1[7]);
;             *(u32x4*)(pp + c1) = o;
;             o[0] = pack2(x2[0], x2[1]); o[1] = pack2(x2[2], x2[3]); o[2] = pack2(x2[4], x2[5]); o[3] = pack2(x2[6], x2[7]);
;             *(u32x4*)(pp + c2) = o;
.LBB0_309:
	v_mul_f32_e32 v167, 0xbfb8aa3b, v196
	v_exp_f32_e32 v167, v167
	s_nop 0
	v_add_f32_e32 v167, 1.0, v167
	v_rcp_f32_e32 v182, v167
	v_mul_f32_e32 v167, 0xbfb8aa3b, v184
	v_exp_f32_e32 v167, v167
	s_nop 0
	v_add_f32_e32 v167, 1.0, v167
	v_rcp_f32_e32 v186, v167
	v_mul_f32_e32 v167, 0xbfb8aa3b, v197
	v_exp_f32_e32 v167, v167
	s_nop 0
	v_add_f32_e32 v167, 1.0, v167
	v_rcp_f32_e32 v183, v167
	v_mul_f32_e32 v167, 0xbfb8aa3b, v185
	v_exp_f32_e32 v167, v167
	v_mul_f32_e32 v182, v196, v182
	v_mul_f32_e32 v183, v197, v183
	v_add_f32_e32 v167, 1.0, v167
	v_rcp_f32_e32 v187, v167
	v_mul_f32_e32 v167, 0xbfb8aa3b, v188
	v_exp_f32_e32 v167, v167
	v_mul_f32_e32 v186, v184, v186
	v_mul_f32_e32 v187, v185, v187
	v_add_f32_e32 v167, 1.0, v167
	v_rcp_f32_e32 v184, v167
	v_mul_f32_e32 v167, 0xbfb8aa3b, v178
	v_exp_f32_e32 v167, v167
	s_nop 0
	v_add_f32_e32 v167, 1.0, v167
	v_rcp_f32_e32 v192, v167
	v_mul_f32_e32 v167, 0xbfb8aa3b, v189
	v_exp_f32_e32 v167, v167
	s_nop 0
	v_add_f32_e32 v167, 1.0, v167
	v_rcp_f32_e32 v185, v167
	v_mul_f32_e32 v167, 0xbfb8aa3b, v179
	v_exp_f32_e32 v167, v167
	v_mul_f32_e32 v190, v188, v184
	v_mul_f32_e32 v191, v189, v185
	v_add_f32_e32 v167, 1.0, v167
	v_rcp_f32_e32 v193, v167
	v_mul_f32_e32 v167, 0xbfb8aa3b, v180
	v_exp_f32_e32 v167, v167
	v_mul_f32_e32 v192, v178, v192
	v_mul_f32_e32 v193, v179, v193
	v_add_f32_e32 v167, 1.0, v167
	v_rcp_f32_e32 v178, v167
	v_mul_f32_e32 v167, 0xbfb8aa3b, v176
	v_exp_f32_e32 v167, v167
	s_nop 0
	v_add_f32_e32 v167, 1.0, v167
	v_rcp_f32_e32 v184, v167
	v_mul_f32_e32 v167, 0xbfb8aa3b, v181
	v_exp_f32_e32 v167, v167
	s_nop 0
	v_add_f32_e32 v167, 1.0, v167
	v_rcp_f32_e32 v179, v167
	v_mul_f32_e32 v167, 0xbfb8aa3b, v177
	v_exp_f32_e32 v167, v167
	v_mul_f32_e32 v194, v180, v178
	v_mul_f32_e32 v195, v181, v179
	v_add_f32_e32 v167, 1.0, v167
	v_rcp_f32_e32 v185, v167
	v_mul_f32_e32 v167, 0xbfb8aa3b, v174
	v_exp_f32_e32 v167, v167
	v_mul_f32_e32 v198, v176, v184
	v_mul_f32_e32 v199, v177, v185
	v_add_f32_e32 v167, 1.0, v167
	v_rcp_f32_e32 v176, v167
	v_mul_f32_e32 v167, 0xbfb8aa3b, v172
	v_exp_f32_e32 v167, v167
	s_nop 0
	v_add_f32_e32 v167, 1.0, v167
	v_rcp_f32_e32 v178, v167
	v_mul_f32_e32 v167, 0xbfb8aa3b, v175
	v_exp_f32_e32 v167, v167
	s_nop 0
	v_add_f32_e32 v167, 1.0, v167
	v_rcp_f32_e32 v177, v167
	v_mul_f32_e32 v167, 0xbfb8aa3b, v173
	v_exp_f32_e32 v167, v167
	v_mul_f32_e32 v200, v174, v176
	v_mul_f32_e32 v201, v175, v177
	v_add_f32_e32 v167, 1.0, v167
	v_rcp_f32_e32 v179, v167
	s_nop 0
	v_mul_f32_e32 v202, v172, v178
	v_mul_f32_e32 v203, v173, v179
.LBB0_310:
	v_readlane_b32 s0, v253, 21
	v_readlane_b32 s14, v253, 35
	v_readlane_b32 s15, v253, 36
	v_readlane_b32 s1, v253, 22
	v_cvt_pk_bf16_f32 v174, v194, v195
	v_mov_b64_e32 v[172:173], s[14:15]
	v_mad_i64_i32 v[172:173], s[0:1], v165, s85, v[172:173]
	v_lshl_add_u64 v[172:173], s[44:45], 1, v[172:173]
	v_lshl_add_u64 v[176:177], v[172:173], 0, s[18:19]
	v_cvt_pk_bf16_f32 v172, v182, v183
	v_cvt_pk_bf16_f32 v173, v190, v191
	v_cvt_pk_bf16_f32 v175, v200, v201
	v_lshl_add_u64 v[176:177], v[144:145], 1, v[176:177]
	s_mov_b32 s53, s19
	global_store_dwordx4 v[176:177], v[172:175], off
	v_lshl_add_u64 v[176:177], v[176:177], 0, s[52:53]
	s_and_b64 vcc, exec, s[96:97]
	v_cvt_pk_bf16_f32 v172, v186, v187
	v_cvt_pk_bf16_f32 v173, v192, v193
	v_cvt_pk_bf16_f32 v174, v198, v199
	v_cvt_pk_bf16_f32 v175, v202, v203
	v_readlane_b32 s2, v253, 23
	v_readlane_b32 s3, v253, 24
	v_readlane_b32 s4, v253, 25
	v_readlane_b32 s5, v253, 26
	v_readlane_b32 s6, v253, 27
	v_readlane_b32 s7, v253, 28
	v_readlane_b32 s8, v253, 29
	v_readlane_b32 s9, v253, 30
	v_readlane_b32 s10, v253, 31
	v_readlane_b32 s11, v253, 32
	v_readlane_b32 s12, v253, 33
	v_readlane_b32 s13, v253, 34
	global_store_dwordx4 v[176:177], v[172:175], off
	s_cbranch_vccnz .LBB0_347
	s_nop 0
	v_mul_f32_e32 v172, v38, v170
	v_mul_f32_e32 v173, v39, v170
	v_mul_f32_e32 v174, v6, v170
	v_mul_f32_e32 v175, v7, v170
	v_mul_f32_e32 v194, v172, v146
	v_mul_f32_e32 v195, v173, v147
	v_mul_f32_e32 v172, v40, v170
	v_mul_f32_e32 v173, v41, v170
	v_mul_f32_e32 v182, v174, v148
	v_mul_f32_e32 v183, v175, v149
	v_mul_f32_e32 v174, v8, v170
	v_mul_f32_e32 v175, v9, v170
	v_mul_f32_e32 v186, v172, v150
	v_mul_f32_e32 v187, v173, v151
	v_mul_f32_e32 v172, v34, v170
	v_mul_f32_e32 v173, v35, v170
	v_mul_f32_e32 v176, v174, v152
	v_mul_f32_e32 v177, v175, v153
	v_mul_f32_e32 v174, v2, v170
	v_mul_f32_e32 v175, v3, v170
	v_mul_f32_e32 v178, v172, v154
	v_mul_f32_e32 v179, v173, v155
	v_mul_f32_e32 v172, v36, v170
	v_mul_f32_e32 v173, v37, v170
	v_mul_f32_e32 v171, v5, v170
	v_mul_f32_e32 v170, v4, v170
	v_mul_f32_e32 v174, v174, v156
	v_mul_f32_e32 v175, v175, v157
	v_mul_f32_e32 v172, v172, v158
	v_mul_f32_e32 v173, v173, v159
	v_mul_f32_e32 v170, v170, v160
	v_mul_f32_e32 v171, v171, v161
	s_and_b64 vcc, exec, s[30:31]
	v_or_b32_e32 v165, 48, v238
	s_cbranch_vccnz .LBB0_313
; DI float fexp2(float x) { return __builtin_amdgcn_exp2f(x); }
; template <int GP> DI void gemm_phase(const Params& p, int l, int which, char* smem, int wv) {
;     ...
;             if (rope && !isctx) {
;               const int tt = (R % TPB) - 256;
;               const float pos = (float)(use_col ? (tt & 63) : (tt >> 6));
; #pragma unroll
;               for (int e = 0; e < 8; ++e) {
;                 float rev = pos * frev[e];
;                 rev = rev - floorf(rev);
;                 const float cs = __builtin_amdgcn_cosf(rev), sn = __builtin_amdgcn_sinf(rev);
;                 const float a = x1[e], bq = x2[e];
;                 x1[e] = a * cs - bq * sn; x2[e] = bq * cs + a * sn;
;               }
;             }
;             if (silu) {
; #pragma unroll
;               for (int e = 0; e < 8; ++e) { x1[e] = x1[e] * __builtin_amdgcn_rcpf(1.f + fexp2(-LOG2E * x1[e])); x2[e] = x2[e] * __builtin_amdgcn_rcpf(1.f + fexp2(-LOG2E * x2[e])); }
;             } else {
; #pragma unroll
;               for (int e = 0; e < 8; ++e) { x1[e] *= qmul; x2[e] *= qmul; }
;             }
.LBB0_312:
	s_mov_b32 s0, 0x38e38e39
	v_mul_hi_i32 v167, v165, s0
	v_lshrrev_b32_e32 v169, 31, v167
	v_ashrrev_i32_e32 v167, 9, v167
	v_add_u32_e32 v167, v167, v169
	v_mul_i32_i24_e32 v167, 0x900, v167
	v_sub_u32_e32 v167, v165, v167
	v_add_u32_e32 v169, 0xffffff00, v167
	v_and_b32_e32 v167, 63, v167
	v_ashrrev_i32_e32 v169, 6, v169
	v_cndmask_b32_e64 v167, v167, v169, s[16:17]
	v_cvt_f32_i32_e32 v167, v167
	v_mul_f32_e32 v169, v240, v167
	v_floor_f32_e32 v169, v169
	v_fma_f32 v169, v240, v167, -v169
	v_cos_f32_e32 v180, v169
	v_sin_f32_e32 v184, v169
	v_mul_f32_e32 v169, v241, v167
	v_floor_f32_e32 v169, v169
	v_fma_f32 v169, v241, v167, -v169
	v_sin_f32_e32 v185, v169
	v_cos_f32_e32 v181, v169
	v_mul_f32_e32 v169, v227, v167
	v_floor_f32_e32 v169, v169
	v_mul_f32_e32 v188, v184, v182
	v_mul_f32_e32 v189, v185, v183
	v_fma_f32 v169, v227, v167, -v169
	v_fma_f32 v188, v180, v194, -v188
	v_fma_f32 v189, v181, v195, -v189
	v_mul_f32_e32 v180, v180, v182
	v_mul_f32_e32 v181, v181, v183
	s_nop 0
	v_fma_f32 v182, v184, v194, v180
	v_fma_f32 v183, v185, v195, v181
	v_cos_f32_e32 v180, v169
	v_sin_f32_e32 v184, v169
	v_mul_f32_e32 v169, v239, v167
	v_floor_f32_e32 v169, v169
	v_fma_f32 v169, v239, v167, -v169
	v_cos_f32_e32 v181, v169
	v_sin_f32_e32 v185, v169
	v_mul_f32_e32 v169, v143, v167
	v_floor_f32_e32 v169, v169
	v_fma_f32 v169, v143, v167, -v169
	v_mul_f32_e32 v190, v184, v176
	v_mul_f32_e32 v191, v185, v177
	v_mul_f32_e32 v176, v180, v176
	v_mul_f32_e32 v177, v181, v177
	v_fma_f32 v190, v180, v186, -v190
	v_fma_f32 v191, v181, v187, -v191
	v_fma_f32 v176, v184, v186, v176
	v_fma_f32 v177, v185, v187, v177
	v_cos_f32_e32 v180, v169
	v_sin_f32_e32 v184, v169
	v_mul_f32_e32 v169, v163, v167
	v_floor_f32_e32 v169, v169
	v_fma_f32 v169, v163, v167, -v169
	v_cos_f32_e32 v181, v169
	v_sin_f32_e32 v185, v169
	v_mul_f32_e32 v169, v131, v167
	v_floor_f32_e32 v169, v169
	v_fma_f32 v169, v131, v167, -v169
	v_mul_f32_e32 v186, v184, v174
	v_mul_f32_e32 v187, v185, v175
	v_mul_f32_e32 v174, v180, v174
	v_mul_f32_e32 v175, v181, v175
	v_fma_f32 v186, v180, v178, -v186
	v_fma_f32 v187, v181, v179, -v187
	v_fma_f32 v174, v184, v178, v174
	v_fma_f32 v175, v185, v179, v175
	v_cos_f32_e32 v178, v169
	v_sin_f32_e32 v180, v169
	v_mul_f32_e32 v169, v137, v167
	v_floor_f32_e32 v169, v169
	v_fma_f32 v167, v137, v167, -v169
	v_sin_f32_e32 v181, v167
	v_cos_f32_e32 v179, v167
	v_mov_b64_e32 v[194:195], v[188:189]
	v_mul_f32_e32 v184, v180, v170
	v_mul_f32_e32 v185, v181, v171
	s_nop 0
	v_fma_f32 v184, v178, v172, -v184
	v_fma_f32 v185, v179, v173, -v185
	v_mul_f32_e32 v170, v178, v170
	v_mul_f32_e32 v171, v179, v171
	v_mov_b64_e32 v[178:179], v[186:187]
	v_fma_f32 v170, v180, v172, v170
	v_fma_f32 v171, v181, v173, v171
	v_mov_b64_e32 v[172:173], v[184:185]
	v_mov_b64_e32 v[186:187], v[190:191]
.LBB0_313:
	s_and_b64 vcc, exec, s[34:35]
	s_mov_b64 s[0:1], -1
	s_cbranch_vccnz .LBB0_315
	v_mul_f32_e32 v180, s50, v194
	v_mul_f32_e32 v181, s50, v195
	v_mul_f32_e32 v184, s50, v182
	v_mul_f32_e32 v185, s50, v183
	v_mul_f32_e32 v188, s50, v186
	v_mul_f32_e32 v189, s50, v187
	v_mul_f32_e32 v190, s50, v176
	v_mul_f32_e32 v191, s50, v177
	v_mul_f32_e32 v192, s50, v178
	v_mul_f32_e32 v193, s50, v179
	v_mul_f32_e32 v196, s50, v174
	v_mul_f32_e32 v197, s50, v175
	v_mul_f32_e32 v198, s50, v172
	v_mul_f32_e32 v199, s50, v173
	v_mul_f32_e32 v200, s50, v170
	v_mul_f32_e32 v201, s50, v171
	s_cbranch_execz .LBB0_316
	s_branch .LBB0_317

; DI unsigned pack2(float a, float b) { f2_t v = {a, b}; bf2_t r = __builtin_convertvector(v, bf2_t); return __builtin_bit_cast(unsigned, r); }
; DI float fexp2(float x) { return __builtin_amdgcn_exp2f(x); }
; template <int GP> DI void gemm_phase(const Params& p, int l, int which, char* smem, int wv) {
;     ...
;             if (ng) {
;               const float rinv = rinv8[ai * 4 + m];
; #pragma unroll
;               for (int e = 0; e < 8; ++e) { x1[e] = (x1[e] * rinv) * g1[e]; x2[e] = (x2[e] * rinv) * g2[e]; }
;             }
;     ...
;             if (silu) {
; #pragma unroll
;               for (int e = 0; e < 8; ++e) { x1[e] = x1[e] * __builtin_amdgcn_rcpf(1.f + fexp2(-LOG2E * x1[e])); x2[e] = x2[e] * __builtin_amdgcn_rcpf(1.f + fexp2(-LOG2E * x2[e])); }
;             } else {
; #pragma unroll
;               for (int e = 0; e < 8; ++e) { x1[e] *= qmul; x2[e] *= qmul; }
;             }
;             u16* pp = p.P + (size_t)R * INW + n0 + head * 128;
;             u32x4 o;
;             o[0] = pack2(x1[0], x1[1]); o[1] = pack2(x1[2], x1[3]); o[2] = pack2(x1[4], x1[5]); o[3] = pack2(x1[6], x1[7]);
;             *(u32x4*)(pp + c1) = o;
;             o[0] = pack2(x2[0], x2[1]); o[1] = pack2(x2[2], x2[3]); o[2] = pack2(x2[4], x2[5]); o[3] = pack2(x2[6], x2[7]);
;             *(u32x4*)(pp + c2) = o;
.LBB0_316:
	v_mul_f32_e32 v167, 0xbfb8aa3b, v194
	v_exp_f32_e32 v167, v167
	s_nop 0
	v_add_f32_e32 v167, 1.0, v167
	v_rcp_f32_e32 v180, v167
	v_mul_f32_e32 v167, 0xbfb8aa3b, v182
	v_exp_f32_e32 v167, v167
	s_nop 0
	v_add_f32_e32 v167, 1.0, v167
	v_rcp_f32_e32 v184, v167
	v_mul_f32_e32 v167, 0xbfb8aa3b, v195
	v_exp_f32_e32 v167, v167
	s_nop 0
	v_add_f32_e32 v167, 1.0, v167
	v_rcp_f32_e32 v181, v167
	v_mul_f32_e32 v167, 0xbfb8aa3b, v183
	v_exp_f32_e32 v167, v167
	v_mul_f32_e32 v180, v194, v180
	v_mul_f32_e32 v181, v195, v181
	v_add_f32_e32 v167, 1.0, v167
	v_rcp_f32_e32 v185, v167
	v_mul_f32_e32 v167, 0xbfb8aa3b, v186
	v_exp_f32_e32 v167, v167
	v_mul_f32_e32 v184, v182, v184
	v_mul_f32_e32 v185, v183, v185
	v_add_f32_e32 v167, 1.0, v167
	v_rcp_f32_e32 v182, v167
	v_mul_f32_e32 v167, 0xbfb8aa3b, v176
	v_exp_f32_e32 v167, v167
	s_nop 0
	v_add_f32_e32 v167, 1.0, v167
	v_rcp_f32_e32 v190, v167
	v_mul_f32_e32 v167, 0xbfb8aa3b, v187
	v_exp_f32_e32 v167, v167
	s_nop 0
	v_add_f32_e32 v167, 1.0, v167
	v_rcp_f32_e32 v183, v167
	v_mul_f32_e32 v167, 0xbfb8aa3b, v177
	v_exp_f32_e32 v167, v167
	v_mul_f32_e32 v188, v186, v182
	v_mul_f32_e32 v189, v187, v183
	v_add_f32_e32 v167, 1.0, v167
	v_rcp_f32_e32 v191, v167
	v_mul_f32_e32 v167, 0xbfb8aa3b, v178
	v_exp_f32_e32 v167, v167
	v_mul_f32_e32 v190, v176, v190
	v_mul_f32_e32 v191, v177, v191
	v_add_f32_e32 v167, 1.0, v167
	v_rcp_f32_e32 v176, v167
	v_mul_f32_e32 v167, 0xbfb8aa3b, v174
	v_exp_f32_e32 v167, v167
	s_nop 0
	v_add_f32_e32 v167, 1.0, v167
	v_rcp_f32_e32 v182, v167
	v_mul_f32_e32 v167, 0xbfb8aa3b, v179
	v_exp_f32_e32 v167, v167
	s_nop 0
	v_add_f32_e32 v167, 1.0, v167
	v_rcp_f32_e32 v177, v167
	v_mul_f32_e32 v167, 0xbfb8aa3b, v175
	v_exp_f32_e32 v167, v167
	v_mul_f32_e32 v192, v178, v176
	v_mul_f32_e32 v193, v179, v177
	v_add_f32_e32 v167, 1.0, v167
	v_rcp_f32_e32 v183, v167
	v_mul_f32_e32 v167, 0xbfb8aa3b, v172
	v_exp_f32_e32 v167, v167
	v_mul_f32_e32 v196, v174, v182
	v_mul_f32_e32 v197, v175, v183
	v_add_f32_e32 v167, 1.0, v167
	v_rcp_f32_e32 v174, v167
	v_mul_f32_e32 v167, 0xbfb8aa3b, v170
	v_exp_f32_e32 v167, v167
	s_nop 0
	v_add_f32_e32 v167, 1.0, v167
	v_rcp_f32_e32 v176, v167
	v_mul_f32_e32 v167, 0xbfb8aa3b, v173
	v_exp_f32_e32 v167, v167
	s_nop 0
	v_add_f32_e32 v167, 1.0, v167
	v_rcp_f32_e32 v175, v167
	v_mul_f32_e32 v167, 0xbfb8aa3b, v171
	v_exp_f32_e32 v167, v167
	v_mul_f32_e32 v198, v172, v174
	v_mul_f32_e32 v199, v173, v175
	v_add_f32_e32 v167, 1.0, v167
	v_rcp_f32_e32 v177, v167
	s_nop 0
	v_mul_f32_e32 v200, v170, v176
	v_mul_f32_e32 v201, v171, v177
.LBB0_317:
	v_readlane_b32 s0, v253, 21
	v_readlane_b32 s14, v253, 35
	v_readlane_b32 s15, v253, 36
	v_readlane_b32 s1, v253, 22
	v_cvt_pk_bf16_f32 v172, v192, v193
	v_mov_b64_e32 v[170:171], s[14:15]
	v_mad_i64_i32 v[170:171], s[0:1], v165, s85, v[170:171]
	v_lshl_add_u64 v[170:171], s[44:45], 1, v[170:171]
	v_lshl_add_u64 v[174:175], v[170:171], 0, s[18:19]
	v_cvt_pk_bf16_f32 v170, v180, v181
	v_cvt_pk_bf16_f32 v171, v188, v189
	v_cvt_pk_bf16_f32 v173, v198, v199
	v_lshl_add_u64 v[174:175], v[144:145], 1, v[174:175]
	s_mov_b32 s53, s19
	global_store_dwordx4 v[174:175], v[170:173], off
	v_lshl_add_u64 v[174:175], v[174:175], 0, s[52:53]
	s_and_b64 vcc, exec, s[96:97]
	v_cvt_pk_bf16_f32 v170, v184, v185
	v_cvt_pk_bf16_f32 v171, v190, v191
	v_cvt_pk_bf16_f32 v172, v196, v197
	v_cvt_pk_bf16_f32 v173, v200, v201
	v_readlane_b32 s2, v253, 23
	v_readlane_b32 s3, v253, 24
	v_readlane_b32 s4, v253, 25
	v_readlane_b32 s5, v253, 26
	v_readlane_b32 s6, v253, 27
	v_readlane_b32 s7, v253, 28
	v_readlane_b32 s8, v253, 29
	v_readlane_b32 s9, v253, 30
	v_readlane_b32 s10, v253, 31
	v_readlane_b32 s11, v253, 32
	v_readlane_b32 s12, v253, 33
	v_readlane_b32 s13, v253, 34
	global_store_dwordx4 v[174:175], v[170:173], off
	s_cbranch_vccnz .LBB0_348
	s_nop 0
	v_mul_f32_e32 v170, v66, v168
	v_mul_f32_e32 v171, v67, v168
	v_mul_f32_e32 v172, v98, v168
	v_mul_f32_e32 v173, v99, v168
	v_mul_f32_e32 v192, v170, v146
	v_mul_f32_e32 v193, v171, v147
	v_mul_f32_e32 v170, v68, v168
	v_mul_f32_e32 v171, v69, v168
	v_mul_f32_e32 v180, v172, v148
	v_mul_f32_e32 v181, v173, v149
	v_mul_f32_e32 v172, v100, v168
	v_mul_f32_e32 v173, v101, v168
	v_mul_f32_e32 v184, v170, v150
	v_mul_f32_e32 v185, v171, v151
	v_mul_f32_e32 v170, v70, v168
	v_mul_f32_e32 v171, v71, v168
	v_mul_f32_e32 v174, v172, v152
	v_mul_f32_e32 v175, v173, v153
	v_mul_f32_e32 v172, v102, v168
	v_mul_f32_e32 v173, v103, v168
	v_mul_f32_e32 v176, v170, v154
	v_mul_f32_e32 v177, v171, v155
	v_mul_f32_e32 v170, v72, v168
	v_mul_f32_e32 v171, v73, v168
	v_mul_f32_e32 v169, v105, v168
	v_mul_f32_e32 v168, v104, v168
	v_mul_f32_e32 v172, v172, v156
	v_mul_f32_e32 v173, v173, v157
	v_mul_f32_e32 v170, v170, v158
	v_mul_f32_e32 v171, v171, v159
	v_mul_f32_e32 v168, v168, v160
	v_mul_f32_e32 v169, v169, v161
	s_and_b64 vcc, exec, s[30:31]
	v_add_u32_e32 v165, 0x80, v238
	s_cbranch_vccnz .LBB0_320
; DI float fexp2(float x) { return __builtin_amdgcn_exp2f(x); }
; template <int GP> DI void gemm_phase(const Params& p, int l, int which, char* smem, int wv) {
;     ...
;             if (rope && !isctx) {
;               const int tt = (R % TPB) - 256;
;               const float pos = (float)(use_col ? (tt & 63) : (tt >> 6));
; #pragma unroll
;               for (int e = 0; e < 8; ++e) {
;                 float rev = pos * frev[e];
;                 rev = rev - floorf(rev);
;                 const float cs = __builtin_amdgcn_cosf(rev), sn = __builtin_amdgcn_sinf(rev);
;                 const float a = x1[e], bq = x2[e];
;                 x1[e] = a * cs - bq * sn; x2[e] = bq * cs + a * sn;
;               }
;             }
;             if (silu) {
; #pragma unroll
;               for (int e = 0; e < 8; ++e) { x1[e] = x1[e] * __builtin_amdgcn_rcpf(1.f + fexp2(-LOG2E * x1[e])); x2[e] = x2[e] * __builtin_amdgcn_rcpf(1.f + fexp2(-LOG2E * x2[e])); }
;             } else {
; #pragma unroll
;               for (int e = 0; e < 8; ++e) { x1[e] *= qmul; x2[e] *= qmul; }
.LBB0_319:
	s_mov_b32 s0, 0x38e38e39
	v_mul_hi_i32 v167, v165, s0
	v_lshrrev_b32_e32 v178, 31, v167
	v_ashrrev_i32_e32 v167, 9, v167
	v_add_u32_e32 v167, v167, v178
	v_mul_i32_i24_e32 v167, 0x900, v167
	v_sub_u32_e32 v167, v165, v167
	v_add_u32_e32 v178, 0xffffff00, v167
	v_and_b32_e32 v167, 15, v167
	v_ashrrev_i32_e32 v178, 6, v178
	v_cndmask_b32_e64 v167, v167, v178, s[16:17]
	v_cvt_f32_i32_e32 v167, v167
	v_mul_f32_e32 v178, v240, v167
	v_floor_f32_e32 v178, v178
	v_fma_f32 v179, v240, v167, -v178
	v_cos_f32_e32 v178, v179
	v_sin_f32_e32 v182, v179
	v_mul_f32_e32 v179, v241, v167
	v_floor_f32_e32 v179, v179
	v_fma_f32 v183, v241, v167, -v179
	v_cos_f32_e32 v179, v183
	v_sin_f32_e32 v183, v183
	s_nop 0
	v_mul_f32_e32 v186, v182, v180
	v_mul_f32_e32 v187, v183, v181
	s_nop 0
	v_fma_f32 v186, v178, v192, -v186
	v_fma_f32 v187, v179, v193, -v187
	v_mul_f32_e32 v178, v178, v180
	v_mul_f32_e32 v179, v179, v181
	s_nop 0
	v_fma_f32 v180, v182, v192, v178
	v_fma_f32 v181, v183, v193, v179
	v_mul_f32_e32 v178, v227, v167
	v_floor_f32_e32 v178, v178
	v_fma_f32 v179, v227, v167, -v178
	v_cos_f32_e32 v178, v179
	v_sin_f32_e32 v182, v179
	v_mul_f32_e32 v179, v239, v167
	v_floor_f32_e32 v179, v179
	v_fma_f32 v183, v239, v167, -v179
	v_cos_f32_e32 v179, v183
	v_sin_f32_e32 v183, v183
	v_mov_b64_e32 v[192:193], v[186:187]
	v_mul_f32_e32 v188, v182, v174
	v_mul_f32_e32 v189, v183, v175
	s_nop 0
	v_fma_f32 v188, v178, v184, -v188
	v_fma_f32 v189, v179, v185, -v189
	v_mul_f32_e32 v174, v178, v174
	v_mul_f32_e32 v175, v179, v175
	v_mul_f32_e32 v178, v143, v167
	v_floor_f32_e32 v178, v178
	v_fma_f32 v179, v143, v167, -v178
	v_fma_f32 v174, v182, v184, v174
	v_fma_f32 v175, v183, v185, v175
	v_cos_f32_e32 v178, v179
	v_sin_f32_e32 v182, v179
	v_mul_f32_e32 v179, v163, v167
	v_floor_f32_e32 v179, v179
	v_fma_f32 v183, v163, v167, -v179
	v_cos_f32_e32 v179, v183
	v_sin_f32_e32 v183, v183
	s_nop 0
	v_mul_f32_e32 v184, v182, v172
	v_mul_f32_e32 v185, v183, v173
	v_mul_f32_e32 v172, v178, v172
	v_mul_f32_e32 v173, v179, v173
	v_fma_f32 v184, v178, v176, -v184
	v_fma_f32 v185, v179, v177, -v185
	v_fma_f32 v172, v182, v176, v172
	v_fma_f32 v173, v183, v177, v173
	v_mul_f32_e32 v176, v131, v167
	v_floor_f32_e32 v176, v176
	v_fma_f32 v177, v131, v167, -v176
	v_cos_f32_e32 v176, v177
	v_sin_f32_e32 v178, v177
	v_mul_f32_e32 v177, v137, v167
	v_floor_f32_e32 v177, v177
	v_fma_f32 v167, v137, v167, -v177
	v_sin_f32_e32 v179, v167
	v_cos_f32_e32 v177, v167
	v_mul_f32_e32 v182, v178, v168
	v_mul_f32_e32 v183, v179, v169
	s_nop 0
	v_fma_f32 v182, v176, v170, -v182
	v_fma_f32 v183, v177, v171, -v183
	v_mul_f32_e32 v168, v176, v168
	v_mul_f32_e32 v169, v177, v169
	v_mov_b64_e32 v[176:177], v[184:185]
	v_fma_f32 v168, v178, v170, v168
	v_fma_f32 v169, v179, v171, v169
	v_mov_b64_e32 v[170:171], v[182:183]
	v_mov_b64_e32 v[184:185], v[188:189]
.LBB0_320:
	s_and_b64 vcc, exec, s[34:35]
	s_mov_b64 s[0:1], -1
	s_cbranch_vccnz .LBB0_322
	v_mul_f32_e32 v178, s50, v192
	v_mul_f32_e32 v179, s50, v193
	v_mul_f32_e32 v182, s50, v180
	v_mul_f32_e32 v183, s50, v181
	v_mul_f32_e32 v186, s50, v184
	v_mul_f32_e32 v187, s50, v185
	v_mul_f32_e32 v188, s50, v174
	v_mul_f32_e32 v189, s50, v175
	v_mul_f32_e32 v190, s50, v176
	v_mul_f32_e32 v191, s50, v177
	v_mul_f32_e32 v194, s50, v172
	v_mul_f32_e32 v195, s50, v173
	v_mul_f32_e32 v196, s50, v170
	v_mul_f32_e32 v197, s50, v171
	v_mul_f32_e32 v198, s50, v168
	v_mul_f32_e32 v199, s50, v169
	s_cbranch_execz .LBB0_323
	s_branch .LBB0_324

; DI unsigned pack2(float a, float b) { f2_t v = {a, b}; bf2_t r = __builtin_convertvector(v, bf2_t); return __builtin_bit_cast(unsigned, r); }
; DI float fexp2(float x) { return __builtin_amdgcn_exp2f(x); }
; template <int GP> DI void gemm_phase(const Params& p, int l, int which, char* smem, int wv) {
;     ...
;             float x1[8], x2[8];
; #pragma unroll
;             for (int n = 0; n < 2; ++n)
; #pragma unroll
;               for (int j = 0; j < 4; ++j) { x1[n * 4 + j] = acc[ai][0][m][n][j]; x2[n * 4 + j] = acc[ai][1][m][n][j]; }
;             if (ng) {
;               const float rinv = rinv8[ai * 4 + m];
; #pragma unroll
;               for (int e = 0; e < 8; ++e) { x1[e] = (x1[e] * rinv) * g1[e]; x2[e] = (x2[e] * rinv) * g2[e]; }
;     ...
;             if (silu) {
; #pragma unroll
;               for (int e = 0; e < 8; ++e) { x1[e] = x1[e] * __builtin_amdgcn_rcpf(1.f + fexp2(-LOG2E * x1[e])); x2[e] = x2[e] * __builtin_amdgcn_rcpf(1.f + fexp2(-LOG2E * x2[e])); }
;             } else {
; #pragma unroll
;               for (int e = 0; e < 8; ++e) { x1[e] *= qmul; x2[e] *= qmul; }
;             }
;             u16* pp = p.P + (size_t)R * INW + n0 + head * 128;
;             u32x4 o;
;             o[0] = pack2(x1[0], x1[1]); o[1] = pack2(x1[2], x1[3]); o[2] = pack2(x1[4], x1[5]); o[3] = pack2(x1[6], x1[7]);
;             *(u32x4*)(pp + c1) = o;
;             o[0] = pack2(x2[0], x2[1]); o[1] = pack2(x2[2], x2[3]); o[2] = pack2(x2[4], x2[5]); o[3] = pack2(x2[6], x2[7]);
;             *(u32x4*)(pp + c2) = o;
.LBB0_323:
	v_mul_f32_e32 v167, 0xbfb8aa3b, v192
	v_exp_f32_e32 v167, v167
	s_nop 0
	v_add_f32_e32 v167, 1.0, v167
	v_rcp_f32_e32 v178, v167
	v_mul_f32_e32 v167, 0xbfb8aa3b, v180
	v_exp_f32_e32 v167, v167
	s_nop 0
	v_add_f32_e32 v167, 1.0, v167
	v_rcp_f32_e32 v182, v167
	v_mul_f32_e32 v167, 0xbfb8aa3b, v193
	v_exp_f32_e32 v167, v167
	s_nop 0
	v_add_f32_e32 v167, 1.0, v167
	v_rcp_f32_e32 v179, v167
	v_mul_f32_e32 v167, 0xbfb8aa3b, v181
	v_exp_f32_e32 v167, v167
	v_mul_f32_e32 v178, v192, v178
	v_mul_f32_e32 v179, v193, v179
	v_add_f32_e32 v167, 1.0, v167
	v_rcp_f32_e32 v183, v167
	v_mul_f32_e32 v167, 0xbfb8aa3b, v184
	v_exp_f32_e32 v167, v167
	v_mul_f32_e32 v182, v180, v182
	v_mul_f32_e32 v183, v181, v183
	v_add_f32_e32 v167, 1.0, v167
	v_rcp_f32_e32 v180, v167
	v_mul_f32_e32 v167, 0xbfb8aa3b, v174
	v_exp_f32_e32 v167, v167
	s_nop 0
	v_add_f32_e32 v167, 1.0, v167
	v_rcp_f32_e32 v188, v167
	v_mul_f32_e32 v167, 0xbfb8aa3b, v185
	v_exp_f32_e32 v167, v167
	s_nop 0
	v_add_f32_e32 v167, 1.0, v167
	v_rcp_f32_e32 v181, v167
	v_mul_f32_e32 v167, 0xbfb8aa3b, v175
	v_exp_f32_e32 v167, v167
	v_mul_f32_e32 v186, v184, v180
	v_mul_f32_e32 v187, v185, v181
	v_add_f32_e32 v167, 1.0, v167
	v_rcp_f32_e32 v189, v167
	v_mul_f32_e32 v167, 0xbfb8aa3b, v176
	v_exp_f32_e32 v167, v167
	v_mul_f32_e32 v188, v174, v188
	v_mul_f32_e32 v189, v175, v189
	v_add_f32_e32 v167, 1.0, v167
	v_rcp_f32_e32 v174, v167
	v_mul_f32_e32 v167, 0xbfb8aa3b, v172
	v_exp_f32_e32 v167, v167
	s_nop 0
	v_add_f32_e32 v167, 1.0, v167
	v_rcp_f32_e32 v180, v167
	v_mul_f32_e32 v167, 0xbfb8aa3b, v177
	v_exp_f32_e32 v167, v167
	s_nop 0
	v_add_f32_e32 v167, 1.0, v167
	v_rcp_f32_e32 v175, v167
	v_mul_f32_e32 v167, 0xbfb8aa3b, v173
	v_exp_f32_e32 v167, v167
	v_mul_f32_e32 v190, v176, v174
	v_mul_f32_e32 v191, v177, v175
	v_add_f32_e32 v167, 1.0, v167
	v_rcp_f32_e32 v181, v167
	v_mul_f32_e32 v167, 0xbfb8aa3b, v170
	v_exp_f32_e32 v167, v167
	v_mul_f32_e32 v194, v172, v180
	v_mul_f32_e32 v195, v173, v181
	v_add_f32_e32 v167, 1.0, v167
	v_rcp_f32_e32 v172, v167
	v_mul_f32_e32 v167, 0xbfb8aa3b, v168
	v_exp_f32_e32 v167, v167
	s_nop 0
	v_add_f32_e32 v167, 1.0, v167
	v_rcp_f32_e32 v174, v167
	v_mul_f32_e32 v167, 0xbfb8aa3b, v171
	v_exp_f32_e32 v167, v167
	s_nop 0
	v_add_f32_e32 v167, 1.0, v167
	v_rcp_f32_e32 v173, v167
	v_mul_f32_e32 v167, 0xbfb8aa3b, v169
	v_exp_f32_e32 v167, v167
	v_mul_f32_e32 v196, v170, v172
	v_mul_f32_e32 v197, v171, v173
	v_add_f32_e32 v167, 1.0, v167
	v_rcp_f32_e32 v175, v167
	s_nop 0
	v_mul_f32_e32 v198, v168, v174
	v_mul_f32_e32 v199, v169, v175
.LBB0_324:
	v_readlane_b32 s0, v253, 21
	v_readlane_b32 s14, v253, 35
	v_readlane_b32 s15, v253, 36
	v_readlane_b32 s1, v253, 22
	v_cvt_pk_bf16_f32 v170, v190, v191
	v_mov_b64_e32 v[168:169], s[14:15]
	v_mad_i64_i32 v[168:169], s[0:1], v165, s85, v[168:169]
	v_lshl_add_u64 v[168:169], s[44:45], 1, v[168:169]
	v_lshl_add_u64 v[172:173], v[168:169], 0, s[18:19]
	v_cvt_pk_bf16_f32 v168, v178, v179
	v_cvt_pk_bf16_f32 v169, v186, v187
	v_cvt_pk_bf16_f32 v171, v196, v197
	v_lshl_add_u64 v[172:173], v[144:145], 1, v[172:173]
	s_mov_b32 s53, s19
	global_store_dwordx4 v[172:173], v[168:171], off
	v_lshl_add_u64 v[172:173], v[172:173], 0, s[52:53]
	s_and_b64 vcc, exec, s[96:97]
	v_cvt_pk_bf16_f32 v168, v182, v183
	v_cvt_pk_bf16_f32 v169, v188, v189
	v_cvt_pk_bf16_f32 v170, v194, v195
	v_cvt_pk_bf16_f32 v171, v198, v199
	v_readlane_b32 s2, v253, 23
	v_readlane_b32 s3, v253, 24
	v_readlane_b32 s4, v253, 25
	v_readlane_b32 s5, v253, 26
	v_readlane_b32 s6, v253, 27
	v_readlane_b32 s7, v253, 28
	v_readlane_b32 s8, v253, 29
	v_readlane_b32 s9, v253, 30
	v_readlane_b32 s10, v253, 31
	v_readlane_b32 s11, v253, 32
	v_readlane_b32 s12, v253, 33
	v_readlane_b32 s13, v253, 34
	global_store_dwordx4 v[172:173], v[168:171], off
	s_cbranch_vccnz .LBB0_349
	s_nop 0
	v_mul_f32_e32 v168, v74, v166
	v_mul_f32_e32 v169, v75, v166
	v_mul_f32_e32 v170, v106, v166
	v_mul_f32_e32 v171, v107, v166
	v_mul_f32_e32 v190, v168, v146
	v_mul_f32_e32 v191, v169, v147
	v_mul_f32_e32 v168, v76, v166
	v_mul_f32_e32 v169, v77, v166
	v_mul_f32_e32 v178, v170, v148
	v_mul_f32_e32 v179, v171, v149
	v_mul_f32_e32 v170, v108, v166
	v_mul_f32_e32 v171, v109, v166
	v_mul_f32_e32 v182, v168, v150
	v_mul_f32_e32 v183, v169, v151
	v_mul_f32_e32 v168, v78, v166
	v_mul_f32_e32 v169, v79, v166
	v_mul_f32_e32 v172, v170, v152
	v_mul_f32_e32 v173, v171, v153
	v_mul_f32_e32 v170, v110, v166
	v_mul_f32_e32 v171, v111, v166
	v_mul_f32_e32 v174, v168, v154
	v_mul_f32_e32 v175, v169, v155
	v_mul_f32_e32 v168, v80, v166
	v_mul_f32_e32 v169, v81, v166
	v_mul_f32_e32 v167, v113, v166
	v_mul_f32_e32 v166, v112, v166
	v_mul_f32_e32 v170, v170, v156
	v_mul_f32_e32 v171, v171, v157
	v_mul_f32_e32 v168, v168, v158
	v_mul_f32_e32 v169, v169, v159
	v_mul_f32_e32 v166, v166, v160
	v_mul_f32_e32 v167, v167, v161
	s_and_b64 vcc, exec, s[30:31]
	v_add_u32_e32 v165, 0x90, v238
	s_cbranch_vccnz .LBB0_327
; DI float fexp2(float x) { return __builtin_amdgcn_exp2f(x); }
; template <int GP> DI void gemm_phase(const Params& p, int l, int which, char* smem, int wv) {
;     ...
;             if (rope && !isctx) {
;               const int tt = (R % TPB) - 256;
;               const float pos = (float)(use_col ? (tt & 63) : (tt >> 6));
; #pragma unroll
;               for (int e = 0; e < 8; ++e) {
;                 float rev = pos * frev[e];
;                 rev = rev - floorf(rev);
;                 const float cs = __builtin_amdgcn_cosf(rev), sn = __builtin_amdgcn_sinf(rev);
;                 const float a = x1[e], bq = x2[e];
;                 x1[e] = a * cs - bq * sn; x2[e] = bq * cs + a * sn;
;               }
;             }
;             if (silu) {
; #pragma unroll
;               for (int e = 0; e < 8; ++e) { x1[e] = x1[e] * __builtin_amdgcn_rcpf(1.f + fexp2(-LOG2E * x1[e])); x2[e] = x2[e] * __builtin_amdgcn_rcpf(1.f + fexp2(-LOG2E * x2[e])); }
;             } else {
; #pragma unroll
;               for (int e = 0; e < 8; ++e) { x1[e] *= qmul; x2[e] *= qmul; }
.LBB0_326:
	s_mov_b32 s0, 0x38e38e39
	v_mul_hi_i32 v176, v165, s0
	v_lshrrev_b32_e32 v177, 31, v176
	v_ashrrev_i32_e32 v176, 9, v176
	v_add_u32_e32 v176, v176, v177
	v_mul_i32_i24_e32 v176, 0x900, v176
	v_sub_u32_e32 v176, v165, v176
	v_add_u32_e32 v177, 0xffffff00, v176
	v_and_b32_e32 v176, 31, v176
	v_ashrrev_i32_e32 v177, 6, v177
	v_cndmask_b32_e64 v176, v176, v177, s[16:17]
	v_cvt_f32_i32_e32 v188, v176
	v_mul_f32_e32 v176, v240, v188
	v_floor_f32_e32 v176, v176
	v_fma_f32 v177, v240, v188, -v176
	v_cos_f32_e32 v176, v177
	v_sin_f32_e32 v180, v177
	v_mul_f32_e32 v177, v241, v188
	v_floor_f32_e32 v177, v177
	v_fma_f32 v181, v241, v188, -v177
	v_cos_f32_e32 v177, v181
	v_sin_f32_e32 v181, v181
	s_nop 0
	v_mul_f32_e32 v184, v180, v178
	v_mul_f32_e32 v185, v181, v179
	s_nop 0
	v_fma_f32 v184, v176, v190, -v184
	v_fma_f32 v185, v177, v191, -v185
	v_mul_f32_e32 v176, v176, v178
	v_mul_f32_e32 v177, v177, v179
	s_nop 0
	v_fma_f32 v178, v180, v190, v176
	v_fma_f32 v179, v181, v191, v177
	v_mul_f32_e32 v176, v227, v188
	v_floor_f32_e32 v176, v176
	v_fma_f32 v177, v227, v188, -v176
	v_cos_f32_e32 v176, v177
	v_sin_f32_e32 v180, v177
	v_mul_f32_e32 v177, v239, v188
	v_floor_f32_e32 v177, v177
	v_fma_f32 v181, v239, v188, -v177
	v_cos_f32_e32 v177, v181
	v_sin_f32_e32 v181, v181
	v_mov_b64_e32 v[190:191], v[184:185]
	v_mul_f32_e32 v186, v180, v172
	v_mul_f32_e32 v187, v181, v173
	s_nop 0
	v_fma_f32 v186, v176, v182, -v186
	v_fma_f32 v187, v177, v183, -v187
	v_mul_f32_e32 v172, v176, v172
	v_mul_f32_e32 v173, v177, v173
	v_mul_f32_e32 v176, v143, v188
	v_floor_f32_e32 v176, v176
	v_fma_f32 v177, v143, v188, -v176
	v_fma_f32 v172, v180, v182, v172
	v_fma_f32 v173, v181, v183, v173
	v_cos_f32_e32 v176, v177
	v_sin_f32_e32 v180, v177
	v_mul_f32_e32 v177, v163, v188
	v_floor_f32_e32 v177, v177
	v_fma_f32 v181, v163, v188, -v177
	v_cos_f32_e32 v177, v181
	v_sin_f32_e32 v181, v181
	s_nop 0
	v_mul_f32_e32 v182, v180, v170
	v_mul_f32_e32 v183, v181, v171
	v_mul_f32_e32 v170, v176, v170
	v_mul_f32_e32 v171, v177, v171
	v_fma_f32 v182, v176, v174, -v182
	v_fma_f32 v183, v177, v175, -v183
	v_fma_f32 v170, v180, v174, v170
	v_fma_f32 v171, v181, v175, v171
	v_mul_f32_e32 v174, v131, v188
	v_floor_f32_e32 v174, v174
	v_fma_f32 v175, v131, v188, -v174
	v_cos_f32_e32 v174, v175
	v_sin_f32_e32 v176, v175
	v_mul_f32_e32 v175, v137, v188
	v_floor_f32_e32 v175, v175
	v_fma_f32 v177, v137, v188, -v175
	v_cos_f32_e32 v175, v177
	v_sin_f32_e32 v177, v177
	s_nop 0
	v_mul_f32_e32 v180, v176, v166
	v_mul_f32_e32 v181, v177, v167
	s_nop 0
	v_fma_f32 v180, v174, v168, -v180
	v_fma_f32 v181, v175, v169, -v181
	v_mul_f32_e32 v166, v174, v166
	v_mul_f32_e32 v167, v175, v167
	v_mov_b64_e32 v[174:175], v[182:183]
	v_fma_f32 v166, v176, v168, v166
	v_fma_f32 v167, v177, v169, v167
	v_mov_b64_e32 v[168:169], v[180:181]
	v_mov_b64_e32 v[182:183], v[186:187]
.LBB0_327:
	s_and_b64 vcc, exec, s[34:35]
	s_mov_b64 s[0:1], -1
	s_cbranch_vccnz .LBB0_329
	v_mul_f32_e32 v176, s50, v190
	v_mul_f32_e32 v177, s50, v191
	v_mul_f32_e32 v180, s50, v178
	v_mul_f32_e32 v181, s50, v179
	v_mul_f32_e32 v184, s50, v182
	v_mul_f32_e32 v185, s50, v183
	v_mul_f32_e32 v186, s50, v172
	v_mul_f32_e32 v187, s50, v173
	v_mul_f32_e32 v188, s50, v174
	v_mul_f32_e32 v189, s50, v175
	v_mul_f32_e32 v192, s50, v170
	v_mul_f32_e32 v193, s50, v171
	v_mul_f32_e32 v194, s50, v168
	v_mul_f32_e32 v195, s50, v169
	v_mul_f32_e32 v196, s50, v166
	v_mul_f32_e32 v197, s50, v167
	s_cbranch_execz .LBB0_330
	s_branch .LBB0_331

; DI unsigned pack2(float a, float b) { f2_t v = {a, b}; bf2_t r = __builtin_convertvector(v, bf2_t); return __builtin_bit_cast(unsigned, r); }
; DI float fexp2(float x) { return __builtin_amdgcn_exp2f(x); }
; template <int GP> DI void gemm_phase(const Params& p, int l, int which, char* smem, int wv) {
;     ...
;             float x1[8], x2[8];
; #pragma unroll
;             for (int n = 0; n < 2; ++n)
; #pragma unroll
;               for (int j = 0; j < 4; ++j) { x1[n * 4 + j] = acc[ai][0][m][n][j]; x2[n * 4 + j] = acc[ai][1][m][n][j]; }
;             if (ng) {
;               const float rinv = rinv8[ai * 4 + m];
; #pragma unroll
;               for (int e = 0; e < 8; ++e) { x1[e] = (x1[e] * rinv) * g1[e]; x2[e] = (x2[e] * rinv) * g2[e]; }
;     ...
;             if (silu) {
; #pragma unroll
;               for (int e = 0; e < 8; ++e) { x1[e] = x1[e] * __builtin_amdgcn_rcpf(1.f + fexp2(-LOG2E * x1[e])); x2[e] = x2[e] * __builtin_amdgcn_rcpf(1.f + fexp2(-LOG2E * x2[e])); }
;             } else {
; #pragma unroll
;               for (int e = 0; e < 8; ++e) { x1[e] *= qmul; x2[e] *= qmul; }
;             }
;             u16* pp = p.P + (size_t)R * INW + n0 + head * 128;
;             u32x4 o;
;             o[0] = pack2(x1[0], x1[1]); o[1] = pack2(x1[2], x1[3]); o[2] = pack2(x1[4], x1[5]); o[3] = pack2(x1[6], x1[7]);
;             *(u32x4*)(pp + c1) = o;
;             o[0] = pack2(x2[0], x2[1]); o[1] = pack2(x2[2], x2[3]); o[2] = pack2(x2[4], x2[5]); o[3] = pack2(x2[6], x2[7]);
;             *(u32x4*)(pp + c2) = o;
.LBB0_330:
	v_mul_f32_e32 v177, 0xbfb8aa3b, v178
	v_mul_f32_e32 v181, 0xbfb8aa3b, v179
	v_exp_f32_e32 v177, v177
	v_exp_f32_e32 v181, v181
	v_mul_f32_e32 v176, 0xbfb8aa3b, v190
	v_exp_f32_e32 v176, v176
	v_add_f32_e32 v177, 1.0, v177
	v_add_f32_e32 v181, 1.0, v181
	v_rcp_f32_e32 v180, v177
	v_rcp_f32_e32 v181, v181
	v_mul_f32_e32 v177, 0xbfb8aa3b, v191
	v_exp_f32_e32 v177, v177
	v_add_f32_e32 v176, 1.0, v176
	v_mul_f32_e32 v180, v178, v180
	v_mul_f32_e32 v181, v179, v181
	v_mul_f32_e32 v179, 0xbfb8aa3b, v172
	v_exp_f32_e32 v179, v179
	v_mul_f32_e32 v178, 0xbfb8aa3b, v182
	v_exp_f32_e32 v178, v178
	v_add_f32_e32 v177, 1.0, v177
	v_add_f32_e32 v179, 1.0, v179
	v_rcp_f32_e32 v186, v179
	v_mul_f32_e32 v179, 0xbfb8aa3b, v183
	v_exp_f32_e32 v179, v179
	v_add_f32_e32 v178, 1.0, v178
	v_rcp_f32_e32 v178, v178
	v_rcp_f32_e32 v176, v176
	v_add_f32_e32 v179, 1.0, v179
	v_rcp_f32_e32 v179, v179
	v_rcp_f32_e32 v177, v177
	v_mul_f32_e32 v184, v182, v178
	v_mul_f32_e32 v185, v183, v179
	v_mul_f32_e32 v178, 0xbfb8aa3b, v173
	v_exp_f32_e32 v178, v178
	v_mul_f32_e32 v176, v190, v176
	v_mul_f32_e32 v177, v191, v177
	v_add_f32_e32 v178, 1.0, v178
	v_rcp_f32_e32 v187, v178
	s_nop 0
	v_mul_f32_e32 v186, v172, v186
	v_mul_f32_e32 v187, v173, v187
	v_mul_f32_e32 v173, 0xbfb8aa3b, v170
	v_exp_f32_e32 v173, v173
	v_mul_f32_e32 v172, 0xbfb8aa3b, v174
	v_exp_f32_e32 v172, v172
	v_add_f32_e32 v173, 1.0, v173
	v_rcp_f32_e32 v178, v173
	v_mul_f32_e32 v173, 0xbfb8aa3b, v175
	v_exp_f32_e32 v173, v173
	v_add_f32_e32 v172, 1.0, v172
	v_rcp_f32_e32 v172, v172
	v_add_f32_e32 v173, 1.0, v173
	v_rcp_f32_e32 v173, v173
	s_nop 0
	v_mul_f32_e32 v188, v174, v172
	v_mul_f32_e32 v189, v175, v173
	v_mul_f32_e32 v172, 0xbfb8aa3b, v171
	v_exp_f32_e32 v172, v172
	s_nop 0
	v_add_f32_e32 v172, 1.0, v172
	v_rcp_f32_e32 v179, v172
	s_nop 0
	v_mul_f32_e32 v192, v170, v178
	v_mul_f32_e32 v193, v171, v179
	v_mul_f32_e32 v171, 0xbfb8aa3b, v166
	v_exp_f32_e32 v171, v171
	v_mul_f32_e32 v170, 0xbfb8aa3b, v168
	v_exp_f32_e32 v170, v170
	v_add_f32_e32 v171, 1.0, v171
	v_rcp_f32_e32 v172, v171
	v_mul_f32_e32 v171, 0xbfb8aa3b, v169
	v_exp_f32_e32 v171, v171
	v_add_f32_e32 v170, 1.0, v170
	v_rcp_f32_e32 v170, v170
	v_add_f32_e32 v171, 1.0, v171
	v_rcp_f32_e32 v171, v171
	s_nop 0
	v_mul_f32_e32 v194, v168, v170
	v_mul_f32_e32 v195, v169, v171
	v_mul_f32_e32 v168, 0xbfb8aa3b, v167
	v_exp_f32_e32 v168, v168
	s_nop 0
	v_add_f32_e32 v168, 1.0, v168
	v_rcp_f32_e32 v173, v168
	s_nop 0
	v_mul_f32_e32 v196, v166, v172
	v_mul_f32_e32 v197, v167, v173
.LBB0_331:
	v_readlane_b32 s0, v253, 21
	v_readlane_b32 s14, v253, 35
	v_readlane_b32 s15, v253, 36
	v_readlane_b32 s1, v253, 22
	v_cvt_pk_bf16_f32 v168, v188, v189
	v_mov_b64_e32 v[166:167], s[14:15]
	v_mad_i64_i32 v[166:167], s[0:1], v165, s85, v[166:167]
	v_lshl_add_u64 v[166:167], s[44:45], 1, v[166:167]
	v_lshl_add_u64 v[170:171], v[166:167], 0, s[18:19]
	v_cvt_pk_bf16_f32 v166, v176, v177
	v_cvt_pk_bf16_f32 v167, v184, v185
	v_cvt_pk_bf16_f32 v169, v194, v195
	v_lshl_add_u64 v[170:171], v[144:145], 1, v[170:171]
	s_mov_b32 s53, s19
	global_store_dwordx4 v[170:171], v[166:169], off
	v_lshl_add_u64 v[170:171], v[170:171], 0, s[52:53]
	s_and_b64 vcc, exec, s[96:97]
	v_cvt_pk_bf16_f32 v166, v180, v181
	v_cvt_pk_bf16_f32 v167, v186, v187
	v_cvt_pk_bf16_f32 v168, v192, v193
	v_cvt_pk_bf16_f32 v169, v196, v197
	v_readlane_b32 s2, v253, 23
	v_readlane_b32 s3, v253, 24
	v_readlane_b32 s4, v253, 25
	v_readlane_b32 s5, v253, 26
	v_readlane_b32 s6, v253, 27
	v_readlane_b32 s7, v253, 28
	v_readlane_b32 s8, v253, 29
	v_readlane_b32 s9, v253, 30
	v_readlane_b32 s10, v253, 31
	v_readlane_b32 s11, v253, 32
	v_readlane_b32 s12, v253, 33
	v_readlane_b32 s13, v253, 34
	global_store_dwordx4 v[170:171], v[166:169], off
	s_cbranch_vccnz .LBB0_350
	s_nop 0
	v_mul_f32_e32 v166, v82, v164
	v_mul_f32_e32 v167, v83, v164
	v_mul_f32_e32 v168, v114, v164
	v_mul_f32_e32 v169, v115, v164
	v_mul_f32_e32 v188, v166, v146
	v_mul_f32_e32 v189, v167, v147
	v_mul_f32_e32 v166, v84, v164
	v_mul_f32_e32 v167, v85, v164
	v_mul_f32_e32 v176, v168, v148
	v_mul_f32_e32 v177, v169, v149
	v_mul_f32_e32 v168, v116, v164
	v_mul_f32_e32 v169, v117, v164
	v_mul_f32_e32 v180, v166, v150
	v_mul_f32_e32 v181, v167, v151
	v_mul_f32_e32 v166, v86, v164
	v_mul_f32_e32 v167, v87, v164
	v_mul_f32_e32 v170, v168, v152
	v_mul_f32_e32 v171, v169, v153
	v_mul_f32_e32 v168, v118, v164
	v_mul_f32_e32 v169, v119, v164
	v_mul_f32_e32 v172, v166, v154
	v_mul_f32_e32 v173, v167, v155
	v_mul_f32_e32 v166, v88, v164
	v_mul_f32_e32 v167, v89, v164
	v_mul_f32_e32 v165, v121, v164
	v_mul_f32_e32 v164, v120, v164
	v_mul_f32_e32 v168, v168, v156
	v_mul_f32_e32 v169, v169, v157
	v_mul_f32_e32 v166, v166, v158
	v_mul_f32_e32 v167, v167, v159
	v_mul_f32_e32 v164, v164, v160
	v_mul_f32_e32 v165, v165, v161
	s_and_b64 vcc, exec, s[30:31]
	v_add_u32_e32 v196, 0xa0, v238
	s_cbranch_vccnz .LBB0_334
; DI float fexp2(float x) { return __builtin_amdgcn_exp2f(x); }
; template <int GP> DI void gemm_phase(const Params& p, int l, int which, char* smem, int wv) {
;     ...
;             if (rope && !isctx) {
;               const int tt = (R % TPB) - 256;
;               const float pos = (float)(use_col ? (tt & 63) : (tt >> 6));
; #pragma unroll
;               for (int e = 0; e < 8; ++e) {
;                 float rev = pos * frev[e];
;                 rev = rev - floorf(rev);
;                 const float cs = __builtin_amdgcn_cosf(rev), sn = __builtin_amdgcn_sinf(rev);
;                 const float a = x1[e], bq = x2[e];
;                 x1[e] = a * cs - bq * sn; x2[e] = bq * cs + a * sn;
;               }
;             }
;             if (silu) {
; #pragma unroll
;               for (int e = 0; e < 8; ++e) { x1[e] = x1[e] * __builtin_amdgcn_rcpf(1.f + fexp2(-LOG2E * x1[e])); x2[e] = x2[e] * __builtin_amdgcn_rcpf(1.f + fexp2(-LOG2E * x2[e])); }
;             } else {
; #pragma unroll
;               for (int e = 0; e < 8; ++e) { x1[e] *= qmul; x2[e] *= qmul; }
.LBB0_333:
	s_mov_b32 s0, 0x38e38e39
	v_mul_hi_i32 v174, v196, s0
	v_lshrrev_b32_e32 v175, 31, v174
	v_ashrrev_i32_e32 v174, 9, v174
	v_add_u32_e32 v174, v174, v175
	v_mul_i32_i24_e32 v174, 0x900, v174
	v_sub_u32_e32 v174, v196, v174
	v_add_u32_e32 v175, 0xffffff00, v174
	v_and_b32_e32 v174, 47, v174
	v_ashrrev_i32_e32 v175, 6, v175
	v_cndmask_b32_e64 v174, v174, v175, s[16:17]
	v_cvt_f32_i32_e32 v186, v174
	v_mul_f32_e32 v174, v240, v186
	v_floor_f32_e32 v174, v174
	v_fma_f32 v175, v240, v186, -v174
	v_cos_f32_e32 v174, v175
	v_sin_f32_e32 v178, v175
	v_mul_f32_e32 v175, v241, v186
	v_floor_f32_e32 v175, v175
	v_fma_f32 v179, v241, v186, -v175
	v_cos_f32_e32 v175, v179
	v_sin_f32_e32 v179, v179
	s_nop 0
	v_mul_f32_e32 v182, v178, v176
	v_mul_f32_e32 v183, v179, v177
	s_nop 0
	v_fma_f32 v182, v174, v188, -v182
	v_fma_f32 v183, v175, v189, -v183
	v_mul_f32_e32 v174, v174, v176
	v_mul_f32_e32 v175, v175, v177
	s_nop 0
	v_fma_f32 v176, v178, v188, v174
	v_fma_f32 v177, v179, v189, v175
	v_mul_f32_e32 v174, v227, v186
	v_floor_f32_e32 v174, v174
	v_fma_f32 v175, v227, v186, -v174
	v_cos_f32_e32 v174, v175
	v_sin_f32_e32 v178, v175
	v_mul_f32_e32 v175, v239, v186
	v_floor_f32_e32 v175, v175
	v_fma_f32 v179, v239, v186, -v175
	v_cos_f32_e32 v175, v179
	v_sin_f32_e32 v179, v179
	v_mov_b64_e32 v[188:189], v[182:183]
	v_mul_f32_e32 v184, v178, v170
	v_mul_f32_e32 v185, v179, v171
	s_nop 0
	v_fma_f32 v184, v174, v180, -v184
	v_fma_f32 v185, v175, v181, -v185
	v_mul_f32_e32 v170, v174, v170
	v_mul_f32_e32 v171, v175, v171
	v_mul_f32_e32 v174, v143, v186
	v_floor_f32_e32 v174, v174
	v_fma_f32 v175, v143, v186, -v174
	v_fma_f32 v170, v178, v180, v170
	v_fma_f32 v171, v179, v181, v171
	v_cos_f32_e32 v174, v175
	v_sin_f32_e32 v178, v175
	v_mul_f32_e32 v175, v163, v186
	v_floor_f32_e32 v175, v175
	v_fma_f32 v179, v163, v186, -v175
	v_cos_f32_e32 v175, v179
	v_sin_f32_e32 v179, v179
	s_nop 0
	v_mul_f32_e32 v180, v178, v168
	v_mul_f32_e32 v181, v179, v169
	v_mul_f32_e32 v168, v174, v168
	v_mul_f32_e32 v169, v175, v169
	v_fma_f32 v180, v174, v172, -v180
	v_fma_f32 v181, v175, v173, -v181
	v_fma_f32 v168, v178, v172, v168
	v_fma_f32 v169, v179, v173, v169
	v_mul_f32_e32 v172, v131, v186
	v_floor_f32_e32 v172, v172
	v_fma_f32 v173, v131, v186, -v172
	v_cos_f32_e32 v172, v173
	v_sin_f32_e32 v174, v173
	v_mul_f32_e32 v173, v137, v186
	v_floor_f32_e32 v173, v173
	v_fma_f32 v175, v137, v186, -v173
	v_cos_f32_e32 v173, v175
	v_sin_f32_e32 v175, v175
	s_nop 0
	v_mul_f32_e32 v178, v174, v164
	v_mul_f32_e32 v179, v175, v165
	s_nop 0
	v_fma_f32 v178, v172, v166, -v178
	v_fma_f32 v179, v173, v167, -v179
	v_mul_f32_e32 v164, v172, v164
	v_mul_f32_e32 v165, v173, v165
	v_mov_b64_e32 v[172:173], v[180:181]
	v_fma_f32 v164, v174, v166, v164
	v_fma_f32 v165, v175, v167, v165
	v_mov_b64_e32 v[166:167], v[178:179]
	v_mov_b64_e32 v[180:181], v[184:185]
.LBB0_334:
	s_and_b64 vcc, exec, s[34:35]
	s_mov_b64 s[0:1], -1
	s_cbranch_vccnz .LBB0_336
	v_mul_f32_e32 v174, s50, v188
	v_mul_f32_e32 v175, s50, v189
	v_mul_f32_e32 v178, s50, v176
	v_mul_f32_e32 v179, s50, v177
	v_mul_f32_e32 v182, s50, v180
	v_mul_f32_e32 v183, s50, v181
	v_mul_f32_e32 v184, s50, v170
	v_mul_f32_e32 v185, s50, v171
	v_mul_f32_e32 v186, s50, v172
	v_mul_f32_e32 v187, s50, v173
	v_mul_f32_e32 v190, s50, v168
	v_mul_f32_e32 v191, s50, v169
	v_mul_f32_e32 v192, s50, v166
	v_mul_f32_e32 v193, s50, v167
	v_mul_f32_e32 v194, s50, v164
	v_mul_f32_e32 v195, s50, v165
	s_cbranch_execz .LBB0_337
	s_branch .LBB0_338

; DI unsigned pack2(float a, float b) { f2_t v = {a, b}; bf2_t r = __builtin_convertvector(v, bf2_t); return __builtin_bit_cast(unsigned, r); }
; DI float fexp2(float x) { return __builtin_amdgcn_exp2f(x); }
; template <int GP> DI void gemm_phase(const Params& p, int l, int which, char* smem, int wv) {
;     ...
;             float x1[8], x2[8];
; #pragma unroll
;             for (int n = 0; n < 2; ++n)
; #pragma unroll
;               for (int j = 0; j < 4; ++j) { x1[n * 4 + j] = acc[ai][0][m][n][j]; x2[n * 4 + j] = acc[ai][1][m][n][j]; }
;             if (ng) {
;               const float rinv = rinv8[ai * 4 + m];
; #pragma unroll
;               for (int e = 0; e < 8; ++e) { x1[e] = (x1[e] * rinv) * g1[e]; x2[e] = (x2[e] * rinv) * g2[e]; }
;     ...
;             if (silu) {
; #pragma unroll
;               for (int e = 0; e < 8; ++e) { x1[e] = x1[e] * __builtin_amdgcn_rcpf(1.f + fexp2(-LOG2E * x1[e])); x2[e] = x2[e] * __builtin_amdgcn_rcpf(1.f + fexp2(-LOG2E * x2[e])); }
;             } else {
; #pragma unroll
;               for (int e = 0; e < 8; ++e) { x1[e] *= qmul; x2[e] *= qmul; }
;             }
;             u16* pp = p.P + (size_t)R * INW + n0 + head * 128;
;             u32x4 o;
;             o[0] = pack2(x1[0], x1[1]); o[1] = pack2(x1[2], x1[3]); o[2] = pack2(x1[4], x1[5]); o[3] = pack2(x1[6], x1[7]);
;             *(u32x4*)(pp + c1) = o;
;             o[0] = pack2(x2[0], x2[1]); o[1] = pack2(x2[2], x2[3]); o[2] = pack2(x2[4], x2[5]); o[3] = pack2(x2[6], x2[7]);
;             *(u32x4*)(pp + c2) = o;
.LBB0_337:
	v_mul_f32_e32 v175, 0xbfb8aa3b, v176
	v_mul_f32_e32 v179, 0xbfb8aa3b, v177
	v_exp_f32_e32 v175, v175
	v_exp_f32_e32 v179, v179
	v_mul_f32_e32 v174, 0xbfb8aa3b, v188
	v_exp_f32_e32 v174, v174
	v_add_f32_e32 v175, 1.0, v175
	v_add_f32_e32 v179, 1.0, v179
	v_rcp_f32_e32 v178, v175
	v_rcp_f32_e32 v179, v179
	v_mul_f32_e32 v175, 0xbfb8aa3b, v189
	v_exp_f32_e32 v175, v175
	v_add_f32_e32 v174, 1.0, v174
	v_mul_f32_e32 v178, v176, v178
	v_mul_f32_e32 v179, v177, v179
	v_mul_f32_e32 v177, 0xbfb8aa3b, v170
	v_exp_f32_e32 v177, v177
	v_mul_f32_e32 v176, 0xbfb8aa3b, v180
	v_exp_f32_e32 v176, v176
	v_add_f32_e32 v175, 1.0, v175
	v_add_f32_e32 v177, 1.0, v177
	v_rcp_f32_e32 v184, v177
	v_mul_f32_e32 v177, 0xbfb8aa3b, v181
	v_exp_f32_e32 v177, v177
	v_add_f32_e32 v176, 1.0, v176
	v_rcp_f32_e32 v176, v176
	v_rcp_f32_e32 v174, v174
	v_add_f32_e32 v177, 1.0, v177
	v_rcp_f32_e32 v177, v177
	v_rcp_f32_e32 v175, v175
	v_mul_f32_e32 v182, v180, v176
	v_mul_f32_e32 v183, v181, v177
	v_mul_f32_e32 v176, 0xbfb8aa3b, v171
	v_exp_f32_e32 v176, v176
	v_mul_f32_e32 v174, v188, v174
	v_mul_f32_e32 v175, v189, v175
	v_add_f32_e32 v176, 1.0, v176
	v_rcp_f32_e32 v185, v176
	s_nop 0
	v_mul_f32_e32 v184, v170, v184
	v_mul_f32_e32 v185, v171, v185
	v_mul_f32_e32 v171, 0xbfb8aa3b, v168
	v_exp_f32_e32 v171, v171
	v_mul_f32_e32 v170, 0xbfb8aa3b, v172
	v_exp_f32_e32 v170, v170
	v_add_f32_e32 v171, 1.0, v171
	v_rcp_f32_e32 v176, v171
	v_mul_f32_e32 v171, 0xbfb8aa3b, v173
	v_exp_f32_e32 v171, v171
	v_add_f32_e32 v170, 1.0, v170
	v_rcp_f32_e32 v170, v170
	v_add_f32_e32 v171, 1.0, v171
	v_rcp_f32_e32 v171, v171
	s_nop 0
	v_mul_f32_e32 v186, v172, v170
	v_mul_f32_e32 v187, v173, v171
	v_mul_f32_e32 v170, 0xbfb8aa3b, v169
	v_exp_f32_e32 v170, v170
	s_nop 0
	v_add_f32_e32 v170, 1.0, v170
	v_rcp_f32_e32 v177, v170
	s_nop 0
	v_mul_f32_e32 v190, v168, v176
	v_mul_f32_e32 v191, v169, v177
	v_mul_f32_e32 v169, 0xbfb8aa3b, v164
	v_exp_f32_e32 v169, v169
	v_mul_f32_e32 v168, 0xbfb8aa3b, v166
	v_exp_f32_e32 v168, v168
	v_add_f32_e32 v169, 1.0, v169
	v_rcp_f32_e32 v170, v169
	v_mul_f32_e32 v169, 0xbfb8aa3b, v167
	v_exp_f32_e32 v169, v169
	v_add_f32_e32 v168, 1.0, v168
	v_rcp_f32_e32 v168, v168
	v_add_f32_e32 v169, 1.0, v169
	v_rcp_f32_e32 v169, v169
	s_nop 0
	v_mul_f32_e32 v192, v166, v168
	v_mul_f32_e32 v193, v167, v169
	v_mul_f32_e32 v166, 0xbfb8aa3b, v165
	v_exp_f32_e32 v166, v166
	s_nop 0
	v_add_f32_e32 v166, 1.0, v166
	v_rcp_f32_e32 v171, v166
	s_nop 0
	v_mul_f32_e32 v194, v164, v170
	v_mul_f32_e32 v195, v165, v171
.LBB0_338:
	v_readlane_b32 s0, v253, 21
	v_readlane_b32 s14, v253, 35
	v_readlane_b32 s15, v253, 36
	v_readlane_b32 s1, v253, 22
	v_cvt_pk_bf16_f32 v166, v186, v187
	v_mov_b64_e32 v[164:165], s[14:15]
	v_mad_i64_i32 v[164:165], s[0:1], v196, s85, v[164:165]
	v_lshl_add_u64 v[164:165], s[44:45], 1, v[164:165]
	v_lshl_add_u64 v[168:169], v[164:165], 0, s[18:19]
	v_cvt_pk_bf16_f32 v164, v174, v175
	v_cvt_pk_bf16_f32 v165, v182, v183
	v_cvt_pk_bf16_f32 v167, v192, v193
	v_lshl_add_u64 v[168:169], v[144:145], 1, v[168:169]
	s_mov_b32 s53, s19
	global_store_dwordx4 v[168:169], v[164:167], off
	v_lshl_add_u64 v[168:169], v[168:169], 0, s[52:53]
	s_and_b64 vcc, exec, s[96:97]
	v_cvt_pk_bf16_f32 v164, v178, v179
	v_cvt_pk_bf16_f32 v165, v184, v185
	v_cvt_pk_bf16_f32 v166, v190, v191
	v_cvt_pk_bf16_f32 v167, v194, v195
	v_readlane_b32 s2, v253, 23
	v_readlane_b32 s3, v253, 24
	v_readlane_b32 s4, v253, 25
	v_readlane_b32 s5, v253, 26
	v_readlane_b32 s6, v253, 27
	v_readlane_b32 s7, v253, 28
	v_readlane_b32 s8, v253, 29
	v_readlane_b32 s9, v253, 30
	v_readlane_b32 s10, v253, 31
	v_readlane_b32 s11, v253, 32
	v_readlane_b32 s12, v253, 33
	v_readlane_b32 s13, v253, 34
	global_store_dwordx4 v[168:169], v[164:167], off
	s_cbranch_vccnz .LBB0_351
	s_nop 0
	v_mul_f32_e32 v164, v90, v162
	v_mul_f32_e32 v165, v91, v162
	v_mul_f32_e32 v166, v122, v162
	v_mul_f32_e32 v167, v123, v162
	v_mul_f32_e32 v170, v164, v146
	v_mul_f32_e32 v171, v165, v147
	v_mul_f32_e32 v164, v166, v148
	v_mul_f32_e32 v165, v167, v149
	v_mul_f32_e32 v146, v92, v162
	v_mul_f32_e32 v147, v93, v162
	v_mul_f32_e32 v148, v124, v162
	v_mul_f32_e32 v149, v125, v162
	v_mul_f32_e32 v166, v146, v150
	v_mul_f32_e32 v167, v147, v151
	v_mul_f32_e32 v152, v148, v152
	v_mul_f32_e32 v153, v149, v153
	v_mul_f32_e32 v146, v94, v162
	v_mul_f32_e32 v147, v95, v162
	v_mul_f32_e32 v148, v126, v162
	v_mul_f32_e32 v149, v127, v162
	v_mul_f32_e32 v154, v146, v154
	v_mul_f32_e32 v155, v147, v155
	v_mul_f32_e32 v150, v148, v156
	v_mul_f32_e32 v151, v149, v157
	v_mul_f32_e32 v146, v96, v162
	v_mul_f32_e32 v147, v97, v162
	v_mul_f32_e32 v156, v128, v162
	v_mul_f32_e32 v157, v129, v162
	v_mul_f32_e32 v148, v146, v158
	v_mul_f32_e32 v149, v147, v159
	v_mul_f32_e32 v146, v156, v160
	v_mul_f32_e32 v147, v157, v161
	s_and_b64 vcc, exec, s[30:31]
	v_add_u32_e32 v178, 0xb0, v238
	s_cbranch_vccnz .LBB0_341
; DI float fexp2(float x) { return __builtin_amdgcn_exp2f(x); }
; template <int GP> DI void gemm_phase(const Params& p, int l, int which, char* smem, int wv) {
;     ...
;             if (rope && !isctx) {
;               const int tt = (R % TPB) - 256;
;               const float pos = (float)(use_col ? (tt & 63) : (tt >> 6));
; #pragma unroll
;               for (int e = 0; e < 8; ++e) {
;                 float rev = pos * frev[e];
;                 rev = rev - floorf(rev);
;                 const float cs = __builtin_amdgcn_cosf(rev), sn = __builtin_amdgcn_sinf(rev);
;                 const float a = x1[e], bq = x2[e];
;                 x1[e] = a * cs - bq * sn; x2[e] = bq * cs + a * sn;
;               }
;             }
;             if (silu) {
; #pragma unroll
;               for (int e = 0; e < 8; ++e) { x1[e] = x1[e] * __builtin_amdgcn_rcpf(1.f + fexp2(-LOG2E * x1[e])); x2[e] = x2[e] * __builtin_amdgcn_rcpf(1.f + fexp2(-LOG2E * x2[e])); }
;             } else {
; #pragma unroll
;               for (int e = 0; e < 8; ++e) { x1[e] *= qmul; x2[e] *= qmul; }
.LBB0_340:
	s_mov_b32 s0, 0x38e38e39
	v_mul_hi_i32 v156, v178, s0
	v_lshrrev_b32_e32 v157, 31, v156
	v_ashrrev_i32_e32 v156, 9, v156
	v_add_u32_e32 v156, v156, v157
	v_mul_i32_i24_e32 v156, 0x900, v156
	v_sub_u32_e32 v156, v178, v156
	v_add_u32_e32 v157, 0xffffff00, v156
	v_and_b32_e32 v156, 63, v156
	v_ashrrev_i32_e32 v157, 6, v157
	v_cndmask_b32_e64 v156, v156, v157, s[16:17]
	v_cvt_f32_i32_e32 v172, v156
	v_mul_f32_e32 v156, v240, v172
	v_floor_f32_e32 v156, v156
	v_fma_f32 v157, v240, v172, -v156
	v_cos_f32_e32 v156, v157
	v_sin_f32_e32 v158, v157
	v_mul_f32_e32 v157, v241, v172
	v_floor_f32_e32 v157, v157
	v_fma_f32 v159, v241, v172, -v157
	v_cos_f32_e32 v157, v159
	v_sin_f32_e32 v159, v159
	s_nop 0
	v_mul_f32_e32 v160, v158, v164
	v_mul_f32_e32 v161, v159, v165
	s_nop 0
	v_fma_f32 v160, v156, v170, -v160
	v_fma_f32 v161, v157, v171, -v161
	v_mul_f32_e32 v156, v156, v164
	v_mul_f32_e32 v157, v157, v165
	s_nop 0
	v_fma_f32 v164, v158, v170, v156
	v_fma_f32 v165, v159, v171, v157
	v_mul_f32_e32 v156, v227, v172
	v_floor_f32_e32 v156, v156
	v_fma_f32 v157, v227, v172, -v156
	v_cos_f32_e32 v156, v157
	v_sin_f32_e32 v158, v157
	v_mul_f32_e32 v157, v239, v172
	v_floor_f32_e32 v157, v157
	v_fma_f32 v159, v239, v172, -v157
	v_cos_f32_e32 v157, v159
	v_sin_f32_e32 v159, v159
	v_mov_b64_e32 v[170:171], v[160:161]
	v_mul_f32_e32 v168, v158, v152
	v_mul_f32_e32 v169, v159, v153
	s_nop 0
	v_fma_f32 v168, v156, v166, -v168
	v_fma_f32 v169, v157, v167, -v169
	v_mul_f32_e32 v152, v156, v152
	v_mul_f32_e32 v153, v157, v153
	v_mul_f32_e32 v156, v143, v172
	v_floor_f32_e32 v156, v156
	v_fma_f32 v143, v143, v172, -v156
	v_fma_f32 v152, v158, v166, v152
	v_fma_f32 v153, v159, v167, v153
	v_cos_f32_e32 v156, v143
	v_sin_f32_e32 v158, v143
	v_mul_f32_e32 v143, v163, v172
	v_floor_f32_e32 v143, v143
	v_fma_f32 v143, v163, v172, -v143
	v_cos_f32_e32 v157, v143
	v_sin_f32_e32 v159, v143
	v_mul_f32_e32 v143, v131, v172
	v_floor_f32_e32 v143, v143
	v_fma_f32 v131, v131, v172, -v143
	v_mul_f32_e32 v162, v158, v150
	v_mul_f32_e32 v163, v159, v151
	v_mul_f32_e32 v150, v156, v150
	v_mul_f32_e32 v151, v157, v151
	v_fma_f32 v162, v156, v154, -v162
	v_fma_f32 v163, v157, v155, -v163
	v_fma_f32 v150, v158, v154, v150
	v_fma_f32 v151, v159, v155, v151
	v_cos_f32_e32 v154, v131
	v_sin_f32_e32 v156, v131
	v_mul_f32_e32 v131, v137, v172
	v_floor_f32_e32 v131, v131
	v_fma_f32 v131, v137, v172, -v131
	v_sin_f32_e32 v157, v131
	v_cos_f32_e32 v155, v131
	v_mov_b64_e32 v[166:167], v[168:169]
	v_mul_f32_e32 v158, v156, v146
	v_mul_f32_e32 v159, v157, v147
	s_nop 0
	v_fma_f32 v158, v154, v148, -v158
	v_fma_f32 v159, v155, v149, -v159
	v_mul_f32_e32 v146, v154, v146
	v_mul_f32_e32 v147, v155, v147
	v_mov_b64_e32 v[154:155], v[162:163]
	v_fma_f32 v146, v156, v148, v146
	v_fma_f32 v147, v157, v149, v147
	v_mov_b64_e32 v[148:149], v[158:159]
.LBB0_341:
	s_and_b64 vcc, exec, s[34:35]
	s_mov_b64 s[0:1], -1
	s_cbranch_vccnz .LBB0_343
	v_mul_f32_e32 v156, s50, v170
	v_mul_f32_e32 v157, s50, v171
	v_mul_f32_e32 v158, s50, v164
	v_mul_f32_e32 v159, s50, v165
	v_mul_f32_e32 v160, s50, v166
	v_mul_f32_e32 v161, s50, v167
	v_mul_f32_e32 v162, s50, v152
	v_mul_f32_e32 v163, s50, v153
	v_mul_f32_e32 v168, s50, v154
	v_mul_f32_e32 v169, s50, v155
	v_mul_f32_e32 v172, s50, v150
	v_mul_f32_e32 v173, s50, v151
	v_mul_f32_e32 v174, s50, v148
	v_mul_f32_e32 v175, s50, v149
	v_mul_f32_e32 v176, s50, v146
	v_mul_f32_e32 v177, s50, v147
	s_mov_b64 s[2:3], s[18:19]
	s_cbranch_execnz .LBB0_185
	s_branch .LBB0_344

; DI float fexp2(float x) { return __builtin_amdgcn_exp2f(x); }
; template <int GP> DI void gemm_phase(const Params& p, int l, int which, char* smem, int wv) {
;     ...
;             if (silu) {
; #pragma unroll
;               for (int e = 0; e < 8; ++e) { x1[e] = x1[e] * __builtin_amdgcn_rcpf(1.f + fexp2(-LOG2E * x1[e])); x2[e] = x2[e] * __builtin_amdgcn_rcpf(1.f + fexp2(-LOG2E * x2[e])); }
.LBB0_344:
	v_mul_f32_e32 v131, 0xbfb8aa3b, v170
	v_exp_f32_e32 v131, v131
	s_nop 0
	v_add_f32_e32 v131, 1.0, v131
	v_rcp_f32_e32 v156, v131
	v_mul_f32_e32 v131, 0xbfb8aa3b, v164
	v_exp_f32_e32 v131, v131
	s_nop 0
	v_add_f32_e32 v131, 1.0, v131
	v_rcp_f32_e32 v158, v131
	v_mul_f32_e32 v131, 0xbfb8aa3b, v171
	v_exp_f32_e32 v131, v131
	s_nop 0
	v_add_f32_e32 v131, 1.0, v131
	v_rcp_f32_e32 v157, v131
	v_mul_f32_e32 v131, 0xbfb8aa3b, v165
	v_exp_f32_e32 v131, v131
	v_mul_f32_e32 v156, v170, v156
	v_mul_f32_e32 v157, v171, v157
	v_add_f32_e32 v131, 1.0, v131
	v_rcp_f32_e32 v159, v131
	v_mul_f32_e32 v131, 0xbfb8aa3b, v166
	v_exp_f32_e32 v131, v131
	v_mul_f32_e32 v158, v164, v158
	v_mul_f32_e32 v159, v165, v159
	v_add_f32_e32 v131, 1.0, v131
	v_rcp_f32_e32 v160, v131
	v_mul_f32_e32 v131, 0xbfb8aa3b, v152
	v_exp_f32_e32 v131, v131
	s_nop 0
	v_add_f32_e32 v131, 1.0, v131
	v_rcp_f32_e32 v162, v131
	v_mul_f32_e32 v131, 0xbfb8aa3b, v167
	v_exp_f32_e32 v131, v131
	s_nop 0
	v_add_f32_e32 v131, 1.0, v131
	v_rcp_f32_e32 v161, v131
	v_mul_f32_e32 v131, 0xbfb8aa3b, v153
	v_exp_f32_e32 v131, v131
	v_mul_f32_e32 v160, v166, v160
	v_mul_f32_e32 v161, v167, v161
	v_add_f32_e32 v131, 1.0, v131
	v_rcp_f32_e32 v163, v131
	v_mul_f32_e32 v131, 0xbfb8aa3b, v154
	v_exp_f32_e32 v131, v131
	v_mul_f32_e32 v162, v152, v162
	v_mul_f32_e32 v163, v153, v163
	v_add_f32_e32 v131, 1.0, v131
	v_rcp_f32_e32 v152, v131
	v_mul_f32_e32 v131, 0xbfb8aa3b, v150
	v_exp_f32_e32 v131, v131
	s_nop 0
	v_add_f32_e32 v131, 1.0, v131
	v_rcp_f32_e32 v164, v131
	v_mul_f32_e32 v131, 0xbfb8aa3b, v155
	v_exp_f32_e32 v131, v131
	s_nop 0
	v_add_f32_e32 v131, 1.0, v131
	v_rcp_f32_e32 v153, v131
	v_mul_f32_e32 v131, 0xbfb8aa3b, v151
	v_exp_f32_e32 v131, v131
	v_mul_f32_e32 v168, v154, v152
	v_mul_f32_e32 v169, v155, v153
	v_add_f32_e32 v131, 1.0, v131
	v_rcp_f32_e32 v165, v131
	v_mul_f32_e32 v131, 0xbfb8aa3b, v148
	v_exp_f32_e32 v131, v131
	v_mul_f32_e32 v172, v150, v164
	v_mul_f32_e32 v173, v151, v165
	v_add_f32_e32 v131, 1.0, v131
	v_rcp_f32_e32 v150, v131
	v_mul_f32_e32 v131, 0xbfb8aa3b, v146
	v_exp_f32_e32 v131, v131
	s_nop 0
	v_add_f32_e32 v131, 1.0, v131
	v_rcp_f32_e32 v152, v131
	v_mul_f32_e32 v131, 0xbfb8aa3b, v149
	v_exp_f32_e32 v131, v131
	s_nop 0
	v_add_f32_e32 v131, 1.0, v131
	v_rcp_f32_e32 v151, v131
	v_mul_f32_e32 v131, 0xbfb8aa3b, v147
	v_exp_f32_e32 v131, v131
	v_mul_f32_e32 v174, v148, v150
	v_mul_f32_e32 v175, v149, v151
	v_add_f32_e32 v131, 1.0, v131
	v_rcp_f32_e32 v153, v131
	s_nop 0
	v_mul_f32_e32 v176, v146, v152
	v_mul_f32_e32 v177, v147, v153
	s_branch .LBB0_185

; DI float fexp2(float x) { return __builtin_amdgcn_exp2f(x); }
; DI float half_max(float v) { const auto r = __builtin_amdgcn_permlane32_swap(__float_as_uint(v), __float_as_uint(v), false, false); return fmaxf(__uint_as_float(r[0]), __uint_as_float(r[1])); }
; template <int PM> DI void attn_phase(const Params& p, int l, char* smem, int* s_item, int wv, int cidx) {
;     ...
;           float mt = sacc[0][0];
; #pragma unroll
;           for (int e = 1; e < 16; ++e) mt = fmaxf(mt, sacc[0][e]);
; #pragma unroll
;           for (int e = 0; e < 16; ++e) mt = fmaxf(mt, sacc[1][e]);
;           mt = half_max(mt);
;           if (__builtin_amdgcn_ballot_w64(mt > m + 8.f) != 0ull) {
;             const float mnew = fmaxf(m, mt);
;             const float alpha = fexp2(m - mnew);
;             m = mnew;
;             lsum *= alpha;
; #pragma unroll
;             for (int db = 0; db < 4; ++db)
; #pragma unroll
;               for (int e = 0; e < 16; ++e) Oacc[db][e] *= alpha;
;           }
.LBB0_512:
	v_max_f32_e32 v0, v17, v17
	s_waitcnt lgkmcnt(2)
	v_max_f32_e32 v2, v16, v16
	v_max_f32_e32 v0, v2, v0
	v_max3_f32 v0, v0, v18, v19
	v_max3_f32 v0, v0, v20, v21
	v_max3_f32 v0, v0, v22, v23
	v_max3_f32 v0, v0, v24, v25
	v_max3_f32 v0, v0, v26, v27
	v_max3_f32 v0, v0, v28, v29
	v_max3_f32 v0, v0, v30, v31
	v_max3_f32 v0, v0, v32, v33
	v_max3_f32 v0, v0, v34, v35
	v_max3_f32 v0, v0, v36, v37
	v_max3_f32 v0, v0, v38, v39
	v_max3_f32 v0, v0, v40, v41
	v_max3_f32 v0, v0, v42, v43
	v_max3_f32 v0, v0, v44, v45
	v_max3_f32 v0, v0, v46, v47
	v_mov_b32_e32 v2, v0
	s_nop 1
	v_permlane32_swap_b32_e32 v0, v2
	v_max_f32_e32 v2, v2, v2
	v_max_f32_e32 v0, v0, v0
	v_max_f32_e32 v0, v0, v2
	v_add_f32_e32 v2, 0x41000000, v233
	v_cmp_gt_f32_e32 vcc, v0, v2
	s_cbranch_vccz .LBB0_514
	v_max_f32_e32 v0, v0, v0
	v_max_f32_e32 v2, v233, v233
	v_max_f32_e32 v2, v2, v0
	v_sub_f32_e32 v0, v233, v2
	v_exp_f32_e32 v0, v0
	v_mov_b32_e32 v233, v2
	v_mul_f32_e32 v142, v142, v0
	v_mul_f32_e32 v143, v143, v0
	v_mul_f32_e32 v140, v140, v0
	v_mul_f32_e32 v141, v141, v0
	v_mul_f32_e32 v138, v138, v0
	v_mul_f32_e32 v139, v139, v0
	v_mul_f32_e32 v136, v136, v0
	v_mul_f32_e32 v137, v137, v0
	v_mul_f32_e32 v134, v134, v0
	v_mul_f32_e32 v135, v135, v0
	v_mul_f32_e32 v132, v132, v0
	v_mul_f32_e32 v133, v133, v0
	v_mul_f32_e32 v130, v130, v0
	v_mul_f32_e32 v131, v131, v0
	v_mul_f32_e32 v128, v128, v0
	v_mul_f32_e32 v129, v129, v0
	v_mul_f32_e32 v126, v126, v0
	v_mul_f32_e32 v127, v127, v0
	v_mul_f32_e32 v124, v124, v0
	v_mul_f32_e32 v125, v125, v0
	v_mul_f32_e32 v122, v122, v0
	v_mul_f32_e32 v123, v123, v0
	v_mul_f32_e32 v120, v120, v0
	v_mul_f32_e32 v121, v121, v0
	v_mul_f32_e32 v118, v118, v0
	v_mul_f32_e32 v119, v119, v0
	v_mul_f32_e32 v116, v116, v0
	v_mul_f32_e32 v117, v117, v0
	v_mul_f32_e32 v114, v114, v0
	v_mul_f32_e32 v115, v115, v0
	v_mul_f32_e32 v112, v112, v0
	v_mul_f32_e32 v113, v113, v0
	v_mul_f32_e32 v110, v110, v0
	v_mul_f32_e32 v111, v111, v0
	v_mul_f32_e32 v108, v108, v0
	v_mul_f32_e32 v109, v109, v0
	v_mul_f32_e32 v106, v106, v0
	v_mul_f32_e32 v107, v107, v0
	v_mul_f32_e32 v104, v104, v0
	v_mul_f32_e32 v105, v105, v0
	v_mul_f32_e32 v102, v102, v0
	v_mul_f32_e32 v103, v103, v0
	v_mul_f32_e32 v100, v100, v0
	v_mul_f32_e32 v101, v101, v0
	v_mul_f32_e32 v98, v98, v0
	v_mul_f32_e32 v99, v99, v0
	v_mul_f32_e32 v96, v96, v0
	v_mul_f32_e32 v97, v97, v0
	v_mul_f32_e32 v94, v94, v0
	v_mul_f32_e32 v95, v95, v0
	v_mul_f32_e32 v92, v92, v0
	v_mul_f32_e32 v93, v93, v0
	v_mul_f32_e32 v90, v90, v0
	v_mul_f32_e32 v91, v91, v0
	v_mul_f32_e32 v88, v88, v0
	v_mul_f32_e32 v89, v89, v0
	v_mul_f32_e32 v86, v86, v0
	v_mul_f32_e32 v87, v87, v0
	v_mul_f32_e32 v84, v84, v0
	v_mul_f32_e32 v85, v85, v0
	v_mul_f32_e32 v82, v82, v0
	v_mul_f32_e32 v83, v83, v0
	v_mul_f32_e32 v80, v80, v0
	v_mul_f32_e32 v81, v81, v0
	v_mul_f32_e32 v235, v235, v0

; DI float fexp2(float x) { return __builtin_amdgcn_exp2f(x); }
; DI float half_sum(float v) { const auto r = __builtin_amdgcn_permlane32_swap(__float_as_uint(v), __float_as_uint(v), false, false); return __uint_as_float(r[0]) + __uint_as_float(r[1]); }
; template <int PM> DI void attn_phase(const Params& p, int l, char* smem, int* s_item, int wv, int cidx) {
;     ...
;       float lt = half_sum(lsum);
;       if (mixer == 1) lt += fexp2(p.sink[l * 4 + head] * LOG2E - m);
;       const float inv = 1.f / lt;
;       float ov[4][16];
; #pragma unroll
;       for (int db = 0; db < 4; ++db)
; #pragma unroll
;         for (int e = 0; e < 16; ++e) ov[db][e] = Oacc[db][e] * inv;
;       if (mixer == 0 && pass == 0) {
; #pragma unroll
;         for (int db = 0; db < 4; ++db)
; #pragma unroll
;           for (int g = 0; g < 4; ++g) {
;             f32x4 o;
; #pragma unroll
;             for (int e = 0; e < 4; ++e) o[e] = ov[db][4 * g + e];
;             *(f32x4*)(asave + db * 32 + 8 * g) = o;
;           }
;         continue;
;       }
;       float rr = 1.f;
;       if (mixer == 0) {
;         float ss = 0.f;
;         const float* ap = asave;
; #pragma unroll
;         for (int db = 0; db < 4; ++db) {
;           asm volatile("" : "+v"(ap), "+v"(ss));
; #pragma unroll
;           for (int g = 0; g < 4; ++g) {
;             const f32x4 sv = *(const f32x4*)(ap + db * 32 + 8 * g);
; #pragma unroll
;             for (int e = 0; e < 4; ++e) { const float o = sv[e] - lam * ov[db][4 * g + e]; ov[db][4 * g + e] = o; ss += o * o; }
;           }
;         }
;         ss = half_sum(ss);
;         rr = rsqrtf(ss * (1.f / 128.f) + EPSV) * (1.f - lambda_init);
.LBB0_524:
	v_div_scale_f32 v2, s[0:1], v0, v0, 1.0
	v_rcp_f32_e32 v3, v2
	v_div_scale_f32 v4, vcc, 1.0, v0, 1.0
	s_or_b32 s0, s91, s86
	v_fma_f32 v5, -v2, v3, 1.0
	v_fmac_f32_e32 v3, v5, v3
	v_mul_f32_e32 v5, v4, v3
	v_fma_f32 v6, -v2, v5, v4
	v_fmac_f32_e32 v5, v6, v3
	v_fma_f32 v2, -v2, v5, v4
	v_div_fmas_f32 v2, v2, v3, v5
	v_div_fixup_f32 v0, v2, v0, 1.0
	v_mul_f32_e32 v2, v128, v0
	v_mul_f32_e32 v3, v129, v0
	v_mul_f32_e32 v4, v130, v0
	v_mul_f32_e32 v5, v131, v0
	v_mul_f32_e32 v6, v132, v0
	v_mul_f32_e32 v7, v133, v0
	v_mul_f32_e32 v8, v134, v0
	v_mul_f32_e32 v9, v135, v0
	v_mul_f32_e32 v48, v136, v0
	v_mul_f32_e32 v49, v137, v0
	v_mul_f32_e32 v50, v138, v0
	v_mul_f32_e32 v51, v139, v0
	v_mul_f32_e32 v56, v140, v0
	v_mul_f32_e32 v57, v141, v0
	v_mul_f32_e32 v58, v142, v0
	v_mul_f32_e32 v59, v143, v0
	v_mul_f32_e32 v10, v112, v0
	v_mul_f32_e32 v11, v113, v0
	v_mul_f32_e32 v12, v114, v0
	v_mul_f32_e32 v13, v115, v0
	v_mul_f32_e32 v52, v116, v0
	v_mul_f32_e32 v53, v117, v0
	v_mul_f32_e32 v54, v118, v0
	v_mul_f32_e32 v55, v119, v0
	v_mul_f32_e32 v64, v120, v0
	v_mul_f32_e32 v65, v121, v0
	v_mul_f32_e32 v66, v122, v0
	v_mul_f32_e32 v67, v123, v0
	v_mul_f32_e32 v72, v124, v0
	v_mul_f32_e32 v73, v125, v0
	v_mul_f32_e32 v74, v126, v0
	v_mul_f32_e32 v75, v127, v0
	v_mul_f32_e32 v60, v96, v0
	v_mul_f32_e32 v61, v97, v0
	v_mul_f32_e32 v62, v98, v0
	v_mul_f32_e32 v63, v99, v0
	v_mul_f32_e32 v68, v100, v0
	v_mul_f32_e32 v69, v101, v0
	v_mul_f32_e32 v70, v102, v0
	v_mul_f32_e32 v71, v103, v0
	v_mul_f32_e32 v96, v104, v0
	v_mul_f32_e32 v97, v105, v0
	v_mul_f32_e32 v98, v106, v0
	v_mul_f32_e32 v99, v107, v0
	v_mul_f32_e32 v100, v108, v0
	v_mul_f32_e32 v101, v109, v0
	v_mul_f32_e32 v102, v110, v0
	v_mul_f32_e32 v103, v111, v0
	v_mul_f32_e32 v76, v80, v0
	v_mul_f32_e32 v77, v81, v0
	v_mul_f32_e32 v78, v82, v0
	v_mul_f32_e32 v79, v83, v0
	v_mul_f32_e32 v80, v84, v0
	v_mul_f32_e32 v81, v85, v0
	v_mul_f32_e32 v82, v86, v0
	v_mul_f32_e32 v83, v87, v0
	v_mul_f32_e32 v84, v88, v0
	v_mul_f32_e32 v85, v89, v0
	v_mul_f32_e32 v86, v90, v0
	v_mul_f32_e32 v87, v91, v0
	v_mul_f32_e32 v88, v92, v0
	v_mul_f32_e32 v89, v93, v0
	s_cmp_lg_u32 s0, 0
	v_mul_f32_e32 v90, v94, v0
	v_mul_f32_e32 v91, v95, v0
	s_cbranch_scc0 .LBB0_560
	v_readlane_b32 s0, v254, 61
	v_readlane_b32 s1, v254, 62
	v_mov_b32_e32 v92, 1.0
	s_andn2_b64 vcc, exec, s[0:1]
	v_cndmask_b32_e64 v0, 0, 1, s[0:1]
	v_cmp_ne_u32_e64 s[72:73], 1, v0
	v_mov_b32_e32 v170, 1.0
	v_mov_b64_e32 v[166:167], v[90:91]
	v_mov_b64_e32 v[162:163], v[88:89]
	v_mov_b64_e32 v[154:155], v[86:87]
	v_mov_b64_e32 v[156:157], v[84:85]
	v_mov_b64_e32 v[158:159], v[82:83]
	v_mov_b64_e32 v[160:161], v[80:81]
	v_mov_b64_e32 v[164:165], v[78:79]
	v_mov_b64_e32 v[168:169], v[76:77]
	v_mov_b64_e32 v[150:151], v[102:103]
	v_mov_b64_e32 v[142:143], v[100:101]
	v_mov_b64_e32 v[134:135], v[98:99]
	v_mov_b64_e32 v[136:137], v[96:97]
	v_mov_b64_e32 v[138:139], v[70:71]
	v_mov_b64_e32 v[140:141], v[68:69]
	v_mov_b64_e32 v[148:149], v[62:63]
	v_mov_b64_e32 v[152:153], v[60:61]
	v_mov_b64_e32 v[130:131], v[74:75]
	v_mov_b64_e32 v[126:127], v[72:73]
	v_mov_b64_e32 v[118:119], v[66:67]
	v_mov_b64_e32 v[120:121], v[64:65]
	v_mov_b64_e32 v[122:123], v[54:55]
	v_mov_b64_e32 v[124:125], v[52:53]
	v_mov_b64_e32 v[128:129], v[12:13]
	v_mov_b64_e32 v[132:133], v[10:11]
	v_mov_b64_e32 v[116:117], v[58:59]
	v_mov_b64_e32 v[114:115], v[56:57]
	v_mov_b64_e32 v[14:15], v[50:51]
	v_mov_b64_e32 v[110:111], v[48:49]
	v_mov_b64_e32 v[108:109], v[8:9]
	v_mov_b64_e32 v[112:113], v[6:7]
	v_mov_b64_e32 v[104:105], v[4:5]
	v_mov_b64_e32 v[106:107], v[2:3]
	s_cbranch_vccnz .LBB0_527
	v_mov_b64_e32 v[94:95], v[206:207]
	v_mov_b32_e32 v0, v1
	s_waitcnt vmcnt(0)
	v_mov_b64_e32 v[106:107], v[16:17]
	v_mov_b64_e32 v[108:109], v[18:19]
	v_mov_b64_e32 v[114:115], v[24:25]
	v_mov_b64_e32 v[116:117], v[26:27]
	s_mov_b32 s0, 0x800000
	s_waitcnt vmcnt(0) lgkmcnt(0)
	v_fma_f32 v104, -s4, v4, v108
	v_fma_f32 v105, -s5, v5, v109
	v_mov_b64_e32 v[108:109], v[20:21]
	v_mov_b64_e32 v[110:111], v[22:23]
	v_fma_f32 v106, -s4, v2, v106
	v_fma_f32 v107, -s5, v3, v107
	s_waitcnt vmcnt(0) lgkmcnt(0)
	v_fma_f32 v112, -s4, v6, v108
	v_fma_f32 v113, -s5, v7, v109
	v_mul_f32_e32 v14, v106, v106
	v_mul_f32_e32 v15, v107, v107
	v_fma_f32 v108, -s4, v8, v110
	v_fma_f32 v109, -s5, v9, v111
	v_add_f32_e32 v0, v0, v14
	v_add_f32_e32 v0, v15, v0
	v_mul_f32_e32 v14, v104, v104
	v_mul_f32_e32 v15, v105, v105
	v_fma_f32 v110, -s4, v48, v114
	v_fma_f32 v111, -s5, v49, v115
	v_add_f32_e32 v0, v14, v0
	v_add_f32_e32 v0, v15, v0
	v_mul_f32_e32 v14, v112, v112
	v_mul_f32_e32 v15, v113, v113
	s_nop 0
	v_add_f32_e32 v0, v14, v0
	v_add_f32_e32 v0, v15, v0
	v_mul_f32_e32 v14, v108, v108
	v_mul_f32_e32 v15, v109, v109
	s_nop 0
	v_add_f32_e32 v0, v14, v0
	v_add_f32_e32 v0, v15, v0
	v_mul_f32_e32 v14, v110, v110
	v_mul_f32_e32 v15, v111, v111
	s_nop 0
	v_add_f32_e32 v0, v14, v0
	v_add_f32_e32 v0, v15, v0
	v_fma_f32 v14, -s4, v50, v116
	v_fma_f32 v15, -s5, v51, v117
	s_nop 0
	v_mul_f32_e32 v114, v14, v14
	v_mul_f32_e32 v115, v15, v15
	s_nop 0
	v_add_f32_e32 v0, v114, v0
	v_add_f32_e32 v0, v115, v0
	v_mov_b64_e32 v[114:115], v[28:29]
	v_mov_b64_e32 v[116:117], v[30:31]
	s_waitcnt vmcnt(0) lgkmcnt(0)
	v_fma_f32 v114, -s4, v56, v114
	v_fma_f32 v115, -s5, v57, v115
	s_nop 0
	v_mul_f32_e32 v118, v114, v114
	v_mul_f32_e32 v119, v115, v115
	v_fma_f32 v116, -s4, v58, v116
	v_fma_f32 v117, -s5, v59, v117
	v_add_f32_e32 v0, v118, v0
	v_add_f32_e32 v0, v119, v0
	v_mul_f32_e32 v118, v116, v116
	v_mul_f32_e32 v119, v117, v117
	s_nop 0
	v_add_f32_e32 v0, v118, v0
	v_add_f32_e32 v0, v119, v0
	v_mov_b64_e32 v[118:119], v[32:33]
	v_mov_b64_e32 v[120:121], v[34:35]
	v_mov_b64_e32 v[134:135], v[40:41]
	v_mov_b64_e32 v[136:137], v[42:43]
	s_waitcnt vmcnt(0) lgkmcnt(0)
; DI float half_sum(float v) { const auto r = __builtin_amdgcn_permlane32_swap(__float_as_uint(v), __float_as_uint(v), false, false); return __uint_as_float(r[0]) + __uint_as_float(r[1]); }
; template <int PM> DI void attn_phase(const Params& p, int l, char* smem, int* s_item, int wv, int cidx) {
;     ...
;       if (mixer == 0) {
;         float ss = 0.f;
;         const float* ap = asave;
; #pragma unroll
;         for (int db = 0; db < 4; ++db) {
;           asm volatile("" : "+v"(ap), "+v"(ss));
; #pragma unroll
;           for (int g = 0; g < 4; ++g) {
;             const f32x4 sv = *(const f32x4*)(ap + db * 32 + 8 * g);
; #pragma unroll
;             for (int e = 0; e < 4; ++e) { const float o = sv[e] - lam * ov[db][4 * g + e]; ov[db][4 * g + e] = o; ss += o * o; }
;           }
;         }
;         ss = half_sum(ss);
;         rr = rsqrtf(ss * (1.f / 128.f) + EPSV) * (1.f - lambda_init);
	v_fma_f32 v132, -s4, v10, v118
	v_fma_f32 v133, -s5, v11, v119
	s_nop 0
	v_mul_f32_e32 v118, v132, v132
	v_mul_f32_e32 v119, v133, v133
	v_fma_f32 v128, -s4, v12, v120
	v_fma_f32 v129, -s5, v13, v121
	v_add_f32_e32 v0, v0, v118
	v_add_f32_e32 v0, v119, v0
	v_mul_f32_e32 v118, v128, v128
	v_mul_f32_e32 v119, v129, v129
	s_nop 0
	v_add_f32_e32 v0, v118, v0
	v_add_f32_e32 v0, v119, v0
	v_mov_b64_e32 v[118:119], v[36:37]
	v_mov_b64_e32 v[120:121], v[38:39]
	s_waitcnt vmcnt(0) lgkmcnt(0)
	v_fma_f32 v124, -s4, v52, v118
	v_fma_f32 v125, -s5, v53, v119
	s_nop 0
	v_mul_f32_e32 v118, v124, v124
	v_mul_f32_e32 v119, v125, v125
	v_fma_f32 v122, -s4, v54, v120
	v_fma_f32 v123, -s5, v55, v121
	v_add_f32_e32 v0, v118, v0
	v_add_f32_e32 v0, v119, v0
	v_mul_f32_e32 v118, v122, v122
	v_mul_f32_e32 v119, v123, v123
	v_fma_f32 v120, -s4, v64, v134
	v_fma_f32 v121, -s5, v65, v135
	v_add_f32_e32 v0, v118, v0
	v_add_f32_e32 v0, v119, v0
	v_mul_f32_e32 v118, v120, v120
	v_mul_f32_e32 v119, v121, v121
	s_nop 0
	v_add_f32_e32 v0, v118, v0
	v_add_f32_e32 v0, v119, v0
	v_fma_f32 v118, -s4, v66, v136
	v_fma_f32 v119, -s5, v67, v137
	v_mov_b64_e32 v[134:135], v[44:45]
	v_mov_b64_e32 v[136:137], v[46:47]
	v_mul_f32_e32 v126, v118, v118
	v_mul_f32_e32 v127, v119, v119
	s_nop 0
	v_add_f32_e32 v0, v126, v0
	v_add_f32_e32 v0, v127, v0
	s_waitcnt vmcnt(0) lgkmcnt(0)
	v_fma_f32 v126, -s4, v72, v134
	v_fma_f32 v127, -s5, v73, v135
	s_nop 0
	v_mul_f32_e32 v130, v126, v126
	v_mul_f32_e32 v131, v127, v127
	s_nop 0
	v_add_f32_e32 v0, v130, v0
	v_add_f32_e32 v0, v131, v0
	v_fma_f32 v130, -s4, v74, v136
	v_fma_f32 v131, -s5, v75, v137
	s_nop 0
	v_mul_f32_e32 v134, v130, v130
	v_mul_f32_e32 v135, v131, v131
	s_nop 0
	v_add_f32_e32 v0, v134, v0
	v_add_f32_e32 v0, v135, v0
	v_mov_b64_e32 v[134:135], v[176:177]
	v_mov_b64_e32 v[136:137], v[178:179]
	v_mov_b64_e32 v[154:155], v[184:185]
	v_mov_b64_e32 v[156:157], v[186:187]
	s_waitcnt vmcnt(0) lgkmcnt(0)
	v_fma_f32 v152, -s4, v60, v134
	v_fma_f32 v153, -s5, v61, v135
	s_nop 0
	v_mul_f32_e32 v134, v152, v152
	v_mul_f32_e32 v135, v153, v153
	v_fma_f32 v148, -s4, v62, v136
	v_fma_f32 v149, -s5, v63, v137
	v_add_f32_e32 v0, v0, v134
	v_add_f32_e32 v0, v135, v0
	v_mul_f32_e32 v134, v148, v148
	v_mul_f32_e32 v135, v149, v149
	s_nop 0
	v_add_f32_e32 v0, v134, v0
	v_add_f32_e32 v0, v135, v0
	v_mov_b64_e32 v[134:135], v[180:181]
	v_mov_b64_e32 v[136:137], v[182:183]
	s_waitcnt vmcnt(0) lgkmcnt(0)
	v_fma_f32 v140, -s4, v68, v134
	v_fma_f32 v141, -s5, v69, v135
	s_nop 0
	v_mul_f32_e32 v134, v140, v140
	v_mul_f32_e32 v135, v141, v141
	v_fma_f32 v138, -s4, v70, v136
	v_fma_f32 v139, -s5, v71, v137
	v_add_f32_e32 v0, v134, v0
	v_add_f32_e32 v0, v135, v0
	v_mul_f32_e32 v134, v138, v138
	v_mul_f32_e32 v135, v139, v139
	v_fma_f32 v136, -s4, v96, v154
	v_fma_f32 v137, -s5, v97, v155
	v_add_f32_e32 v0, v134, v0
	v_add_f32_e32 v0, v135, v0
	v_mul_f32_e32 v134, v136, v136
	v_mul_f32_e32 v135, v137, v137
	s_nop 0
	v_add_f32_e32 v0, v134, v0
	v_add_f32_e32 v0, v135, v0
	v_fma_f32 v134, -s4, v98, v156
	v_fma_f32 v135, -s5, v99, v157
	v_mov_b64_e32 v[154:155], v[188:189]
	v_mov_b64_e32 v[156:157], v[190:191]
	v_mul_f32_e32 v142, v134, v134
	v_mul_f32_e32 v143, v135, v135
	s_nop 0
	v_add_f32_e32 v0, v142, v0
	v_add_f32_e32 v0, v143, v0
	s_waitcnt vmcnt(0) lgkmcnt(0)
	v_fma_f32 v142, -s4, v100, v154
	v_fma_f32 v143, -s5, v101, v155
	s_nop 0
	v_mul_f32_e32 v150, v142, v142
	v_mul_f32_e32 v151, v143, v143
	s_nop 0
	v_add_f32_e32 v0, v150, v0
	v_add_f32_e32 v0, v151, v0
	v_fma_f32 v150, -s4, v102, v156
	v_fma_f32 v151, -s5, v103, v157
	s_nop 0
	v_mul_f32_e32 v154, v150, v150
	v_mul_f32_e32 v155, v151, v151
	s_nop 0
	v_add_f32_e32 v0, v154, v0
	v_add_f32_e32 v0, v155, v0
	v_mov_b64_e32 v[154:155], v[192:193]
	v_mov_b64_e32 v[156:157], v[194:195]
	v_mov_b64_e32 v[170:171], v[214:215]
	v_mov_b64_e32 v[172:173], v[216:217]
	s_waitcnt vmcnt(0) lgkmcnt(0)
	v_fma_f32 v168, -s4, v76, v154
	v_fma_f32 v169, -s5, v77, v155
	s_nop 0
	v_mul_f32_e32 v154, v168, v168
	v_mul_f32_e32 v155, v169, v169
	v_fma_f32 v164, -s4, v78, v156
	v_fma_f32 v165, -s5, v79, v157
	v_add_f32_e32 v0, v0, v154
	v_add_f32_e32 v0, v155, v0
	v_mul_f32_e32 v154, v164, v164
	v_mul_f32_e32 v155, v165, v165
	s_nop 0
	v_add_f32_e32 v0, v154, v0
	v_add_f32_e32 v0, v155, v0
	v_mov_b64_e32 v[154:155], v[210:211]
	v_mov_b64_e32 v[156:157], v[212:213]
	s_waitcnt vmcnt(0) lgkmcnt(0)
	v_fma_f32 v160, -s4, v80, v154
	v_fma_f32 v161, -s5, v81, v155
	s_nop 0
	v_mul_f32_e32 v154, v160, v160
	v_mul_f32_e32 v155, v161, v161
	v_fma_f32 v158, -s4, v82, v156
	v_fma_f32 v159, -s5, v83, v157
	v_add_f32_e32 v0, v154, v0
	v_add_f32_e32 v0, v155, v0
	v_mul_f32_e32 v154, v158, v158
	v_mul_f32_e32 v155, v159, v159
	v_fma_f32 v156, -s4, v84, v170
	v_fma_f32 v157, -s5, v85, v171
	v_add_f32_e32 v0, v154, v0
	v_add_f32_e32 v0, v155, v0
	v_mul_f32_e32 v154, v156, v156
	v_mul_f32_e32 v155, v157, v157
	s_nop 0
	v_add_f32_e32 v0, v154, v0
	v_add_f32_e32 v0, v155, v0
	v_fma_f32 v154, -s4, v86, v172
	v_fma_f32 v155, -s5, v87, v173
	v_mov_b64_e32 v[170:171], v[218:219]
	v_mov_b64_e32 v[172:173], v[220:221]
	v_mul_f32_e32 v162, v154, v154
	v_mul_f32_e32 v163, v155, v155
	s_waitcnt vmcnt(0) lgkmcnt(0)
	v_fma_f32 v166, -s4, v90, v172
	v_fma_f32 v167, -s5, v91, v173
	v_add_f32_e32 v0, v162, v0
	v_add_f32_e32 v0, v163, v0
	v_fma_f32 v162, -s4, v88, v170
	v_fma_f32 v163, -s5, v89, v171
	s_nop 0
	v_mul_f32_e32 v94, v162, v162
	v_mul_f32_e32 v95, v163, v163
	s_nop 0
	v_add_f32_e32 v0, v94, v0
	v_add_f32_e32 v0, v95, v0
	v_mul_f32_e32 v94, v166, v166
	v_mul_f32_e32 v95, v167, v167
	s_nop 0
	v_add_f32_e32 v0, v94, v0
	v_add_f32_e32 v0, v95, v0
	v_mov_b32_e32 v93, v0
	s_nop 1
	v_permlane32_swap_b32_e32 v0, v93
	v_add_f32_e32 v0, v0, v93
	v_fmamk_f32 v0, v0, 0x3c000000, v232
	v_cmp_gt_f32_e32 vcc, s0, v0
	v_mul_f32_e32 v93, 0x4b800000, v0
	s_nop 0
	v_cndmask_b32_e32 v0, v0, v93, vcc
	v_rsq_f32_e32 v0, v0
	s_nop 0
	v_mul_f32_e32 v93, 0x45800000, v0
	v_cndmask_b32_e32 v0, v0, v93, vcc
	v_mul_f32_e32 v170, v244, v0

; DI unsigned pack2(float a, float b) { f2_t v = {a, b}; bf2_t r = __builtin_convertvector(v, bf2_t); return __builtin_bit_cast(unsigned, r); }
; DI float bf_lo(unsigned u) { return __uint_as_float(u << 16); }
; DI float bf_hi(unsigned u) { return __uint_as_float(u & 0xffff0000u); }
; template <int PM> DI void attn_phase(const Params& p, int l, char* smem, int* s_item, int wv, int cidx) {
;     ...
;       {
;         const char* gl = gate_s + (w * 32 + l31) * 264 + 8 * h;
;         u16* op = p.O + (size_t)Rq * DM + mixer * 512 + head * 128 + 4 * h;
;         const float* sg = sg_s + 4 * h;
; #pragma unroll
;         for (int db = 0; db < 4; ++db)
; #pragma unroll
;           for (int g = 0; g < 4; ++g) {
;             const int d = db * 32 + 8 * g;
;             f32x4 sv = {1.f, 1.f, 1.f, 1.f};
;             if (mixer == 0) sv = *(const f32x4*)(sg + d);
;             const u32x2 gv = *(const u32x2*)(gl + d * 2);
;             u32x2 o;
;             o[0] = pack2(ov[db][4 * g + 0] * rr * sv[0] * bf_lo(gv[0]), ov[db][4 * g + 1] * rr * sv[1] * bf_hi(gv[0]));
;             o[1] = pack2(ov[db][4 * g + 2] * rr * sv[2] * bf_lo(gv[1]), ov[db][4 * g + 3] * rr * sv[3] * bf_hi(gv[1]));
;             *(u32x2*)(op + d) = o;
;           }
.LBB0_529:
	s_waitcnt lgkmcnt(0)
	v_mov_b64_e32 v[172:173], v[16:17]
	v_mul_f32_e32 v106, v106, v170
	v_mul_f32_e32 v107, v107, v170
	v_mul_f32_e32 v104, v104, v170
	v_mul_f32_e32 v105, v105, v170
	s_waitcnt lgkmcnt(0)
	v_mul_f32_e32 v92, v106, v92
	v_mul_f32_e32 v93, v107, v93
	v_mul_f32_e32 v94, v104, v94
	v_mul_f32_e32 v95, v105, v95
	s_waitcnt lgkmcnt(0)
	v_lshlrev_b32_e32 v106, 16, v172
	v_and_b32_e32 v107, 0xffff0000, v172
	v_lshlrev_b32_e32 v104, 16, v173
	v_and_b32_e32 v105, 0xffff0000, v173
	v_mul_f32_e32 v92, v92, v106
	v_mul_f32_e32 v93, v93, v107
	v_mul_f32_e32 v94, v94, v104
	v_mul_f32_e32 v95, v95, v105
	v_cvt_pk_bf16_f32 v92, v92, v93
	v_cvt_pk_bf16_f32 v93, v94, v95
	ds_write_b64 v208, v[92:93]
	v_mov_b32_e32 v92, 1.0
	s_and_b64 vcc, exec, s[72:73]
	v_mov_b32_e32 v104, 1.0
	v_mov_b32_e32 v105, 1.0
	v_mov_b32_e32 v106, 1.0
	v_mov_b32_e32 v107, 1.0
	s_cbranch_vccnz .LBB0_531
	ds_read_b128 v[104:107], v245 offset:32
.LBB0_531:
	v_mov_b64_e32 v[94:95], v[18:19]
	v_mov_b32_e32 v171, v170
	v_mul_f32_e32 v112, v112, v170
	v_mul_f32_e32 v113, v113, v171
	s_and_b64 vcc, exec, s[72:73]
	s_waitcnt lgkmcnt(0)
	v_mul_f32_e32 v104, v112, v104
	v_mul_f32_e32 v105, v113, v105
	s_waitcnt lgkmcnt(0)
	v_lshlrev_b32_e32 v112, 16, v94
	v_and_b32_e32 v113, 0xffff0000, v94
	v_mul_f32_e32 v104, v104, v112
	v_mul_f32_e32 v105, v105, v113
	v_mov_b32_e32 v93, 1.0
	v_cvt_pk_bf16_f32 v94, v104, v105
	v_mul_f32_e32 v104, v108, v170
	v_mul_f32_e32 v105, v109, v171
	s_nop 0
	v_mul_f32_e32 v104, v104, v106
	v_mul_f32_e32 v105, v105, v107
	v_lshlrev_b32_e32 v106, 16, v95
	v_and_b32_e32 v107, 0xffff0000, v95
	v_mul_f32_e32 v104, v104, v106
	v_mul_f32_e32 v105, v105, v107
	s_nop 0
	v_cvt_pk_bf16_f32 v95, v104, v105
	ds_write_b64 v208, v[94:95] offset:16
	v_mov_b32_e32 v94, 1.0
	v_mov_b32_e32 v95, 1.0
	s_cbranch_vccnz .LBB0_533
	ds_read_b128 v[92:95], v245 offset:64
.LBB0_533:
	v_mov_b64_e32 v[104:105], v[20:21]
	v_mul_f32_e32 v106, v110, v170
	v_mul_f32_e32 v107, v111, v171
	v_mul_f32_e32 v14, v14, v170
	v_mul_f32_e32 v15, v15, v171
	s_waitcnt lgkmcnt(0)
	v_mul_f32_e32 v92, v106, v92
	v_mul_f32_e32 v93, v107, v93
	v_mul_f32_e32 v14, v14, v94
	v_mul_f32_e32 v15, v15, v95
	s_waitcnt lgkmcnt(0)
	v_lshlrev_b32_e32 v106, 16, v104
	v_and_b32_e32 v107, 0xffff0000, v104
	v_lshlrev_b32_e32 v94, 16, v105
	v_and_b32_e32 v95, 0xffff0000, v105
	v_mul_f32_e32 v92, v92, v106
	v_mul_f32_e32 v93, v93, v107
	v_mul_f32_e32 v14, v14, v94
	v_mul_f32_e32 v15, v15, v95
	v_cvt_pk_bf16_f32 v92, v92, v93
	v_cvt_pk_bf16_f32 v93, v14, v15
	ds_write_b64 v208, v[92:93] offset:32
	v_mov_b32_e32 v92, 1.0
	s_and_b64 vcc, exec, s[72:73]
	v_mov_b32_e32 v104, 1.0
	v_mov_b32_e32 v105, 1.0
	v_mov_b32_e32 v106, 1.0
	v_mov_b32_e32 v107, 1.0
	s_cbranch_vccnz .LBB0_535
	ds_read_b128 v[104:107], v245 offset:96
.LBB0_535:
	v_mov_b64_e32 v[14:15], v[22:23]
	v_mul_f32_e32 v94, v114, v170
	v_mul_f32_e32 v95, v115, v171
	v_mul_f32_e32 v108, v116, v170
	v_mul_f32_e32 v109, v117, v171
	s_waitcnt lgkmcnt(0)
	v_mul_f32_e32 v94, v94, v104
	v_mul_f32_e32 v95, v95, v105
	s_and_b64 vcc, exec, s[72:73]
	s_waitcnt lgkmcnt(0)
	v_lshlrev_b32_e32 v104, 16, v14
	v_and_b32_e32 v105, 0xffff0000, v14
	v_mul_f32_e32 v94, v94, v104
	v_mul_f32_e32 v95, v95, v105
	v_lshlrev_b32_e32 v104, 16, v15
	v_cvt_pk_bf16_f32 v14, v94, v95
	v_mul_f32_e32 v94, v108, v106
	v_mul_f32_e32 v95, v109, v107
	v_and_b32_e32 v105, 0xffff0000, v15
	v_mul_f32_e32 v94, v94, v104
	v_mul_f32_e32 v95, v95, v105
	v_mov_b32_e32 v93, 1.0
	v_cvt_pk_bf16_f32 v15, v94, v95
	v_mov_b32_e32 v94, 1.0
	v_mov_b32_e32 v95, 1.0
	ds_write_b64 v208, v[14:15] offset:48
	s_cbranch_vccnz .LBB0_537
	ds_read_b128 v[92:95], v245 offset:128
.LBB0_537:
	v_mov_b64_e32 v[14:15], v[24:25]
	v_mul_f32_e32 v104, v132, v170
	v_mul_f32_e32 v105, v133, v171
	v_mul_f32_e32 v106, v128, v170
	v_mul_f32_e32 v107, v129, v171
	s_waitcnt lgkmcnt(0)
	v_mul_f32_e32 v92, v104, v92
	v_mul_f32_e32 v93, v105, v93
	s_and_b64 vcc, exec, s[72:73]
	s_waitcnt lgkmcnt(0)
	v_lshlrev_b32_e32 v104, 16, v14
	v_and_b32_e32 v105, 0xffff0000, v14
	v_mul_f32_e32 v92, v92, v104
	v_mul_f32_e32 v93, v93, v105
	v_mov_b32_e32 v104, 1.0
	v_cvt_pk_bf16_f32 v14, v92, v93
	v_mul_f32_e32 v92, v106, v94
	v_mul_f32_e32 v93, v107, v95
	v_lshlrev_b32_e32 v94, 16, v15
	v_and_b32_e32 v95, 0xffff0000, v15
	v_mul_f32_e32 v92, v92, v94
	v_mul_f32_e32 v93, v93, v95
	v_mov_b32_e32 v105, 1.0
	v_cvt_pk_bf16_f32 v15, v92, v93
	v_mov_b32_e32 v92, 1.0
	v_mov_b32_e32 v106, 1.0
	v_mov_b32_e32 v107, 1.0
	ds_write_b64 v208, v[14:15] offset:64
	s_cbranch_vccnz .LBB0_539
	ds_read_b128 v[104:107], v245 offset:160
.LBB0_539:
	v_mov_b64_e32 v[14:15], v[26:27]
	v_mul_f32_e32 v94, v124, v170
	v_mul_f32_e32 v95, v125, v171
	v_mul_f32_e32 v108, v122, v170
	v_mul_f32_e32 v109, v123, v171
	s_waitcnt lgkmcnt(0)
	v_mul_f32_e32 v94, v94, v104
	v_mul_f32_e32 v95, v95, v105
	s_and_b64 vcc, exec, s[72:73]
	s_waitcnt lgkmcnt(0)
	v_lshlrev_b32_e32 v104, 16, v14
	v_and_b32_e32 v105, 0xffff0000, v14
	v_mul_f32_e32 v94, v94, v104
	v_mul_f32_e32 v95, v95, v105
	v_lshlrev_b32_e32 v104, 16, v15
	v_cvt_pk_bf16_f32 v14, v94, v95
	v_mul_f32_e32 v94, v108, v106
	v_mul_f32_e32 v95, v109, v107
	v_and_b32_e32 v105, 0xffff0000, v15
	v_mul_f32_e32 v94, v94, v104
	v_mul_f32_e32 v95, v95, v105
	v_mov_b32_e32 v93, 1.0
	v_cvt_pk_bf16_f32 v15, v94, v95
	v_mov_b32_e32 v94, 1.0
	v_mov_b32_e32 v95, 1.0
	ds_write_b64 v208, v[14:15] offset:80
	s_cbranch_vccnz .LBB0_541
	ds_read_b128 v[92:95], v245 offset:192
; DI unsigned pack2(float a, float b) { f2_t v = {a, b}; bf2_t r = __builtin_convertvector(v, bf2_t); return __builtin_bit_cast(unsigned, r); }
; DI float bf_lo(unsigned u) { return __uint_as_float(u << 16); }
; DI float bf_hi(unsigned u) { return __uint_as_float(u & 0xffff0000u); }
; template <int PM> DI void attn_phase(const Params& p, int l, char* smem, int* s_item, int wv, int cidx) {
;     ...
;       {
;         const char* gl = gate_s + (w * 32 + l31) * 264 + 8 * h;
;         u16* op = p.O + (size_t)Rq * DM + mixer * 512 + head * 128 + 4 * h;
;         const float* sg = sg_s + 4 * h;
; #pragma unroll
;         for (int db = 0; db < 4; ++db)
; #pragma unroll
;           for (int g = 0; g < 4; ++g) {
;             const int d = db * 32 + 8 * g;
;             f32x4 sv = {1.f, 1.f, 1.f, 1.f};
;             if (mixer == 0) sv = *(const f32x4*)(sg + d);
;             const u32x2 gv = *(const u32x2*)(gl + d * 2);
;             u32x2 o;
;             o[0] = pack2(ov[db][4 * g + 0] * rr * sv[0] * bf_lo(gv[0]), ov[db][4 * g + 1] * rr * sv[1] * bf_hi(gv[0]));
;             o[1] = pack2(ov[db][4 * g + 2] * rr * sv[2] * bf_lo(gv[1]), ov[db][4 * g + 3] * rr * sv[3] * bf_hi(gv[1]));
;             *(u32x2*)(op + d) = o;
;           }
.LBB0_541:
	v_mov_b64_e32 v[14:15], v[28:29]
	v_mul_f32_e32 v104, v120, v170
	v_mul_f32_e32 v105, v121, v171
	v_mul_f32_e32 v106, v118, v170
	v_mul_f32_e32 v107, v119, v171
	s_waitcnt lgkmcnt(0)
	v_mul_f32_e32 v92, v104, v92
	v_mul_f32_e32 v93, v105, v93
	s_and_b64 vcc, exec, s[72:73]
	s_waitcnt lgkmcnt(0)
	v_lshlrev_b32_e32 v104, 16, v14
	v_and_b32_e32 v105, 0xffff0000, v14
	v_mul_f32_e32 v92, v92, v104
	v_mul_f32_e32 v93, v93, v105
	v_mov_b32_e32 v104, 1.0
	v_cvt_pk_bf16_f32 v14, v92, v93
	v_mul_f32_e32 v92, v106, v94
	v_mul_f32_e32 v93, v107, v95
	v_lshlrev_b32_e32 v94, 16, v15
	v_and_b32_e32 v95, 0xffff0000, v15
	v_mul_f32_e32 v92, v92, v94
	v_mul_f32_e32 v93, v93, v95
	v_mov_b32_e32 v105, 1.0
	v_cvt_pk_bf16_f32 v15, v92, v93
	v_mov_b32_e32 v92, 1.0
	v_mov_b32_e32 v106, 1.0
	v_mov_b32_e32 v107, 1.0
	ds_write_b64 v208, v[14:15] offset:96
	s_cbranch_vccnz .LBB0_543
	ds_read_b128 v[104:107], v245 offset:224
.LBB0_543:
	v_mov_b64_e32 v[14:15], v[30:31]
	v_mul_f32_e32 v94, v126, v170
	v_mul_f32_e32 v95, v127, v171
	v_mul_f32_e32 v108, v130, v170
	v_mul_f32_e32 v109, v131, v171
	s_waitcnt lgkmcnt(0)
	v_mul_f32_e32 v94, v94, v104
	v_mul_f32_e32 v95, v95, v105
	s_and_b64 vcc, exec, s[72:73]
	s_waitcnt lgkmcnt(0)
	v_lshlrev_b32_e32 v104, 16, v14
	v_and_b32_e32 v105, 0xffff0000, v14
	v_mul_f32_e32 v94, v94, v104
	v_mul_f32_e32 v95, v95, v105
	v_lshlrev_b32_e32 v104, 16, v15
	v_cvt_pk_bf16_f32 v14, v94, v95
	v_mul_f32_e32 v94, v108, v106
	v_mul_f32_e32 v95, v109, v107
	v_and_b32_e32 v105, 0xffff0000, v15
	v_mul_f32_e32 v94, v94, v104
	v_mul_f32_e32 v95, v95, v105
	v_mov_b32_e32 v93, 1.0
	v_cvt_pk_bf16_f32 v15, v94, v95
	v_mov_b32_e32 v94, 1.0
	v_mov_b32_e32 v95, 1.0
	ds_write_b64 v208, v[14:15] offset:112
	s_cbranch_vccnz .LBB0_545
	ds_read_b128 v[92:95], v245 offset:256
.LBB0_545:
	v_mov_b64_e32 v[14:15], v[32:33]
	v_mul_f32_e32 v104, v152, v170
	v_mul_f32_e32 v105, v153, v171
	v_mul_f32_e32 v106, v148, v170
	v_mul_f32_e32 v107, v149, v171
	s_waitcnt lgkmcnt(0)
	v_mul_f32_e32 v92, v104, v92
	v_mul_f32_e32 v93, v105, v93
	s_and_b64 vcc, exec, s[72:73]
	s_waitcnt lgkmcnt(0)
	v_lshlrev_b32_e32 v104, 16, v14
	v_and_b32_e32 v105, 0xffff0000, v14
	v_mul_f32_e32 v92, v92, v104
	v_mul_f32_e32 v93, v93, v105
	v_mov_b32_e32 v104, 1.0
	v_cvt_pk_bf16_f32 v14, v92, v93
	v_mul_f32_e32 v92, v106, v94
	v_mul_f32_e32 v93, v107, v95
	v_lshlrev_b32_e32 v94, 16, v15
	v_and_b32_e32 v95, 0xffff0000, v15
	v_mul_f32_e32 v92, v92, v94
	v_mul_f32_e32 v93, v93, v95
	v_mov_b32_e32 v105, 1.0
	v_cvt_pk_bf16_f32 v15, v92, v93
	v_mov_b32_e32 v92, 1.0
	v_mov_b32_e32 v106, 1.0
	v_mov_b32_e32 v107, 1.0
	ds_write_b64 v208, v[14:15] offset:128
	s_cbranch_vccnz .LBB0_547
	ds_read_b128 v[104:107], v245 offset:288
.LBB0_547:
	v_mov_b64_e32 v[14:15], v[34:35]
	v_mul_f32_e32 v94, v140, v170
	v_mul_f32_e32 v95, v141, v171
	v_mul_f32_e32 v108, v138, v170
	v_mul_f32_e32 v109, v139, v171
	s_waitcnt lgkmcnt(0)
	v_mul_f32_e32 v94, v94, v104
	v_mul_f32_e32 v95, v95, v105
	s_and_b64 vcc, exec, s[72:73]
	s_waitcnt lgkmcnt(0)
	v_lshlrev_b32_e32 v104, 16, v14
	v_and_b32_e32 v105, 0xffff0000, v14
	v_mul_f32_e32 v94, v94, v104
	v_mul_f32_e32 v95, v95, v105
	v_lshlrev_b32_e32 v104, 16, v15
	v_cvt_pk_bf16_f32 v14, v94, v95
	v_mul_f32_e32 v94, v108, v106
	v_mul_f32_e32 v95, v109, v107
	v_and_b32_e32 v105, 0xffff0000, v15
	v_mul_f32_e32 v94, v94, v104
	v_mul_f32_e32 v95, v95, v105
	v_mov_b32_e32 v93, 1.0
	v_cvt_pk_bf16_f32 v15, v94, v95
	v_mov_b32_e32 v94, 1.0
	v_mov_b32_e32 v95, 1.0
	ds_write_b64 v208, v[14:15] offset:144
	s_cbranch_vccnz .LBB0_549
	ds_read_b128 v[92:95], v245 offset:320
.LBB0_549:
	v_mov_b64_e32 v[14:15], v[36:37]
	v_mul_f32_e32 v104, v136, v170
	v_mul_f32_e32 v105, v137, v171
	v_mul_f32_e32 v106, v134, v170
	v_mul_f32_e32 v107, v135, v171
	s_waitcnt lgkmcnt(0)
	v_mul_f32_e32 v92, v104, v92
	v_mul_f32_e32 v93, v105, v93
	s_and_b64 vcc, exec, s[72:73]
	s_waitcnt lgkmcnt(0)
	v_lshlrev_b32_e32 v104, 16, v14
	v_and_b32_e32 v105, 0xffff0000, v14
	v_mul_f32_e32 v92, v92, v104
	v_mul_f32_e32 v93, v93, v105
	v_mov_b32_e32 v104, 1.0
	v_cvt_pk_bf16_f32 v14, v92, v93
	v_mul_f32_e32 v92, v106, v94
	v_mul_f32_e32 v93, v107, v95
	v_lshlrev_b32_e32 v94, 16, v15
	v_and_b32_e32 v95, 0xffff0000, v15
	v_mul_f32_e32 v92, v92, v94
	v_mul_f32_e32 v93, v93, v95
	v_mov_b32_e32 v105, 1.0
	v_cvt_pk_bf16_f32 v15, v92, v93
	v_mov_b32_e32 v92, 1.0
	v_mov_b32_e32 v106, 1.0
	v_mov_b32_e32 v107, 1.0
	ds_write_b64 v208, v[14:15] offset:160
	s_cbranch_vccnz .LBB0_551
	ds_read_b128 v[104:107], v245 offset:352
.LBB0_551:
	v_mov_b64_e32 v[14:15], v[38:39]
	v_mul_f32_e32 v94, v142, v170
	v_mul_f32_e32 v95, v143, v171
	v_mul_f32_e32 v108, v150, v170
	v_mul_f32_e32 v109, v151, v171
	s_waitcnt lgkmcnt(0)
	v_mul_f32_e32 v94, v94, v104
	v_mul_f32_e32 v95, v95, v105
	s_and_b64 vcc, exec, s[72:73]
	s_waitcnt lgkmcnt(0)
	v_lshlrev_b32_e32 v104, 16, v14
	v_and_b32_e32 v105, 0xffff0000, v14
	v_mul_f32_e32 v94, v94, v104
	v_mul_f32_e32 v95, v95, v105
	v_lshlrev_b32_e32 v104, 16, v15
	v_cvt_pk_bf16_f32 v14, v94, v95
	v_mul_f32_e32 v94, v108, v106
	v_mul_f32_e32 v95, v109, v107
	v_and_b32_e32 v105, 0xffff0000, v15
	v_mul_f32_e32 v94, v94, v104
	v_mul_f32_e32 v95, v95, v105
	v_mov_b32_e32 v93, 1.0
	v_cvt_pk_bf16_f32 v15, v94, v95
	v_mov_b32_e32 v94, 1.0
	v_mov_b32_e32 v95, 1.0
	ds_write_b64 v208, v[14:15] offset:176
	s_cbranch_vccnz .LBB0_553
	ds_read_b128 v[92:95], v245 offset:384
; DI unsigned pack2(float a, float b) { f2_t v = {a, b}; bf2_t r = __builtin_convertvector(v, bf2_t); return __builtin_bit_cast(unsigned, r); }
; DI float bf_lo(unsigned u) { return __uint_as_float(u << 16); }
; DI float bf_hi(unsigned u) { return __uint_as_float(u & 0xffff0000u); }
; template <int PM> DI void attn_phase(const Params& p, int l, char* smem, int* s_item, int wv, int cidx) {
;     ...
;       {
;         const char* gl = gate_s + (w * 32 + l31) * 264 + 8 * h;
;         u16* op = p.O + (size_t)Rq * DM + mixer * 512 + head * 128 + 4 * h;
;         const float* sg = sg_s + 4 * h;
; #pragma unroll
;         for (int db = 0; db < 4; ++db)
; #pragma unroll
;           for (int g = 0; g < 4; ++g) {
;             const int d = db * 32 + 8 * g;
;             f32x4 sv = {1.f, 1.f, 1.f, 1.f};
;             if (mixer == 0) sv = *(const f32x4*)(sg + d);
;             const u32x2 gv = *(const u32x2*)(gl + d * 2);
;             u32x2 o;
;             o[0] = pack2(ov[db][4 * g + 0] * rr * sv[0] * bf_lo(gv[0]), ov[db][4 * g + 1] * rr * sv[1] * bf_hi(gv[0]));
;             o[1] = pack2(ov[db][4 * g + 2] * rr * sv[2] * bf_lo(gv[1]), ov[db][4 * g + 3] * rr * sv[3] * bf_hi(gv[1]));
;             *(u32x2*)(op + d) = o;
;           }
.LBB0_553:
	v_mov_b64_e32 v[14:15], v[40:41]
	v_mul_f32_e32 v104, v168, v170
	v_mul_f32_e32 v105, v169, v171
	v_mul_f32_e32 v106, v164, v170
	v_mul_f32_e32 v107, v165, v171
	s_waitcnt lgkmcnt(0)
	v_mul_f32_e32 v92, v104, v92
	v_mul_f32_e32 v93, v105, v93
	s_and_b64 vcc, exec, s[72:73]
	s_waitcnt lgkmcnt(0)
	v_lshlrev_b32_e32 v104, 16, v14
	v_and_b32_e32 v105, 0xffff0000, v14
	v_mul_f32_e32 v92, v92, v104
	v_mul_f32_e32 v93, v93, v105
	v_mov_b32_e32 v104, 1.0
	v_cvt_pk_bf16_f32 v14, v92, v93
	v_mul_f32_e32 v92, v106, v94
	v_mul_f32_e32 v93, v107, v95
	v_lshlrev_b32_e32 v94, 16, v15
	v_and_b32_e32 v95, 0xffff0000, v15
	v_mul_f32_e32 v92, v92, v94
	v_mul_f32_e32 v93, v93, v95
	v_mov_b32_e32 v105, 1.0
	v_cvt_pk_bf16_f32 v15, v92, v93
	v_mov_b32_e32 v92, 1.0
	v_mov_b32_e32 v106, 1.0
	v_mov_b32_e32 v107, 1.0
	ds_write_b64 v208, v[14:15] offset:192
	s_cbranch_vccnz .LBB0_555
	ds_read_b128 v[104:107], v245 offset:416
.LBB0_555:
	v_mov_b64_e32 v[14:15], v[42:43]
	v_mul_f32_e32 v94, v160, v170
	v_mul_f32_e32 v95, v161, v171
	v_mul_f32_e32 v108, v158, v170
	v_mul_f32_e32 v109, v159, v171
	s_waitcnt lgkmcnt(0)
	v_mul_f32_e32 v94, v94, v104
	v_mul_f32_e32 v95, v95, v105
	s_and_b64 vcc, exec, s[72:73]
	s_waitcnt lgkmcnt(0)
	v_lshlrev_b32_e32 v104, 16, v14
	v_and_b32_e32 v105, 0xffff0000, v14
	v_mul_f32_e32 v94, v94, v104
	v_mul_f32_e32 v95, v95, v105
	v_lshlrev_b32_e32 v104, 16, v15
	v_cvt_pk_bf16_f32 v14, v94, v95
	v_mul_f32_e32 v94, v108, v106
	v_mul_f32_e32 v95, v109, v107
	v_and_b32_e32 v105, 0xffff0000, v15
	v_mul_f32_e32 v94, v94, v104
	v_mul_f32_e32 v95, v95, v105
	v_mov_b32_e32 v93, 1.0
	v_cvt_pk_bf16_f32 v15, v94, v95
	v_mov_b32_e32 v94, 1.0
	v_mov_b32_e32 v95, 1.0
	ds_write_b64 v208, v[14:15] offset:208
	s_cbranch_vccnz .LBB0_557
	ds_read_b128 v[92:95], v245 offset:448
.LBB0_557:
	v_mov_b64_e32 v[14:15], v[44:45]
	v_mul_f32_e32 v104, v156, v170
	v_mul_f32_e32 v105, v157, v171
	v_mul_f32_e32 v106, v154, v170
	v_mul_f32_e32 v107, v155, v171
	s_waitcnt lgkmcnt(0)
	v_mul_f32_e32 v92, v104, v92
	v_mul_f32_e32 v93, v105, v93
	s_and_b64 vcc, exec, s[72:73]
	s_waitcnt lgkmcnt(0)
	v_lshlrev_b32_e32 v104, 16, v14
	v_and_b32_e32 v105, 0xffff0000, v14
	v_mul_f32_e32 v92, v92, v104
	v_mul_f32_e32 v93, v93, v105
	s_nop 0
	v_cvt_pk_bf16_f32 v14, v92, v93
	v_mul_f32_e32 v92, v106, v94
	v_mul_f32_e32 v93, v107, v95
	v_lshlrev_b32_e32 v94, 16, v15
	v_and_b32_e32 v95, 0xffff0000, v15
	v_mul_f32_e32 v92, v92, v94
	v_mul_f32_e32 v93, v93, v95
	v_mov_b32_e32 v94, 1.0
	v_cvt_pk_bf16_f32 v15, v92, v93
	v_mov_b32_e32 v92, 1.0
	v_mov_b32_e32 v93, 1.0
	v_mov_b32_e32 v95, 1.0
	ds_write_b64 v208, v[14:15] offset:224
	s_cbranch_vccnz .LBB0_559
	ds_read_b128 v[92:95], v245 offset:480
.LBB0_559:
	v_mov_b64_e32 v[14:15], v[46:47]
	v_mul_f32_e32 v104, v162, v170
	v_mul_f32_e32 v105, v163, v171
	v_mul_f32_e32 v106, v166, v170
	v_mul_f32_e32 v107, v167, v171
	s_waitcnt lgkmcnt(0)
	v_mul_f32_e32 v92, v104, v92
	v_mul_f32_e32 v93, v105, v93
	s_waitcnt lgkmcnt(0)
	v_lshlrev_b32_e32 v104, 16, v14
	v_and_b32_e32 v105, 0xffff0000, v14
	v_mul_f32_e32 v92, v92, v104
	v_mul_f32_e32 v93, v93, v105
	s_nop 0
	v_cvt_pk_bf16_f32 v14, v92, v93
	v_mul_f32_e32 v92, v106, v94
	v_mul_f32_e32 v93, v107, v95
	v_lshlrev_b32_e32 v94, 16, v15
	v_and_b32_e32 v95, 0xffff0000, v15
	v_mul_f32_e32 v92, v92, v94
	v_mul_f32_e32 v93, v93, v95
	s_nop 0
	v_cvt_pk_bf16_f32 v15, v92, v93
	ds_write_b64 v208, v[14:15] offset:240
	v_lshrrev_b32_e32 v212, 4, v240
	v_lshrrev_b32_e32 v213, 1, v198
	v_add_u32_e32 v212, v212, v213
	v_and_b32_e32 v213, 15, v240
	v_mul_u32_u24_e32 v209, 0x110, v212
	v_lshl_add_u32 v209, v213, 4, v209
	v_add_u32_e32 v209, s0, v209
	v_sub_u32_e32 v212, v212, v240
	v_lshlrev_b32_e32 v212, 12, v212
	v_lshl_add_u32 v212, v213, 4, v212
	v_lshlrev_b32_e32 v213, 1, v198
	v_sub_u32_e32 v212, v212, v213
	v_ashrrev_i32_e32 v213, 31, v212
	v_lshl_add_u64 v[210:211], v[212:213], 0, v[226:227]
	s_mov_b64 s[0:1], 0x4000
	s_waitcnt lgkmcnt(0)
	ds_read_b128 v[16:19], v209
	ds_read_b128 v[20:23], v209 offset:1088
	ds_read_b128 v[24:27], v209 offset:2176
	ds_read_b128 v[28:31], v209 offset:3264
	ds_read_b128 v[32:35], v209 offset:4352
	ds_read_b128 v[36:39], v209 offset:5440
	ds_read_b128 v[40:43], v209 offset:6528
	ds_read_b128 v[44:47], v209 offset:7616
	s_waitcnt lgkmcnt(7)
	global_store_dwordx4 v[210:211], v[16:19], off
	s_nop 1
	v_lshl_add_u64 v[210:211], v[210:211], 0, s[0:1]
	s_waitcnt lgkmcnt(6)
	global_store_dwordx4 v[210:211], v[20:23], off
	s_nop 1
	v_lshl_add_u64 v[210:211], v[210:211], 0, s[0:1]
	s_waitcnt lgkmcnt(5)
	global_store_dwordx4 v[210:211], v[24:27], off
	s_nop 1
	v_lshl_add_u64 v[210:211], v[210:211], 0, s[0:1]
	s_waitcnt lgkmcnt(4)
	global_store_dwordx4 v[210:211], v[28:31], off
	s_nop 1
	v_lshl_add_u64 v[210:211], v[210:211], 0, s[0:1]
	s_waitcnt lgkmcnt(3)
	global_store_dwordx4 v[210:211], v[32:35], off
	s_nop 1
	v_lshl_add_u64 v[210:211], v[210:211], 0, s[0:1]
	s_waitcnt lgkmcnt(2)
	global_store_dwordx4 v[210:211], v[36:39], off
	s_nop 1
	v_lshl_add_u64 v[210:211], v[210:211], 0, s[0:1]
	s_waitcnt lgkmcnt(1)
	global_store_dwordx4 v[210:211], v[40:43], off
	s_nop 1
	v_lshl_add_u64 v[210:211], v[210:211], 0, s[0:1]
	s_waitcnt lgkmcnt(0)
	global_store_dwordx4 v[210:211], v[44:47], off
	s_branch .LBB0_408

; DI void phase0(const Params& p, char* smem, int wv) {
;     ...
;     for (int k = 0; k < 128; ++k) {
;       const f32x4 wvv = *(const f32x4*)(wp + (size_t)k * 6144);
;       a0 += sf[k] * wvv; a1 += sf[128 + k] * wvv; a2 += sf[256 + k] * wvv; a3 += sf[384 + k] * wvv; a4 += sf[512 + k] * wvv;
;     }
.LBB0_578:
	v_lshl_add_u64 v[36:37], v[32:33], 0, s[2:3]
	s_mov_b64 s[6:7], 0x6000
	global_load_dwordx4 v[68:71], v[36:37], off
	v_lshl_add_u64 v[36:37], v[36:37], 0, s[6:7]
	global_load_dwordx4 v[72:75], v[36:37], off
	v_lshl_add_u64 v[36:37], v[36:37], 0, s[6:7]
	global_load_dwordx4 v[76:79], v[36:37], off
	v_lshl_add_u64 v[36:37], v[36:37], 0, s[6:7]
	global_load_dwordx4 v[80:83], v[36:37], off
	v_lshl_add_u64 v[36:37], v[36:37], 0, s[6:7]
	global_load_dwordx4 v[84:87], v[36:37], off
	v_lshl_add_u64 v[36:37], v[36:37], 0, s[6:7]
	global_load_dwordx4 v[88:91], v[36:37], off
	v_lshl_add_u64 v[36:37], v[36:37], 0, s[6:7]
	global_load_dwordx4 v[92:95], v[36:37], off
	v_lshl_add_u64 v[36:37], v[36:37], 0, s[6:7]
	global_load_dwordx4 v[96:99], v[36:37], off
	v_lshl_add_u64 v[36:37], v[36:37], 0, s[6:7]
	global_load_dwordx4 v[100:103], v[36:37], off
	v_lshl_add_u64 v[36:37], v[36:37], 0, s[6:7]
	global_load_dwordx4 v[104:107], v[36:37], off
	v_lshl_add_u64 v[36:37], v[36:37], 0, s[6:7]
	global_load_dwordx4 v[108:111], v[36:37], off
	v_lshl_add_u64 v[36:37], v[36:37], 0, s[6:7]
	global_load_dwordx4 v[112:115], v[36:37], off
	v_lshl_add_u64 v[36:37], v[36:37], 0, s[6:7]
	global_load_dwordx4 v[116:119], v[36:37], off
	v_lshl_add_u64 v[36:37], v[36:37], 0, s[6:7]
	global_load_dwordx4 v[120:123], v[36:37], off
	v_lshl_add_u64 v[36:37], v[36:37], 0, s[6:7]
	global_load_dwordx4 v[124:127], v[36:37], off
	v_lshl_add_u64 v[36:37], v[36:37], 0, s[6:7]
	global_load_dwordx4 v[128:131], v[36:37], off
	v_mov_b32_e32 v39, s1
	ds_read_b128 v[132:135], v39
	ds_read_b128 v[136:139], v39 offset:16
	ds_read_b128 v[140:143], v39 offset:32
	ds_read_b128 v[144:147], v39 offset:48
	ds_read_b128 v[148:151], v39 offset:512
	ds_read_b128 v[152:155], v39 offset:528
	ds_read_b128 v[156:159], v39 offset:544
	ds_read_b128 v[160:163], v39 offset:560
	ds_read_b128 v[164:167], v39 offset:1024
	ds_read_b128 v[168:171], v39 offset:1040
	ds_read_b128 v[172:175], v39 offset:1056
	ds_read_b128 v[176:179], v39 offset:1072
	ds_read_b128 v[180:183], v39 offset:1536
	ds_read_b128 v[184:187], v39 offset:1552
	ds_read_b128 v[188:191], v39 offset:1568
	ds_read_b128 v[192:195], v39 offset:1584
	ds_read_b128 v[196:199], v39 offset:2048
	ds_read_b128 v[200:203], v39 offset:2064
	ds_read_b128 v[204:207], v39 offset:2080
	ds_read_b128 v[208:211], v39 offset:2096
	s_add_u32 s2, s2, 0x60000
	s_addc_u32 s3, s3, 0
	s_add_i32 s1, s1, 64
	s_cmp_eq_u32 s2, 0x300000
	s_waitcnt lgkmcnt(0)
	s_waitcnt vmcnt(15)
	v_fma_f32 v14, v68, v132, v14
	v_fma_f32 v15, v69, v132, v15
	v_fma_f32 v16, v70, v132, v16
	v_fma_f32 v17, v71, v132, v17
	v_fma_f32 v18, v68, v148, v18
	v_fma_f32 v19, v69, v148, v19
	v_fma_f32 v20, v70, v148, v20
	v_fma_f32 v21, v71, v148, v21
	v_fma_f32 v10, v68, v164, v10
	v_fma_f32 v11, v69, v164, v11
	v_fma_f32 v12, v70, v164, v12
	v_fma_f32 v13, v71, v164, v13
	v_fma_f32 v6, v68, v180, v6
	v_fma_f32 v7, v69, v180, v7
	v_fma_f32 v8, v70, v180, v8
	v_fma_f32 v9, v71, v180, v9
	v_fma_f32 v2, v68, v196, v2
	v_fma_f32 v3, v69, v196, v3
	v_fma_f32 v4, v70, v196, v4
	v_fma_f32 v5, v71, v196, v5
	s_waitcnt vmcnt(14)
	v_fma_f32 v14, v72, v133, v14
	v_fma_f32 v15, v73, v133, v15
	v_fma_f32 v16, v74, v133, v16
	v_fma_f32 v17, v75, v133, v17
	v_fma_f32 v18, v72, v149, v18
	v_fma_f32 v19, v73, v149, v19
	v_fma_f32 v20, v74, v149, v20
	v_fma_f32 v21, v75, v149, v21
	v_fma_f32 v10, v72, v165, v10
	v_fma_f32 v11, v73, v165, v11
	v_fma_f32 v12, v74, v165, v12
	v_fma_f32 v13, v75, v165, v13
	v_fma_f32 v6, v72, v181, v6
	v_fma_f32 v7, v73, v181, v7
	v_fma_f32 v8, v74, v181, v8
	v_fma_f32 v9, v75, v181, v9
	v_fma_f32 v2, v72, v197, v2
	v_fma_f32 v3, v73, v197, v3
	v_fma_f32 v4, v74, v197, v4
	v_fma_f32 v5, v75, v197, v5
	s_waitcnt vmcnt(13)
	v_fma_f32 v14, v76, v134, v14
	v_fma_f32 v15, v77, v134, v15
	v_fma_f32 v16, v78, v134, v16
	v_fma_f32 v17, v79, v134, v17
	v_fma_f32 v18, v76, v150, v18
	v_fma_f32 v19, v77, v150, v19
	v_fma_f32 v20, v78, v150, v20
	v_fma_f32 v21, v79, v150, v21
	v_fma_f32 v10, v76, v166, v10
	v_fma_f32 v11, v77, v166, v11
	v_fma_f32 v12, v78, v166, v12
	v_fma_f32 v13, v79, v166, v13
	v_fma_f32 v6, v76, v182, v6
	v_fma_f32 v7, v77, v182, v7
	v_fma_f32 v8, v78, v182, v8
	v_fma_f32 v9, v79, v182, v9
	v_fma_f32 v2, v76, v198, v2
	v_fma_f32 v3, v77, v198, v3
	v_fma_f32 v4, v78, v198, v4
	v_fma_f32 v5, v79, v198, v5
	s_waitcnt vmcnt(12)
	v_fma_f32 v14, v80, v135, v14
	v_fma_f32 v15, v81, v135, v15
	v_fma_f32 v16, v82, v135, v16
	v_fma_f32 v17, v83, v135, v17
	v_fma_f32 v18, v80, v151, v18
	v_fma_f32 v19, v81, v151, v19
	v_fma_f32 v20, v82, v151, v20
	v_fma_f32 v21, v83, v151, v21
	v_fma_f32 v10, v80, v167, v10
	v_fma_f32 v11, v81, v167, v11
	v_fma_f32 v12, v82, v167, v12
	v_fma_f32 v13, v83, v167, v13
	v_fma_f32 v6, v80, v183, v6
	v_fma_f32 v7, v81, v183, v7
	v_fma_f32 v8, v82, v183, v8
	v_fma_f32 v9, v83, v183, v9
	v_fma_f32 v2, v80, v199, v2
	v_fma_f32 v3, v81, v199, v3
	v_fma_f32 v4, v82, v199, v4
	v_fma_f32 v5, v83, v199, v5
	s_waitcnt vmcnt(11)
	v_fma_f32 v14, v84, v136, v14
	v_fma_f32 v15, v85, v136, v15
	v_fma_f32 v16, v86, v136, v16
	v_fma_f32 v17, v87, v136, v17
	v_fma_f32 v18, v84, v152, v18
	v_fma_f32 v19, v85, v152, v19
	v_fma_f32 v20, v86, v152, v20
	v_fma_f32 v21, v87, v152, v21
	v_fma_f32 v10, v84, v168, v10
	v_fma_f32 v11, v85, v168, v11
	v_fma_f32 v12, v86, v168, v12
	v_fma_f32 v13, v87, v168, v13
	v_fma_f32 v6, v84, v184, v6
	v_fma_f32 v7, v85, v184, v7
	v_fma_f32 v8, v86, v184, v8
	v_fma_f32 v9, v87, v184, v9
	v_fma_f32 v2, v84, v200, v2
	v_fma_f32 v3, v85, v200, v3
	v_fma_f32 v4, v86, v200, v4
	v_fma_f32 v5, v87, v200, v5
	s_waitcnt vmcnt(10)
; DI void phase0(const Params& p, char* smem, int wv) {
;     ...
;     for (int k = 0; k < 128; ++k) {
;       const f32x4 wvv = *(const f32x4*)(wp + (size_t)k * 6144);
;       a0 += sf[k] * wvv; a1 += sf[128 + k] * wvv; a2 += sf[256 + k] * wvv; a3 += sf[384 + k] * wvv; a4 += sf[512 + k] * wvv;
;     }
	v_fma_f32 v14, v88, v137, v14
	v_fma_f32 v15, v89, v137, v15
	v_fma_f32 v16, v90, v137, v16
	v_fma_f32 v17, v91, v137, v17
	v_fma_f32 v18, v88, v153, v18
	v_fma_f32 v19, v89, v153, v19
	v_fma_f32 v20, v90, v153, v20
	v_fma_f32 v21, v91, v153, v21
	v_fma_f32 v10, v88, v169, v10
	v_fma_f32 v11, v89, v169, v11
	v_fma_f32 v12, v90, v169, v12
	v_fma_f32 v13, v91, v169, v13
	v_fma_f32 v6, v88, v185, v6
	v_fma_f32 v7, v89, v185, v7
	v_fma_f32 v8, v90, v185, v8
	v_fma_f32 v9, v91, v185, v9
	v_fma_f32 v2, v88, v201, v2
	v_fma_f32 v3, v89, v201, v3
	v_fma_f32 v4, v90, v201, v4
	v_fma_f32 v5, v91, v201, v5
	s_waitcnt vmcnt(9)
	v_fma_f32 v14, v92, v138, v14
	v_fma_f32 v15, v93, v138, v15
	v_fma_f32 v16, v94, v138, v16
	v_fma_f32 v17, v95, v138, v17
	v_fma_f32 v18, v92, v154, v18
	v_fma_f32 v19, v93, v154, v19
	v_fma_f32 v20, v94, v154, v20
	v_fma_f32 v21, v95, v154, v21
	v_fma_f32 v10, v92, v170, v10
	v_fma_f32 v11, v93, v170, v11
	v_fma_f32 v12, v94, v170, v12
	v_fma_f32 v13, v95, v170, v13
	v_fma_f32 v6, v92, v186, v6
	v_fma_f32 v7, v93, v186, v7
	v_fma_f32 v8, v94, v186, v8
	v_fma_f32 v9, v95, v186, v9
	v_fma_f32 v2, v92, v202, v2
	v_fma_f32 v3, v93, v202, v3
	v_fma_f32 v4, v94, v202, v4
	v_fma_f32 v5, v95, v202, v5
	s_waitcnt vmcnt(8)
	v_fma_f32 v14, v96, v139, v14
	v_fma_f32 v15, v97, v139, v15
	v_fma_f32 v16, v98, v139, v16
	v_fma_f32 v17, v99, v139, v17
	v_fma_f32 v18, v96, v155, v18
	v_fma_f32 v19, v97, v155, v19
	v_fma_f32 v20, v98, v155, v20
	v_fma_f32 v21, v99, v155, v21
	v_fma_f32 v10, v96, v171, v10
	v_fma_f32 v11, v97, v171, v11
	v_fma_f32 v12, v98, v171, v12
	v_fma_f32 v13, v99, v171, v13
	v_fma_f32 v6, v96, v187, v6
	v_fma_f32 v7, v97, v187, v7
	v_fma_f32 v8, v98, v187, v8
	v_fma_f32 v9, v99, v187, v9
	v_fma_f32 v2, v96, v203, v2
	v_fma_f32 v3, v97, v203, v3
	v_fma_f32 v4, v98, v203, v4
	v_fma_f32 v5, v99, v203, v5
	s_waitcnt vmcnt(7)
	v_fma_f32 v14, v100, v140, v14
	v_fma_f32 v15, v101, v140, v15
	v_fma_f32 v16, v102, v140, v16
	v_fma_f32 v17, v103, v140, v17
	v_fma_f32 v18, v100, v156, v18
	v_fma_f32 v19, v101, v156, v19
	v_fma_f32 v20, v102, v156, v20
	v_fma_f32 v21, v103, v156, v21
	v_fma_f32 v10, v100, v172, v10
	v_fma_f32 v11, v101, v172, v11
	v_fma_f32 v12, v102, v172, v12
	v_fma_f32 v13, v103, v172, v13
	v_fma_f32 v6, v100, v188, v6
	v_fma_f32 v7, v101, v188, v7
	v_fma_f32 v8, v102, v188, v8
	v_fma_f32 v9, v103, v188, v9
	v_fma_f32 v2, v100, v204, v2
	v_fma_f32 v3, v101, v204, v3
	v_fma_f32 v4, v102, v204, v4
	v_fma_f32 v5, v103, v204, v5
	s_waitcnt vmcnt(6)
	v_fma_f32 v14, v104, v141, v14
	v_fma_f32 v15, v105, v141, v15
	v_fma_f32 v16, v106, v141, v16
	v_fma_f32 v17, v107, v141, v17
	v_fma_f32 v18, v104, v157, v18
	v_fma_f32 v19, v105, v157, v19
	v_fma_f32 v20, v106, v157, v20
	v_fma_f32 v21, v107, v157, v21
	v_fma_f32 v10, v104, v173, v10
	v_fma_f32 v11, v105, v173, v11
	v_fma_f32 v12, v106, v173, v12
	v_fma_f32 v13, v107, v173, v13
	v_fma_f32 v6, v104, v189, v6
	v_fma_f32 v7, v105, v189, v7
	v_fma_f32 v8, v106, v189, v8
	v_fma_f32 v9, v107, v189, v9
	v_fma_f32 v2, v104, v205, v2
	v_fma_f32 v3, v105, v205, v3
	v_fma_f32 v4, v106, v205, v4
	v_fma_f32 v5, v107, v205, v5
	s_waitcnt vmcnt(5)
	v_fma_f32 v14, v108, v142, v14
	v_fma_f32 v15, v109, v142, v15
	v_fma_f32 v16, v110, v142, v16
	v_fma_f32 v17, v111, v142, v17
	v_fma_f32 v18, v108, v158, v18
	v_fma_f32 v19, v109, v158, v19
	v_fma_f32 v20, v110, v158, v20
	v_fma_f32 v21, v111, v158, v21
	v_fma_f32 v10, v108, v174, v10
	v_fma_f32 v11, v109, v174, v11
	v_fma_f32 v12, v110, v174, v12
	v_fma_f32 v13, v111, v174, v13
	v_fma_f32 v6, v108, v190, v6
	v_fma_f32 v7, v109, v190, v7
	v_fma_f32 v8, v110, v190, v8
	v_fma_f32 v9, v111, v190, v9
	v_fma_f32 v2, v108, v206, v2
	v_fma_f32 v3, v109, v206, v3
	v_fma_f32 v4, v110, v206, v4
	v_fma_f32 v5, v111, v206, v5
	s_waitcnt vmcnt(4)
	v_fma_f32 v14, v112, v143, v14
	v_fma_f32 v15, v113, v143, v15
	v_fma_f32 v16, v114, v143, v16
	v_fma_f32 v17, v115, v143, v17
	v_fma_f32 v18, v112, v159, v18
	v_fma_f32 v19, v113, v159, v19
	v_fma_f32 v20, v114, v159, v20
	v_fma_f32 v21, v115, v159, v21
	v_fma_f32 v10, v112, v175, v10
	v_fma_f32 v11, v113, v175, v11
	v_fma_f32 v12, v114, v175, v12
	v_fma_f32 v13, v115, v175, v13
	v_fma_f32 v6, v112, v191, v6
	v_fma_f32 v7, v113, v191, v7
	v_fma_f32 v8, v114, v191, v8
	v_fma_f32 v9, v115, v191, v9
	v_fma_f32 v2, v112, v207, v2
	v_fma_f32 v3, v113, v207, v3
	v_fma_f32 v4, v114, v207, v4
	v_fma_f32 v5, v115, v207, v5
	s_waitcnt vmcnt(3)
	v_fma_f32 v14, v116, v144, v14
	v_fma_f32 v15, v117, v144, v15
	v_fma_f32 v16, v118, v144, v16
	v_fma_f32 v17, v119, v144, v17
	v_fma_f32 v18, v116, v160, v18
	v_fma_f32 v19, v117, v160, v19
	v_fma_f32 v20, v118, v160, v20
	v_fma_f32 v21, v119, v160, v21
	v_fma_f32 v10, v116, v176, v10
	v_fma_f32 v11, v117, v176, v11
	v_fma_f32 v12, v118, v176, v12
	v_fma_f32 v13, v119, v176, v13
	v_fma_f32 v6, v116, v192, v6
	v_fma_f32 v7, v117, v192, v7
	v_fma_f32 v8, v118, v192, v8
	v_fma_f32 v9, v119, v192, v9
	v_fma_f32 v2, v116, v208, v2
	v_fma_f32 v3, v117, v208, v3
	v_fma_f32 v4, v118, v208, v4
	v_fma_f32 v5, v119, v208, v5
	s_waitcnt vmcnt(2)
	v_fma_f32 v14, v120, v145, v14
	v_fma_f32 v15, v121, v145, v15
	v_fma_f32 v16, v122, v145, v16
	v_fma_f32 v17, v123, v145, v17
	v_fma_f32 v18, v120, v161, v18
	v_fma_f32 v19, v121, v161, v19
	v_fma_f32 v20, v122, v161, v20
	v_fma_f32 v21, v123, v161, v21
	v_fma_f32 v10, v120, v177, v10
	v_fma_f32 v11, v121, v177, v11
	v_fma_f32 v12, v122, v177, v12
	v_fma_f32 v13, v123, v177, v13
	v_fma_f32 v6, v120, v193, v6
	v_fma_f32 v7, v121, v193, v7
	v_fma_f32 v8, v122, v193, v8
	v_fma_f32 v9, v123, v193, v9
	v_fma_f32 v2, v120, v209, v2
	v_fma_f32 v3, v121, v209, v3
	v_fma_f32 v4, v122, v209, v4
	v_fma_f32 v5, v123, v209, v5
	s_waitcnt vmcnt(1)
	v_fma_f32 v14, v124, v146, v14
	v_fma_f32 v15, v125, v146, v15
	v_fma_f32 v16, v126, v146, v16
	v_fma_f32 v17, v127, v146, v17
	v_fma_f32 v18, v124, v162, v18
	v_fma_f32 v19, v125, v162, v19
	v_fma_f32 v20, v126, v162, v20
	v_fma_f32 v21, v127, v162, v21
	v_fma_f32 v10, v124, v178, v10
	v_fma_f32 v11, v125, v178, v11
	v_fma_f32 v12, v126, v178, v12
	v_fma_f32 v13, v127, v178, v13
	v_fma_f32 v6, v124, v194, v6
	v_fma_f32 v7, v125, v194, v7
	v_fma_f32 v8, v126, v194, v8
	v_fma_f32 v9, v127, v194, v9
	v_fma_f32 v2, v124, v210, v2
	v_fma_f32 v3, v125, v210, v3
	v_fma_f32 v4, v126, v210, v4
	v_fma_f32 v5, v127, v210, v5
	s_waitcnt vmcnt(0)
	v_fma_f32 v14, v128, v147, v14
	v_fma_f32 v15, v129, v147, v15
	v_fma_f32 v16, v130, v147, v16
	v_fma_f32 v17, v131, v147, v17
	v_fma_f32 v18, v128, v163, v18
	v_fma_f32 v19, v129, v163, v19
	v_fma_f32 v20, v130, v163, v20
	v_fma_f32 v21, v131, v163, v21
	v_fma_f32 v10, v128, v179, v10
	v_fma_f32 v11, v129, v179, v11
	v_fma_f32 v12, v130, v179, v12
	v_fma_f32 v13, v131, v179, v13
	v_fma_f32 v6, v128, v195, v6
	v_fma_f32 v7, v129, v195, v7
	v_fma_f32 v8, v130, v195, v8
	v_fma_f32 v9, v131, v195, v9
	v_fma_f32 v2, v128, v211, v2
	v_fma_f32 v3, v129, v211, v3
	v_fma_f32 v4, v130, v211, v4
	v_fma_f32 v5, v131, v211, v5
	s_cbranch_scc0 .LBB0_578
; DI void phase0(const Params& p, char* smem, int wv) {
;     ...
;     float* mp = p.modpart + (size_t)(kc * 4 + l) * 30720 + col;
;     *(f32x4*)(mp) = a0; *(f32x4*)(mp + 6144) = a1; *(f32x4*)(mp + 2 * 6144) = a2;
;     *(f32x4*)(mp + 3 * 6144) = a3; *(f32x4*)(mp + 4 * 6144) = a4;
;     __syncthreads();
	s_lshl_b32 s1, s9, 2
	s_add_i32 s0, s1, s0
	s_mul_hi_i32 s1, s0, 0x1e000
	s_mul_i32 s0, s0, 0x1e000
	s_add_u32 s0, s60, s0
	s_addc_u32 s1, s61, s1
	v_lshl_add_u64 v[22:23], v[30:31], 2, s[0:1]
	global_store_dwordx4 v[22:23], v[14:17], off
	s_add_i32 s8, s8, s80
	s_cmpk_gt_i32 s8, 0xbf
	v_add_co_u32_e32 v14, vcc, s20, v22
	s_nop 1
	v_addc_co_u32_e32 v15, vcc, 0, v23, vcc
	global_store_dwordx4 v[14:15], v[18:21], off
	v_add_co_u32_e32 v14, vcc, 0xc000, v22
	s_nop 1
	v_addc_co_u32_e32 v15, vcc, 0, v23, vcc
	global_store_dwordx4 v[14:15], v[10:13], off
	s_nop 1
	v_add_co_u32_e32 v10, vcc, 0x12000, v22
	s_nop 1
	v_addc_co_u32_e32 v11, vcc, 0, v23, vcc
	global_store_dwordx4 v[10:11], v[6:9], off
	s_nop 1
	v_add_co_u32_e32 v6, vcc, 0x18000, v22
	s_nop 1
	v_addc_co_u32_e32 v7, vcc, 0, v23, vcc
	global_store_dwordx4 v[6:7], v[2:5], off
	s_barrier
	s_cbranch_scc0 .LBB0_574
	v_mov_b32_e32 v2, v0
